# inverted K-loop priorities: loader segments at s_setprio 1, compute segments at 0 (flips stay outside the barrier pair); reset to 0 at loop exit
# speedup vs baseline: 1.0023x; 1.0023x over previous
; #define PG8_STAGE(bufoff, gbase, voff) do { _Pragma("unroll") for (int _i = 0; _i < 2; ++_i) \
;         __builtin_amdgcn_global_load_lds((const unsigned*)((const char*)(gbase) + (voff)[_i]), (LAS unsigned*)(lds + (bufoff) + ldsw + _i * 8192), 16, 0, 0); } while (0)
; #define PG8_LDA(dst, b, h) do { _Pragma("unroll") for (int m = 0; m < 4; ++m) _Pragma("unroll") for (int k = 0; k < 2; ++k) dst[m][k] = *(const LAS bf16x8*)(lds + PG8_SA(b, h) + aoff + m * 2048 + k * 1024); } while (0)
; #define PG8_LDB(dst, b, h) do { _Pragma("unroll") for (int n = 0; n < 2; ++n) _Pragma("unroll") for (int k = 0; k < 2; ++k) dst[n][k] = *(const LAS bf16x8*)(lds + PG8_SB(b, h) + boff + n * 2048 + k * 1024); } while (0)
; #define PG8_WAIT_V(n) asm volatile("s_waitcnt vmcnt(" #n ")" ::: "memory")
; #define PG8_WAIT_L(n) asm volatile("s_waitcnt lgkmcnt(" #n ")" ::: "memory")
; #define PG8_BAR __builtin_amdgcn_s_barrier()
; #define PG8_SCHED __builtin_amdgcn_sched_barrier(0)
; template <class Epi, class Sched = StaticOrder, class EpiSub = NoSub, bool FAST = false>
; __device__ __forceinline__ void gemm_phase(LAS unsigned char* lds, const Gemm g, const Sched& S, const Epi& E, const EpiSub& ES = EpiSub()) {
;     ...
;         const bool has_next = S.next(ui + 1, nxt);
;         const size_t nko = (has_next && nxt.kb >= 0) ? nxt.kb * ksubB : 0;
;         const char* nA = has_next ? (const char*)g.A + (size_t)nxt.pm * tstepA + (size_t)nxt.pn * g.acs + nko : cA; const char* nB = has_next ? (const char*)g.Bt + (size_t)nxt.pn * tstepB + nko : cB;
;         const int nt = cur.kb < 0 ? ntMain : ntSub;
;         for (int t = 0; t < nt; t += 2) {
;             const bool last = (t == nt - 2);
;             const char* a1 = cA + (size_t)(t + 1) * kstep;
;             const char* a2 = last ? nA : cA + (size_t)(t + 2) * kstep; const char* b2 = last ? nB : cB + (size_t)(t + 2) * kstep;
;             const char* a3 = a2 + kstep; const char* b3 = b2 + kstep;
;             if constexpr (FAST && PG8_SP2) {
;             PG8_LDB(B0, 0, 0); PG8_LDB(B1, 0, 1); PG8_SCHED; PG8_LDA(At, 0, 0); PG8_STAGE(PG8_SA(1, 1), a1 + hstepA, voffA);
;             PG8_WAIT_V(8); PG8_WAIT_L(0); PG8_BAR; PG8_MMA(0, 0, At, B0); PG8_MMA(0, 1, At, B1); PG8_BAR; PG8_SCHED;
;             PG8_LDA(At, 0, 1); PG8_STAGE(PG8_SB(0, 0), b2, voffB); PG8_STAGE(PG8_SB(0, 1), b2 + hstepB, voffB); PG8_STAGE(PG8_SA(0, 0), a2, voffA);
.LBB0_215:
	s_ashr_i32 s15, s14, 31
	s_lshl_b64 s[2:3], s[14:15], 20
	v_readlane_b32 s16, v254, 36
	v_readlane_b32 s17, v254, 37
	s_add_u32 s16, s16, s2
	s_addc_u32 s17, s17, s3
	s_and_b64 s[2:3], s[0:1], exec
	s_cselect_b32 s2, s17, s23
	s_cselect_b32 s3, s16, s22
	s_ashr_i32 s13, s12, 31
	s_lshl_b64 s[18:19], s[12:13], 20
	s_add_u32 s18, s28, s18
	s_addc_u32 s19, s29, s19
	s_and_b64 s[26:27], s[0:1], exec
	s_cselect_b32 s13, s19, s25
	s_cselect_b32 s15, s18, s24
	s_add_u32 s22, s22, 0x80080
	s_addc_u32 s23, s23, 0
	s_add_u32 s48, s24, 0x100
	s_addc_u32 s49, s25, 0
	s_mov_b32 s50, -2
	ds_read_b128 v[154:157], v150
	ds_read_b128 v[158:161], v150 offset:1024
	ds_read_b128 v[162:165], v150 offset:2048
	ds_read_b128 v[166:169], v150 offset:3072
	ds_read_b128 v[170:173], v151
	ds_read_b128 v[174:177], v151 offset:1024
	ds_read_b128 v[178:181], v151 offset:2048
	ds_read_b128 v[182:185], v151 offset:3072
	s_add_u32 s24, s22, 0xfff80080
	s_addc_u32 s25, s23, -1
	s_cmp_eq_u32 s50, 28
	s_cselect_b32 s27, s2, s25
	s_cselect_b32 s26, s3, s24
	s_cselect_b32 s25, s13, s49
	s_cselect_b32 s24, s15, s48
	v_lshl_add_u64 v[144:145], s[22:23], 0, v[136:137]
	s_add_i32 m0, s21, 0xc000
	ds_read_b128 v[186:189], v152
	ds_read_b128 v[194:197], v152 offset:1024
	ds_read_b128 v[198:201], v152 offset:2048
	ds_read_b128 v[202:205], v152 offset:3072
	ds_read_b128 v[206:209], v152 offset:4096
	ds_read_b128 v[210:213], v152 offset:5120
	ds_read_b128 v[214:217], v152 offset:6144
	ds_read_b128 v[218:221], v152 offset:7168
	global_load_lds_dwordx4 v[144:145], off
	v_lshl_add_u64 v[144:145], s[22:23], 0, v[138:139]
	s_add_i32 m0, s21, 0xe000
	s_nop 0
	global_load_lds_dwordx4 v[144:145], off
	s_waitcnt vmcnt(8)
	s_waitcnt lgkmcnt(0)
	s_setprio 0
	s_barrier
	v_mfma_f32_16x16x32_bf16 v[124:127], v[154:157], v[186:189], 0
	v_mfma_f32_16x16x32_bf16 v[120:123], v[162:165], v[186:189], 0
	v_mfma_f32_16x16x32_bf16 v[116:119], v[154:157], v[198:201], 0
	v_mfma_f32_16x16x32_bf16 v[108:111], v[162:165], v[198:201], 0
	v_mfma_f32_16x16x32_bf16 v[100:103], v[154:157], v[206:209], 0
	v_mfma_f32_16x16x32_bf16 v[92:95], v[162:165], v[206:209], 0
	v_mfma_f32_16x16x32_bf16 v[84:87], v[154:157], v[214:217], 0
	v_mfma_f32_16x16x32_bf16 v[76:79], v[162:165], v[214:217], 0
	v_mfma_f32_16x16x32_bf16 v[124:127], v[158:161], v[194:197], v[124:127]
	v_mfma_f32_16x16x32_bf16 v[120:123], v[166:169], v[194:197], v[120:123]
	v_mfma_f32_16x16x32_bf16 v[116:119], v[158:161], v[202:205], v[116:119]
	v_mfma_f32_16x16x32_bf16 v[108:111], v[166:169], v[202:205], v[108:111]
	v_mfma_f32_16x16x32_bf16 v[100:103], v[158:161], v[210:213], v[100:103]
	v_mfma_f32_16x16x32_bf16 v[92:95], v[166:169], v[210:213], v[92:95]
	v_mfma_f32_16x16x32_bf16 v[84:87], v[158:161], v[218:221], v[84:87]
	v_mfma_f32_16x16x32_bf16 v[76:79], v[166:169], v[218:221], v[76:79]
	v_mfma_f32_16x16x32_bf16 v[112:115], v[170:173], v[186:189], 0
	v_mfma_f32_16x16x32_bf16 v[104:107], v[178:181], v[186:189], 0
	v_mfma_f32_16x16x32_bf16 v[96:99], v[170:173], v[198:201], 0
	v_mfma_f32_16x16x32_bf16 v[88:91], v[178:181], v[198:201], 0
	v_mfma_f32_16x16x32_bf16 v[80:83], v[170:173], v[206:209], 0
	v_mfma_f32_16x16x32_bf16 v[72:75], v[178:181], v[206:209], 0
	v_mfma_f32_16x16x32_bf16 v[68:71], v[170:173], v[214:217], 0
	v_mfma_f32_16x16x32_bf16 v[64:67], v[178:181], v[214:217], 0
	v_mfma_f32_16x16x32_bf16 v[112:115], v[174:177], v[194:197], v[112:115]
	v_mfma_f32_16x16x32_bf16 v[104:107], v[182:185], v[194:197], v[104:107]
	v_mfma_f32_16x16x32_bf16 v[96:99], v[174:177], v[202:205], v[96:99]
	v_mfma_f32_16x16x32_bf16 v[88:91], v[182:185], v[202:205], v[88:91]
	v_mfma_f32_16x16x32_bf16 v[80:83], v[174:177], v[210:213], v[80:83]
	v_mfma_f32_16x16x32_bf16 v[72:75], v[182:185], v[210:213], v[72:75]
	v_mfma_f32_16x16x32_bf16 v[68:71], v[174:177], v[218:221], v[68:71]
	v_mfma_f32_16x16x32_bf16 v[64:67], v[182:185], v[218:221], v[64:67]
	s_barrier
	s_setprio 1
	s_add_i32 s51, s41, s30
	v_lshl_add_u64 v[144:145], s[24:25], 0, v[130:131]
	s_mov_b32 m0, s51
	ds_read_b128 v[186:189], v152 offset:16384
	ds_read_b128 v[194:197], v152 offset:17408
	ds_read_b128 v[198:201], v152 offset:18432
	ds_read_b128 v[202:205], v152 offset:19456
	ds_read_b128 v[206:209], v152 offset:20480
	ds_read_b128 v[210:213], v152 offset:21504
	ds_read_b128 v[214:217], v152 offset:22528
	ds_read_b128 v[218:221], v152 offset:23552
	global_load_lds_dwordx4 v[144:145], off
	s_add_i32 m0, s51, 0x2000
	s_add_u32 s68, s24, 0x80000
	v_lshl_add_u64 v[190:191], s[24:25], 0, v[134:135]
	s_addc_u32 s69, s25, 0
	s_add_i32 s51, s42, s30
	global_load_lds_dwordx4 v[190:191], off
	v_lshl_add_u64 v[222:223], s[68:69], 0, v[130:131]
	s_mov_b32 m0, s51
	v_lshl_add_u64 v[224:225], s[26:27], 0, v[132:133]
	global_load_lds_dwordx4 v[222:223], off
	v_lshl_add_u64 v[222:223], s[68:69], 0, v[134:135]
	s_add_i32 m0, s51, 0x2000
	s_nop 0
	global_load_lds_dwordx4 v[222:223], off
	v_lshl_add_u64 v[222:223], s[26:27], 0, v[128:129]
	s_mov_b32 m0, s21
	s_nop 0
	global_load_lds_dwordx4 v[222:223], off
	s_mov_b32 m0, s34
	s_nop 0
	global_load_lds_dwordx4 v[224:225], off
	s_waitcnt vmcnt(8)
	s_waitcnt lgkmcnt(0)
	s_setprio 0
	s_barrier
; #define PG8_STAGE(bufoff, gbase, voff) do { _Pragma("unroll") for (int _i = 0; _i < 2; ++_i) \
;         __builtin_amdgcn_global_load_lds((const unsigned*)((const char*)(gbase) + (voff)[_i]), (LAS unsigned*)(lds + (bufoff) + ldsw + _i * 8192), 16, 0, 0); } while (0)
; #define PG8_LDA(dst, b, h) do { _Pragma("unroll") for (int m = 0; m < 4; ++m) _Pragma("unroll") for (int k = 0; k < 2; ++k) dst[m][k] = *(const LAS bf16x8*)(lds + PG8_SA(b, h) + aoff + m * 2048 + k * 1024); } while (0)
; #define PG8_LDB(dst, b, h) do { _Pragma("unroll") for (int n = 0; n < 2; ++n) _Pragma("unroll") for (int k = 0; k < 2; ++k) dst[n][k] = *(const LAS bf16x8*)(lds + PG8_SB(b, h) + boff + n * 2048 + k * 1024); } while (0)
; #define PG8_MMA(ai, bj, At, Bt) do { __builtin_amdgcn_s_setprio(1); _Pragma("unroll") for (int m = 0; m < 4; ++m) _Pragma("unroll") for (int n = 0; n < 2; ++n) _Pragma("unroll") for (int k = 0; k < 2; ++k) \
;         acc[ai][bj][m][n] = __builtin_amdgcn_mfma_f32_16x16x32_bf16(Bt[n][k], At[m][k], acc[ai][bj][m][n], 0, 0, 0); __builtin_amdgcn_s_setprio(0); } while (0)
; #define PG8_WAIT_V(n) asm volatile("s_waitcnt vmcnt(" #n ")" ::: "memory")
; #define PG8_WAIT_L(n) asm volatile("s_waitcnt lgkmcnt(" #n ")" ::: "memory")
; #define PG8_BAR __builtin_amdgcn_s_barrier()
; #define PG8_SCHED __builtin_amdgcn_sched_barrier(0)
; template <class Epi, class Sched = StaticOrder, class EpiSub = NoSub, bool FAST = false>
; __device__ __forceinline__ void gemm_phase(LAS unsigned char* lds, const Gemm g, const Sched& S, const Epi& E, const EpiSub& ES = EpiSub()) {
;     ...
;             PG8_WAIT_V(8); PG8_WAIT_L(0); PG8_BAR; PG8_MMA(1, 0, At, B0); PG8_MMA(1, 1, At, B1); PG8_BAR; PG8_SCHED;
;             PG8_LDB(B0, 1, 0); PG8_LDB(B1, 1, 1); PG8_SCHED; PG8_LDA(At, 1, 0); PG8_STAGE(PG8_SA(0, 1), a2 + hstepA, voffA);
;             PG8_WAIT_V(8); PG8_WAIT_L(0); PG8_BAR; PG8_MMA(0, 0, At, B0); PG8_MMA(0, 1, At, B1); PG8_BAR; PG8_SCHED;
	v_mfma_f32_16x16x32_bf16 v[60:63], v[154:157], v[186:189], 0
	v_mfma_f32_16x16x32_bf16 v[56:59], v[162:165], v[186:189], 0
	v_mfma_f32_16x16x32_bf16 v[52:55], v[154:157], v[198:201], 0
	v_mfma_f32_16x16x32_bf16 v[44:47], v[162:165], v[198:201], 0
	v_mfma_f32_16x16x32_bf16 v[36:39], v[154:157], v[206:209], 0
	v_mfma_f32_16x16x32_bf16 v[28:31], v[162:165], v[206:209], 0
	v_mfma_f32_16x16x32_bf16 v[20:23], v[154:157], v[214:217], 0
	v_mfma_f32_16x16x32_bf16 v[12:15], v[162:165], v[214:217], 0
	v_mfma_f32_16x16x32_bf16 v[60:63], v[158:161], v[194:197], v[60:63]
	v_mfma_f32_16x16x32_bf16 v[56:59], v[166:169], v[194:197], v[56:59]
	v_mfma_f32_16x16x32_bf16 v[52:55], v[158:161], v[202:205], v[52:55]
	v_mfma_f32_16x16x32_bf16 v[44:47], v[166:169], v[202:205], v[44:47]
	v_mfma_f32_16x16x32_bf16 v[36:39], v[158:161], v[210:213], v[36:39]
	v_mfma_f32_16x16x32_bf16 v[28:31], v[166:169], v[210:213], v[28:31]
	v_mfma_f32_16x16x32_bf16 v[20:23], v[158:161], v[218:221], v[20:23]
	v_mfma_f32_16x16x32_bf16 v[12:15], v[166:169], v[218:221], v[12:15]
	v_mfma_f32_16x16x32_bf16 v[48:51], v[170:173], v[186:189], 0
	v_mfma_f32_16x16x32_bf16 v[40:43], v[178:181], v[186:189], 0
	v_mfma_f32_16x16x32_bf16 v[32:35], v[170:173], v[198:201], 0
	v_mfma_f32_16x16x32_bf16 v[24:27], v[178:181], v[198:201], 0
	v_mfma_f32_16x16x32_bf16 v[16:19], v[170:173], v[206:209], 0
	v_mfma_f32_16x16x32_bf16 v[8:11], v[178:181], v[206:209], 0
	v_mfma_f32_16x16x32_bf16 v[4:7], v[170:173], v[214:217], 0
	v_mfma_f32_16x16x32_bf16 v[0:3], v[178:181], v[214:217], 0
	v_mfma_f32_16x16x32_bf16 v[48:51], v[174:177], v[194:197], v[48:51]
	v_mfma_f32_16x16x32_bf16 v[40:43], v[182:185], v[194:197], v[40:43]
	v_mfma_f32_16x16x32_bf16 v[32:35], v[174:177], v[202:205], v[32:35]
	v_mfma_f32_16x16x32_bf16 v[24:27], v[182:185], v[202:205], v[24:27]
	v_mfma_f32_16x16x32_bf16 v[16:19], v[174:177], v[210:213], v[16:19]
	v_mfma_f32_16x16x32_bf16 v[8:11], v[182:185], v[210:213], v[8:11]
	v_mfma_f32_16x16x32_bf16 v[4:7], v[174:177], v[218:221], v[4:7]
	v_mfma_f32_16x16x32_bf16 v[0:3], v[182:185], v[218:221], v[0:3]
	s_barrier
	s_setprio 1
	s_add_i32 s51, 0, 0x18000
	v_add_u32_e32 v153, s51, v148
	s_add_i32 s68, 0, 0x1c000
	ds_read_b128 v[154:157], v153
	ds_read_b128 v[158:161], v153 offset:1024
	ds_read_b128 v[162:165], v153 offset:2048
	ds_read_b128 v[166:169], v153 offset:3072
	v_add_u32_e32 v153, s68, v148
	ds_read_b128 v[170:173], v153
	ds_read_b128 v[174:177], v153 offset:1024
	ds_read_b128 v[178:181], v153 offset:2048
	ds_read_b128 v[182:185], v153 offset:3072
	s_add_u32 s26, s26, 0x80000
	s_addc_u32 s27, s27, 0
	s_mov_b32 m0, s35
	v_lshl_add_u64 v[226:227], s[26:27], 0, v[128:129]
	ds_read_b128 v[186:189], v152 offset:32768
	ds_read_b128 v[194:197], v152 offset:33792
	ds_read_b128 v[198:201], v152 offset:34816
	ds_read_b128 v[202:205], v152 offset:35840
	ds_read_b128 v[206:209], v152 offset:36864
	ds_read_b128 v[210:213], v152 offset:37888
	ds_read_b128 v[214:217], v152 offset:38912
	ds_read_b128 v[218:221], v152 offset:39936
	global_load_lds_dwordx4 v[226:227], off
	v_lshl_add_u64 v[226:227], s[26:27], 0, v[132:133]
	s_mov_b32 m0, s36
	s_nop 0
	global_load_lds_dwordx4 v[226:227], off
	s_waitcnt vmcnt(8)
	s_waitcnt lgkmcnt(0)
	s_setprio 0
	s_barrier
	v_mfma_f32_16x16x32_bf16 v[124:127], v[154:157], v[186:189], v[124:127]
	v_mfma_f32_16x16x32_bf16 v[120:123], v[162:165], v[186:189], v[120:123]
	v_mfma_f32_16x16x32_bf16 v[116:119], v[154:157], v[198:201], v[116:119]
	v_mfma_f32_16x16x32_bf16 v[108:111], v[162:165], v[198:201], v[108:111]
	v_mfma_f32_16x16x32_bf16 v[100:103], v[154:157], v[206:209], v[100:103]
	v_mfma_f32_16x16x32_bf16 v[92:95], v[162:165], v[206:209], v[92:95]
	v_mfma_f32_16x16x32_bf16 v[84:87], v[154:157], v[214:217], v[84:87]
	v_mfma_f32_16x16x32_bf16 v[76:79], v[162:165], v[214:217], v[76:79]
	v_mfma_f32_16x16x32_bf16 v[124:127], v[158:161], v[194:197], v[124:127]
	v_mfma_f32_16x16x32_bf16 v[120:123], v[166:169], v[194:197], v[120:123]
	v_mfma_f32_16x16x32_bf16 v[116:119], v[158:161], v[202:205], v[116:119]
	v_mfma_f32_16x16x32_bf16 v[108:111], v[166:169], v[202:205], v[108:111]
	v_mfma_f32_16x16x32_bf16 v[100:103], v[158:161], v[210:213], v[100:103]
	v_mfma_f32_16x16x32_bf16 v[92:95], v[166:169], v[210:213], v[92:95]
	v_mfma_f32_16x16x32_bf16 v[84:87], v[158:161], v[218:221], v[84:87]
	v_mfma_f32_16x16x32_bf16 v[76:79], v[166:169], v[218:221], v[76:79]
	v_mfma_f32_16x16x32_bf16 v[112:115], v[170:173], v[186:189], v[112:115]
	v_mfma_f32_16x16x32_bf16 v[104:107], v[178:181], v[186:189], v[104:107]
	v_mfma_f32_16x16x32_bf16 v[96:99], v[170:173], v[198:201], v[96:99]
	v_mfma_f32_16x16x32_bf16 v[88:91], v[178:181], v[198:201], v[88:91]
	v_mfma_f32_16x16x32_bf16 v[80:83], v[170:173], v[206:209], v[80:83]
	v_mfma_f32_16x16x32_bf16 v[72:75], v[178:181], v[206:209], v[72:75]
	v_mfma_f32_16x16x32_bf16 v[68:71], v[170:173], v[214:217], v[68:71]
	v_mfma_f32_16x16x32_bf16 v[64:67], v[178:181], v[214:217], v[64:67]
	v_mfma_f32_16x16x32_bf16 v[112:115], v[174:177], v[194:197], v[112:115]
	v_mfma_f32_16x16x32_bf16 v[104:107], v[182:185], v[194:197], v[104:107]
	v_mfma_f32_16x16x32_bf16 v[96:99], v[174:177], v[202:205], v[96:99]
	v_mfma_f32_16x16x32_bf16 v[88:91], v[182:185], v[202:205], v[88:91]
	v_mfma_f32_16x16x32_bf16 v[80:83], v[174:177], v[210:213], v[80:83]
	v_mfma_f32_16x16x32_bf16 v[72:75], v[182:185], v[210:213], v[72:75]
	v_mfma_f32_16x16x32_bf16 v[68:71], v[174:177], v[218:221], v[68:71]
	v_mfma_f32_16x16x32_bf16 v[64:67], v[182:185], v[218:221], v[64:67]
	s_barrier
; #define PG8_STAGE(bufoff, gbase, voff) do { _Pragma("unroll") for (int _i = 0; _i < 2; ++_i) \
;         __builtin_amdgcn_global_load_lds((const unsigned*)((const char*)(gbase) + (voff)[_i]), (LAS unsigned*)(lds + (bufoff) + ldsw + _i * 8192), 16, 0, 0); } while (0)
; #define PG8_LDA(dst, b, h) do { _Pragma("unroll") for (int m = 0; m < 4; ++m) _Pragma("unroll") for (int k = 0; k < 2; ++k) dst[m][k] = *(const LAS bf16x8*)(lds + PG8_SA(b, h) + aoff + m * 2048 + k * 1024); } while (0)
; #define PG8_LDB(dst, b, h) do { _Pragma("unroll") for (int n = 0; n < 2; ++n) _Pragma("unroll") for (int k = 0; k < 2; ++k) dst[n][k] = *(const LAS bf16x8*)(lds + PG8_SB(b, h) + boff + n * 2048 + k * 1024); } while (0)
; #define PG8_MMA(ai, bj, At, Bt) do { __builtin_amdgcn_s_setprio(1); _Pragma("unroll") for (int m = 0; m < 4; ++m) _Pragma("unroll") for (int n = 0; n < 2; ++n) _Pragma("unroll") for (int k = 0; k < 2; ++k) \
;         acc[ai][bj][m][n] = __builtin_amdgcn_mfma_f32_16x16x32_bf16(Bt[n][k], At[m][k], acc[ai][bj][m][n], 0, 0, 0); __builtin_amdgcn_s_setprio(0); } while (0)
; #define PG8_WAIT_V(n) asm volatile("s_waitcnt vmcnt(" #n ")" ::: "memory")
; #define PG8_WAIT_L(n) asm volatile("s_waitcnt lgkmcnt(" #n ")" ::: "memory")
; #define PG8_BAR __builtin_amdgcn_s_barrier()
; #define PG8_SCHED __builtin_amdgcn_sched_barrier(0)
; template <class Epi, class Sched = StaticOrder, class EpiSub = NoSub, bool FAST = false>
; __device__ __forceinline__ void gemm_phase(LAS unsigned char* lds, const Gemm g, const Sched& S, const Epi& E, const EpiSub& ES = EpiSub()) {
;     ...
;             PG8_LDB(B0, 0, 0); PG8_LDB(B1, 0, 1); PG8_SCHED; PG8_LDA(At, 0, 0); PG8_STAGE(PG8_SA(1, 1), a1 + hstepA, voffA);
;             PG8_WAIT_V(8); PG8_WAIT_L(0); PG8_BAR; PG8_MMA(0, 0, At, B0); PG8_MMA(0, 1, At, B1); PG8_BAR; PG8_SCHED;
;     ...
;             PG8_LDA(At, 1, 1); PG8_STAGE(PG8_SB(1, 0), b3, voffB); PG8_STAGE(PG8_SB(1, 1), b3 + hstepB, voffB); PG8_STAGE(PG8_SA(1, 0), a3, voffA);
;             PG8_WAIT_V(8); PG8_WAIT_L(0); PG8_BAR; PG8_MMA(1, 0, At, B0); PG8_MMA(1, 1, At, B1); PG8_BAR; PG8_SCHED;
	s_setprio 1
	s_add_i32 s26, s51, s30
	v_lshl_add_u64 v[144:145], v[144:145], 0, s[8:9]
	s_mov_b32 m0, s26
	ds_read_b128 v[186:189], v152 offset:49152
	ds_read_b128 v[194:197], v152 offset:50176
	ds_read_b128 v[198:201], v152 offset:51200
	ds_read_b128 v[202:205], v152 offset:52224
	ds_read_b128 v[206:209], v152 offset:53248
	ds_read_b128 v[210:213], v152 offset:54272
	ds_read_b128 v[214:217], v152 offset:55296
	ds_read_b128 v[218:221], v152 offset:56320
	global_load_lds_dwordx4 v[144:145], off
	s_add_i32 m0, s26, 0x2000
	s_add_u32 s24, s24, 0x80080
	v_lshl_add_u64 v[144:145], v[190:191], 0, s[8:9]
	s_addc_u32 s25, s25, 0
	s_add_i32 s26, s68, s30
	global_load_lds_dwordx4 v[144:145], off
	v_lshl_add_u64 v[144:145], s[24:25], 0, v[130:131]
	s_mov_b32 m0, s26
	s_nop 0
	global_load_lds_dwordx4 v[144:145], off
	v_lshl_add_u64 v[144:145], s[24:25], 0, v[134:135]
	s_add_i32 m0, s26, 0x2000
	s_nop 0
	global_load_lds_dwordx4 v[144:145], off
	v_lshl_add_u64 v[144:145], v[222:223], 0, s[8:9]
	s_mov_b32 m0, s39
	s_nop 0
	global_load_lds_dwordx4 v[144:145], off
	v_lshl_add_u64 v[144:145], v[224:225], 0, s[8:9]
	s_mov_b32 m0, s40
	s_nop 0
	global_load_lds_dwordx4 v[144:145], off
	s_waitcnt vmcnt(8)
	s_waitcnt lgkmcnt(0)
	s_setprio 0
	s_barrier
	v_mfma_f32_16x16x32_bf16 v[60:63], v[154:157], v[186:189], v[60:63]
	v_mfma_f32_16x16x32_bf16 v[56:59], v[162:165], v[186:189], v[56:59]
	v_mfma_f32_16x16x32_bf16 v[52:55], v[154:157], v[198:201], v[52:55]
	v_mfma_f32_16x16x32_bf16 v[44:47], v[162:165], v[198:201], v[44:47]
	v_mfma_f32_16x16x32_bf16 v[36:39], v[154:157], v[206:209], v[36:39]
	v_mfma_f32_16x16x32_bf16 v[28:31], v[162:165], v[206:209], v[28:31]
	v_mfma_f32_16x16x32_bf16 v[20:23], v[154:157], v[214:217], v[20:23]
	v_mfma_f32_16x16x32_bf16 v[12:15], v[162:165], v[214:217], v[12:15]
	v_mfma_f32_16x16x32_bf16 v[60:63], v[158:161], v[194:197], v[60:63]
	v_mfma_f32_16x16x32_bf16 v[56:59], v[166:169], v[194:197], v[56:59]
	v_mfma_f32_16x16x32_bf16 v[52:55], v[158:161], v[202:205], v[52:55]
	v_mfma_f32_16x16x32_bf16 v[44:47], v[166:169], v[202:205], v[44:47]
	v_mfma_f32_16x16x32_bf16 v[36:39], v[158:161], v[210:213], v[36:39]
	v_mfma_f32_16x16x32_bf16 v[28:31], v[166:169], v[210:213], v[28:31]
	v_mfma_f32_16x16x32_bf16 v[20:23], v[158:161], v[218:221], v[20:23]
	v_mfma_f32_16x16x32_bf16 v[12:15], v[166:169], v[218:221], v[12:15]
	v_mfma_f32_16x16x32_bf16 v[48:51], v[170:173], v[186:189], v[48:51]
	v_mfma_f32_16x16x32_bf16 v[40:43], v[178:181], v[186:189], v[40:43]
	v_mfma_f32_16x16x32_bf16 v[32:35], v[170:173], v[198:201], v[32:35]
	v_mfma_f32_16x16x32_bf16 v[24:27], v[178:181], v[198:201], v[24:27]
	v_mfma_f32_16x16x32_bf16 v[16:19], v[170:173], v[206:209], v[16:19]
	v_mfma_f32_16x16x32_bf16 v[8:11], v[178:181], v[206:209], v[8:11]
	v_mfma_f32_16x16x32_bf16 v[4:7], v[170:173], v[214:217], v[4:7]
	v_mfma_f32_16x16x32_bf16 v[0:3], v[178:181], v[214:217], v[0:3]
	v_mfma_f32_16x16x32_bf16 v[48:51], v[174:177], v[194:197], v[48:51]
	v_mfma_f32_16x16x32_bf16 v[40:43], v[182:185], v[194:197], v[40:43]
	v_mfma_f32_16x16x32_bf16 v[32:35], v[174:177], v[202:205], v[32:35]
	v_mfma_f32_16x16x32_bf16 v[24:27], v[182:185], v[202:205], v[24:27]
	v_mfma_f32_16x16x32_bf16 v[16:19], v[174:177], v[210:213], v[16:19]
	v_mfma_f32_16x16x32_bf16 v[8:11], v[182:185], v[210:213], v[8:11]
	v_mfma_f32_16x16x32_bf16 v[4:7], v[174:177], v[218:221], v[4:7]
	v_mfma_f32_16x16x32_bf16 v[0:3], v[182:185], v[218:221], v[0:3]
	s_barrier
	s_setprio 1
	s_add_i32 s50, s50, 2
	s_add_u32 s22, s22, 0x100
	s_addc_u32 s23, s23, 0
	s_add_u32 s48, s48, 0x100
	s_addc_u32 s49, s49, 0
	s_cmp_gt_u32 s50, 29
	s_cbranch_scc1 .Lkpeel_216_exit
.LBB0_216:
	ds_read_b128 v[154:157], v150
	ds_read_b128 v[158:161], v150 offset:1024
	ds_read_b128 v[162:165], v150 offset:2048
	ds_read_b128 v[166:169], v150 offset:3072
	ds_read_b128 v[170:173], v151
	ds_read_b128 v[174:177], v151 offset:1024
	ds_read_b128 v[178:181], v151 offset:2048
	ds_read_b128 v[182:185], v151 offset:3072
	s_add_u32 s24, s22, 0xfff80080
	s_addc_u32 s25, s23, -1
	s_cmp_eq_u32 s50, 28
	s_cselect_b32 s27, s2, s25
	s_cselect_b32 s26, s3, s24
	s_cselect_b32 s25, s13, s49
	s_cselect_b32 s24, s15, s48
	v_lshl_add_u64 v[144:145], s[22:23], 0, v[136:137]
	s_add_i32 m0, s21, 0xc000
	ds_read_b128 v[186:189], v152
	ds_read_b128 v[194:197], v152 offset:1024
	ds_read_b128 v[198:201], v152 offset:2048
	ds_read_b128 v[202:205], v152 offset:3072
	ds_read_b128 v[206:209], v152 offset:4096
	ds_read_b128 v[210:213], v152 offset:5120
	ds_read_b128 v[214:217], v152 offset:6144
	ds_read_b128 v[218:221], v152 offset:7168
	global_load_lds_dwordx4 v[144:145], off
	v_lshl_add_u64 v[144:145], s[22:23], 0, v[138:139]
	s_add_i32 m0, s21, 0xe000
	s_nop 0
	global_load_lds_dwordx4 v[144:145], off
	s_waitcnt vmcnt(8)
	s_waitcnt lgkmcnt(0)
	s_setprio 0
	s_barrier
; #define PG8_STAGE(bufoff, gbase, voff) do { _Pragma("unroll") for (int _i = 0; _i < 2; ++_i) \
;         __builtin_amdgcn_global_load_lds((const unsigned*)((const char*)(gbase) + (voff)[_i]), (LAS unsigned*)(lds + (bufoff) + ldsw + _i * 8192), 16, 0, 0); } while (0)
; #define PG8_LDA(dst, b, h) do { _Pragma("unroll") for (int m = 0; m < 4; ++m) _Pragma("unroll") for (int k = 0; k < 2; ++k) dst[m][k] = *(const LAS bf16x8*)(lds + PG8_SA(b, h) + aoff + m * 2048 + k * 1024); } while (0)
; #define PG8_MMA(ai, bj, At, Bt) do { __builtin_amdgcn_s_setprio(1); _Pragma("unroll") for (int m = 0; m < 4; ++m) _Pragma("unroll") for (int n = 0; n < 2; ++n) _Pragma("unroll") for (int k = 0; k < 2; ++k) \
;         acc[ai][bj][m][n] = __builtin_amdgcn_mfma_f32_16x16x32_bf16(Bt[n][k], At[m][k], acc[ai][bj][m][n], 0, 0, 0); __builtin_amdgcn_s_setprio(0); } while (0)
; #define PG8_WAIT_V(n) asm volatile("s_waitcnt vmcnt(" #n ")" ::: "memory")
; #define PG8_WAIT_L(n) asm volatile("s_waitcnt lgkmcnt(" #n ")" ::: "memory")
; #define PG8_BAR __builtin_amdgcn_s_barrier()
; #define PG8_SCHED __builtin_amdgcn_sched_barrier(0)
; template <class Epi, class Sched = StaticOrder, class EpiSub = NoSub, bool FAST = false>
; __device__ __forceinline__ void gemm_phase(LAS unsigned char* lds, const Gemm g, const Sched& S, const Epi& E, const EpiSub& ES = EpiSub()) {
;     ...
;             PG8_WAIT_V(8); PG8_WAIT_L(0); PG8_BAR; PG8_MMA(0, 0, At, B0); PG8_MMA(0, 1, At, B1); PG8_BAR; PG8_SCHED;
;             PG8_LDA(At, 0, 1); PG8_STAGE(PG8_SB(0, 0), b2, voffB); PG8_STAGE(PG8_SB(0, 1), b2 + hstepB, voffB); PG8_STAGE(PG8_SA(0, 0), a2, voffA);
;             PG8_WAIT_V(8); PG8_WAIT_L(0); PG8_BAR; PG8_MMA(1, 0, At, B0); PG8_MMA(1, 1, At, B1); PG8_BAR; PG8_SCHED;
	v_mfma_f32_16x16x32_bf16 v[124:127], v[154:157], v[186:189], v[124:127]
	v_mfma_f32_16x16x32_bf16 v[120:123], v[162:165], v[186:189], v[120:123]
	v_mfma_f32_16x16x32_bf16 v[116:119], v[154:157], v[198:201], v[116:119]
	v_mfma_f32_16x16x32_bf16 v[108:111], v[162:165], v[198:201], v[108:111]
	v_mfma_f32_16x16x32_bf16 v[100:103], v[154:157], v[206:209], v[100:103]
	v_mfma_f32_16x16x32_bf16 v[92:95], v[162:165], v[206:209], v[92:95]
	v_mfma_f32_16x16x32_bf16 v[84:87], v[154:157], v[214:217], v[84:87]
	v_mfma_f32_16x16x32_bf16 v[76:79], v[162:165], v[214:217], v[76:79]
	v_mfma_f32_16x16x32_bf16 v[124:127], v[158:161], v[194:197], v[124:127]
	v_mfma_f32_16x16x32_bf16 v[120:123], v[166:169], v[194:197], v[120:123]
	v_mfma_f32_16x16x32_bf16 v[116:119], v[158:161], v[202:205], v[116:119]
	v_mfma_f32_16x16x32_bf16 v[108:111], v[166:169], v[202:205], v[108:111]
	v_mfma_f32_16x16x32_bf16 v[100:103], v[158:161], v[210:213], v[100:103]
	v_mfma_f32_16x16x32_bf16 v[92:95], v[166:169], v[210:213], v[92:95]
	v_mfma_f32_16x16x32_bf16 v[84:87], v[158:161], v[218:221], v[84:87]
	v_mfma_f32_16x16x32_bf16 v[76:79], v[166:169], v[218:221], v[76:79]
	v_mfma_f32_16x16x32_bf16 v[112:115], v[170:173], v[186:189], v[112:115]
	v_mfma_f32_16x16x32_bf16 v[104:107], v[178:181], v[186:189], v[104:107]
	v_mfma_f32_16x16x32_bf16 v[96:99], v[170:173], v[198:201], v[96:99]
	v_mfma_f32_16x16x32_bf16 v[88:91], v[178:181], v[198:201], v[88:91]
	v_mfma_f32_16x16x32_bf16 v[80:83], v[170:173], v[206:209], v[80:83]
	v_mfma_f32_16x16x32_bf16 v[72:75], v[178:181], v[206:209], v[72:75]
	v_mfma_f32_16x16x32_bf16 v[68:71], v[170:173], v[214:217], v[68:71]
	v_mfma_f32_16x16x32_bf16 v[64:67], v[178:181], v[214:217], v[64:67]
	v_mfma_f32_16x16x32_bf16 v[112:115], v[174:177], v[194:197], v[112:115]
	v_mfma_f32_16x16x32_bf16 v[104:107], v[182:185], v[194:197], v[104:107]
	v_mfma_f32_16x16x32_bf16 v[96:99], v[174:177], v[202:205], v[96:99]
	v_mfma_f32_16x16x32_bf16 v[88:91], v[182:185], v[202:205], v[88:91]
	v_mfma_f32_16x16x32_bf16 v[80:83], v[174:177], v[210:213], v[80:83]
	v_mfma_f32_16x16x32_bf16 v[72:75], v[182:185], v[210:213], v[72:75]
	v_mfma_f32_16x16x32_bf16 v[68:71], v[174:177], v[218:221], v[68:71]
	v_mfma_f32_16x16x32_bf16 v[64:67], v[182:185], v[218:221], v[64:67]
	s_barrier
	s_setprio 1
	s_add_i32 s51, s41, s30
	v_lshl_add_u64 v[144:145], s[24:25], 0, v[130:131]
	s_mov_b32 m0, s51
	ds_read_b128 v[186:189], v152 offset:16384
	ds_read_b128 v[194:197], v152 offset:17408
	ds_read_b128 v[198:201], v152 offset:18432
	ds_read_b128 v[202:205], v152 offset:19456
	ds_read_b128 v[206:209], v152 offset:20480
	ds_read_b128 v[210:213], v152 offset:21504
	ds_read_b128 v[214:217], v152 offset:22528
	ds_read_b128 v[218:221], v152 offset:23552
	global_load_lds_dwordx4 v[144:145], off
	s_add_i32 m0, s51, 0x2000
	s_add_u32 s68, s24, 0x80000
	v_lshl_add_u64 v[190:191], s[24:25], 0, v[134:135]
	s_addc_u32 s69, s25, 0
	s_add_i32 s51, s42, s30
	global_load_lds_dwordx4 v[190:191], off
	v_lshl_add_u64 v[222:223], s[68:69], 0, v[130:131]
	s_mov_b32 m0, s51
	v_lshl_add_u64 v[224:225], s[26:27], 0, v[132:133]
	global_load_lds_dwordx4 v[222:223], off
	v_lshl_add_u64 v[222:223], s[68:69], 0, v[134:135]
	s_add_i32 m0, s51, 0x2000
	s_nop 0
	global_load_lds_dwordx4 v[222:223], off
	v_lshl_add_u64 v[222:223], s[26:27], 0, v[128:129]
	s_mov_b32 m0, s21
	s_nop 0
	global_load_lds_dwordx4 v[222:223], off
	s_mov_b32 m0, s34
	s_nop 0
	global_load_lds_dwordx4 v[224:225], off
	s_waitcnt vmcnt(8)
	s_waitcnt lgkmcnt(0)
	s_setprio 0
	s_barrier
	v_mfma_f32_16x16x32_bf16 v[60:63], v[154:157], v[186:189], v[60:63]
	v_mfma_f32_16x16x32_bf16 v[56:59], v[162:165], v[186:189], v[56:59]
	v_mfma_f32_16x16x32_bf16 v[52:55], v[154:157], v[198:201], v[52:55]
	v_mfma_f32_16x16x32_bf16 v[44:47], v[162:165], v[198:201], v[44:47]
	v_mfma_f32_16x16x32_bf16 v[36:39], v[154:157], v[206:209], v[36:39]
	v_mfma_f32_16x16x32_bf16 v[28:31], v[162:165], v[206:209], v[28:31]
	v_mfma_f32_16x16x32_bf16 v[20:23], v[154:157], v[214:217], v[20:23]
	v_mfma_f32_16x16x32_bf16 v[12:15], v[162:165], v[214:217], v[12:15]
	v_mfma_f32_16x16x32_bf16 v[60:63], v[158:161], v[194:197], v[60:63]
	v_mfma_f32_16x16x32_bf16 v[56:59], v[166:169], v[194:197], v[56:59]
	v_mfma_f32_16x16x32_bf16 v[52:55], v[158:161], v[202:205], v[52:55]
	v_mfma_f32_16x16x32_bf16 v[44:47], v[166:169], v[202:205], v[44:47]
	v_mfma_f32_16x16x32_bf16 v[36:39], v[158:161], v[210:213], v[36:39]
	v_mfma_f32_16x16x32_bf16 v[28:31], v[166:169], v[210:213], v[28:31]
	v_mfma_f32_16x16x32_bf16 v[20:23], v[158:161], v[218:221], v[20:23]
	v_mfma_f32_16x16x32_bf16 v[12:15], v[166:169], v[218:221], v[12:15]
	v_mfma_f32_16x16x32_bf16 v[48:51], v[170:173], v[186:189], v[48:51]
	v_mfma_f32_16x16x32_bf16 v[40:43], v[178:181], v[186:189], v[40:43]
	v_mfma_f32_16x16x32_bf16 v[32:35], v[170:173], v[198:201], v[32:35]
	v_mfma_f32_16x16x32_bf16 v[24:27], v[178:181], v[198:201], v[24:27]
	v_mfma_f32_16x16x32_bf16 v[16:19], v[170:173], v[206:209], v[16:19]
	v_mfma_f32_16x16x32_bf16 v[8:11], v[178:181], v[206:209], v[8:11]
	v_mfma_f32_16x16x32_bf16 v[4:7], v[170:173], v[214:217], v[4:7]
	v_mfma_f32_16x16x32_bf16 v[0:3], v[178:181], v[214:217], v[0:3]
	v_mfma_f32_16x16x32_bf16 v[48:51], v[174:177], v[194:197], v[48:51]
	v_mfma_f32_16x16x32_bf16 v[40:43], v[182:185], v[194:197], v[40:43]
	v_mfma_f32_16x16x32_bf16 v[32:35], v[174:177], v[202:205], v[32:35]
	v_mfma_f32_16x16x32_bf16 v[24:27], v[182:185], v[202:205], v[24:27]
	v_mfma_f32_16x16x32_bf16 v[16:19], v[174:177], v[210:213], v[16:19]
	v_mfma_f32_16x16x32_bf16 v[8:11], v[182:185], v[210:213], v[8:11]
	v_mfma_f32_16x16x32_bf16 v[4:7], v[174:177], v[218:221], v[4:7]
	v_mfma_f32_16x16x32_bf16 v[0:3], v[182:185], v[218:221], v[0:3]
	s_barrier
; #define PG8_STAGE(bufoff, gbase, voff) do { _Pragma("unroll") for (int _i = 0; _i < 2; ++_i) \
;         __builtin_amdgcn_global_load_lds((const unsigned*)((const char*)(gbase) + (voff)[_i]), (LAS unsigned*)(lds + (bufoff) + ldsw + _i * 8192), 16, 0, 0); } while (0)
; #define PG8_LDA(dst, b, h) do { _Pragma("unroll") for (int m = 0; m < 4; ++m) _Pragma("unroll") for (int k = 0; k < 2; ++k) dst[m][k] = *(const LAS bf16x8*)(lds + PG8_SA(b, h) + aoff + m * 2048 + k * 1024); } while (0)
; #define PG8_LDB(dst, b, h) do { _Pragma("unroll") for (int n = 0; n < 2; ++n) _Pragma("unroll") for (int k = 0; k < 2; ++k) dst[n][k] = *(const LAS bf16x8*)(lds + PG8_SB(b, h) + boff + n * 2048 + k * 1024); } while (0)
; #define PG8_MMA(ai, bj, At, Bt) do { __builtin_amdgcn_s_setprio(1); _Pragma("unroll") for (int m = 0; m < 4; ++m) _Pragma("unroll") for (int n = 0; n < 2; ++n) _Pragma("unroll") for (int k = 0; k < 2; ++k) \
;         acc[ai][bj][m][n] = __builtin_amdgcn_mfma_f32_16x16x32_bf16(Bt[n][k], At[m][k], acc[ai][bj][m][n], 0, 0, 0); __builtin_amdgcn_s_setprio(0); } while (0)
; #define PG8_WAIT_V(n) asm volatile("s_waitcnt vmcnt(" #n ")" ::: "memory")
; #define PG8_WAIT_L(n) asm volatile("s_waitcnt lgkmcnt(" #n ")" ::: "memory")
; #define PG8_BAR __builtin_amdgcn_s_barrier()
; #define PG8_SCHED __builtin_amdgcn_sched_barrier(0)
; template <class Epi, class Sched = StaticOrder, class EpiSub = NoSub, bool FAST = false>
; __device__ __forceinline__ void gemm_phase(LAS unsigned char* lds, const Gemm g, const Sched& S, const Epi& E, const EpiSub& ES = EpiSub()) {
;     ...
;             PG8_LDB(B0, 1, 0); PG8_LDB(B1, 1, 1); PG8_SCHED; PG8_LDA(At, 1, 0); PG8_STAGE(PG8_SA(0, 1), a2 + hstepA, voffA);
;             PG8_WAIT_V(8); PG8_WAIT_L(0); PG8_BAR; PG8_MMA(0, 0, At, B0); PG8_MMA(0, 1, At, B1); PG8_BAR; PG8_SCHED;
	s_setprio 1
	s_add_i32 s51, 0, 0x18000
	v_add_u32_e32 v153, s51, v148
	s_add_i32 s68, 0, 0x1c000
	ds_read_b128 v[154:157], v153
	ds_read_b128 v[158:161], v153 offset:1024
	ds_read_b128 v[162:165], v153 offset:2048
	ds_read_b128 v[166:169], v153 offset:3072
	v_add_u32_e32 v153, s68, v148
	ds_read_b128 v[170:173], v153
	ds_read_b128 v[174:177], v153 offset:1024
	ds_read_b128 v[178:181], v153 offset:2048
	ds_read_b128 v[182:185], v153 offset:3072
	s_add_u32 s26, s26, 0x80000
	s_addc_u32 s27, s27, 0
	s_mov_b32 m0, s35
	v_lshl_add_u64 v[226:227], s[26:27], 0, v[128:129]
	ds_read_b128 v[186:189], v152 offset:32768
	ds_read_b128 v[194:197], v152 offset:33792
	ds_read_b128 v[198:201], v152 offset:34816
	ds_read_b128 v[202:205], v152 offset:35840
	ds_read_b128 v[206:209], v152 offset:36864
	ds_read_b128 v[210:213], v152 offset:37888
	ds_read_b128 v[214:217], v152 offset:38912
	ds_read_b128 v[218:221], v152 offset:39936
	global_load_lds_dwordx4 v[226:227], off
	v_lshl_add_u64 v[226:227], s[26:27], 0, v[132:133]
	s_mov_b32 m0, s36
	s_nop 0
	global_load_lds_dwordx4 v[226:227], off
	s_waitcnt vmcnt(8)
	s_waitcnt lgkmcnt(0)
	s_setprio 0
	s_barrier
	v_mfma_f32_16x16x32_bf16 v[124:127], v[154:157], v[186:189], v[124:127]
	v_mfma_f32_16x16x32_bf16 v[120:123], v[162:165], v[186:189], v[120:123]
	v_mfma_f32_16x16x32_bf16 v[116:119], v[154:157], v[198:201], v[116:119]
	v_mfma_f32_16x16x32_bf16 v[108:111], v[162:165], v[198:201], v[108:111]
	v_mfma_f32_16x16x32_bf16 v[100:103], v[154:157], v[206:209], v[100:103]
	v_mfma_f32_16x16x32_bf16 v[92:95], v[162:165], v[206:209], v[92:95]
	v_mfma_f32_16x16x32_bf16 v[84:87], v[154:157], v[214:217], v[84:87]
	v_mfma_f32_16x16x32_bf16 v[76:79], v[162:165], v[214:217], v[76:79]
	v_mfma_f32_16x16x32_bf16 v[124:127], v[158:161], v[194:197], v[124:127]
	v_mfma_f32_16x16x32_bf16 v[120:123], v[166:169], v[194:197], v[120:123]
	v_mfma_f32_16x16x32_bf16 v[116:119], v[158:161], v[202:205], v[116:119]
	v_mfma_f32_16x16x32_bf16 v[108:111], v[166:169], v[202:205], v[108:111]
	v_mfma_f32_16x16x32_bf16 v[100:103], v[158:161], v[210:213], v[100:103]
	v_mfma_f32_16x16x32_bf16 v[92:95], v[166:169], v[210:213], v[92:95]
	v_mfma_f32_16x16x32_bf16 v[84:87], v[158:161], v[218:221], v[84:87]
	v_mfma_f32_16x16x32_bf16 v[76:79], v[166:169], v[218:221], v[76:79]
	v_mfma_f32_16x16x32_bf16 v[112:115], v[170:173], v[186:189], v[112:115]
	v_mfma_f32_16x16x32_bf16 v[104:107], v[178:181], v[186:189], v[104:107]
	v_mfma_f32_16x16x32_bf16 v[96:99], v[170:173], v[198:201], v[96:99]
	v_mfma_f32_16x16x32_bf16 v[88:91], v[178:181], v[198:201], v[88:91]
	v_mfma_f32_16x16x32_bf16 v[80:83], v[170:173], v[206:209], v[80:83]
	v_mfma_f32_16x16x32_bf16 v[72:75], v[178:181], v[206:209], v[72:75]
	v_mfma_f32_16x16x32_bf16 v[68:71], v[170:173], v[214:217], v[68:71]
	v_mfma_f32_16x16x32_bf16 v[64:67], v[178:181], v[214:217], v[64:67]
	v_mfma_f32_16x16x32_bf16 v[112:115], v[174:177], v[194:197], v[112:115]
	v_mfma_f32_16x16x32_bf16 v[104:107], v[182:185], v[194:197], v[104:107]
	v_mfma_f32_16x16x32_bf16 v[96:99], v[174:177], v[202:205], v[96:99]
	v_mfma_f32_16x16x32_bf16 v[88:91], v[182:185], v[202:205], v[88:91]
	v_mfma_f32_16x16x32_bf16 v[80:83], v[174:177], v[210:213], v[80:83]
	v_mfma_f32_16x16x32_bf16 v[72:75], v[182:185], v[210:213], v[72:75]
	v_mfma_f32_16x16x32_bf16 v[68:71], v[174:177], v[218:221], v[68:71]
	v_mfma_f32_16x16x32_bf16 v[64:67], v[182:185], v[218:221], v[64:67]
	s_barrier
; #define PG8_STAGE(bufoff, gbase, voff) do { _Pragma("unroll") for (int _i = 0; _i < 2; ++_i) \
;         __builtin_amdgcn_global_load_lds((const unsigned*)((const char*)(gbase) + (voff)[_i]), (LAS unsigned*)(lds + (bufoff) + ldsw + _i * 8192), 16, 0, 0); } while (0)
; #define PG8_LDA(dst, b, h) do { _Pragma("unroll") for (int m = 0; m < 4; ++m) _Pragma("unroll") for (int k = 0; k < 2; ++k) dst[m][k] = *(const LAS bf16x8*)(lds + PG8_SA(b, h) + aoff + m * 2048 + k * 1024); } while (0)
; #define PG8_MMA(ai, bj, At, Bt) do { __builtin_amdgcn_s_setprio(1); _Pragma("unroll") for (int m = 0; m < 4; ++m) _Pragma("unroll") for (int n = 0; n < 2; ++n) _Pragma("unroll") for (int k = 0; k < 2; ++k) \
;         acc[ai][bj][m][n] = __builtin_amdgcn_mfma_f32_16x16x32_bf16(Bt[n][k], At[m][k], acc[ai][bj][m][n], 0, 0, 0); __builtin_amdgcn_s_setprio(0); } while (0)
; #define PG8_WAIT_V(n) asm volatile("s_waitcnt vmcnt(" #n ")" ::: "memory")
; #define PG8_WAIT_L(n) asm volatile("s_waitcnt lgkmcnt(" #n ")" ::: "memory")
; #define PG8_BAR __builtin_amdgcn_s_barrier()
; #define PG8_SCHED __builtin_amdgcn_sched_barrier(0)
; template <class Epi, class Sched = StaticOrder, class EpiSub = NoSub, bool FAST = false>
; __device__ __forceinline__ void gemm_phase(LAS unsigned char* lds, const Gemm g, const Sched& S, const Epi& E, const EpiSub& ES = EpiSub()) {
;     ...
;             PG8_LDA(At, 1, 1); PG8_STAGE(PG8_SB(1, 0), b3, voffB); PG8_STAGE(PG8_SB(1, 1), b3 + hstepB, voffB); PG8_STAGE(PG8_SA(1, 0), a3, voffA);
;             PG8_WAIT_V(8); PG8_WAIT_L(0); PG8_BAR; PG8_MMA(1, 0, At, B0); PG8_MMA(1, 1, At, B1); PG8_BAR; PG8_SCHED;
;     ...
;         if constexpr (FAST && PG8_ALIGN) { if (wr == 0) PG8_BAR; }
	s_setprio 1
	s_add_i32 s26, s51, s30
	v_lshl_add_u64 v[144:145], v[144:145], 0, s[8:9]
	s_mov_b32 m0, s26
	ds_read_b128 v[186:189], v152 offset:49152
	ds_read_b128 v[194:197], v152 offset:50176
	ds_read_b128 v[198:201], v152 offset:51200
	ds_read_b128 v[202:205], v152 offset:52224
	ds_read_b128 v[206:209], v152 offset:53248
	ds_read_b128 v[210:213], v152 offset:54272
	ds_read_b128 v[214:217], v152 offset:55296
	ds_read_b128 v[218:221], v152 offset:56320
	global_load_lds_dwordx4 v[144:145], off
	s_add_i32 m0, s26, 0x2000
	s_add_u32 s24, s24, 0x80080
	v_lshl_add_u64 v[144:145], v[190:191], 0, s[8:9]
	s_addc_u32 s25, s25, 0
	s_add_i32 s26, s68, s30
	global_load_lds_dwordx4 v[144:145], off
	v_lshl_add_u64 v[144:145], s[24:25], 0, v[130:131]
	s_mov_b32 m0, s26
	s_nop 0
	global_load_lds_dwordx4 v[144:145], off
	v_lshl_add_u64 v[144:145], s[24:25], 0, v[134:135]
	s_add_i32 m0, s26, 0x2000
	s_nop 0
	global_load_lds_dwordx4 v[144:145], off
	v_lshl_add_u64 v[144:145], v[222:223], 0, s[8:9]
	s_mov_b32 m0, s39
	s_nop 0
	global_load_lds_dwordx4 v[144:145], off
	v_lshl_add_u64 v[144:145], v[224:225], 0, s[8:9]
	s_mov_b32 m0, s40
	s_nop 0
	global_load_lds_dwordx4 v[144:145], off
	s_waitcnt vmcnt(8)
	s_waitcnt lgkmcnt(0)
	s_setprio 0
	s_barrier
	v_mfma_f32_16x16x32_bf16 v[60:63], v[154:157], v[186:189], v[60:63]
	v_mfma_f32_16x16x32_bf16 v[56:59], v[162:165], v[186:189], v[56:59]
	v_mfma_f32_16x16x32_bf16 v[52:55], v[154:157], v[198:201], v[52:55]
	v_mfma_f32_16x16x32_bf16 v[44:47], v[162:165], v[198:201], v[44:47]
	v_mfma_f32_16x16x32_bf16 v[36:39], v[154:157], v[206:209], v[36:39]
	v_mfma_f32_16x16x32_bf16 v[28:31], v[162:165], v[206:209], v[28:31]
	v_mfma_f32_16x16x32_bf16 v[20:23], v[154:157], v[214:217], v[20:23]
	v_mfma_f32_16x16x32_bf16 v[12:15], v[162:165], v[214:217], v[12:15]
	v_mfma_f32_16x16x32_bf16 v[60:63], v[158:161], v[194:197], v[60:63]
	v_mfma_f32_16x16x32_bf16 v[56:59], v[166:169], v[194:197], v[56:59]
	v_mfma_f32_16x16x32_bf16 v[52:55], v[158:161], v[202:205], v[52:55]
	v_mfma_f32_16x16x32_bf16 v[44:47], v[166:169], v[202:205], v[44:47]
	v_mfma_f32_16x16x32_bf16 v[36:39], v[158:161], v[210:213], v[36:39]
	v_mfma_f32_16x16x32_bf16 v[28:31], v[166:169], v[210:213], v[28:31]
	v_mfma_f32_16x16x32_bf16 v[20:23], v[158:161], v[218:221], v[20:23]
	v_mfma_f32_16x16x32_bf16 v[12:15], v[166:169], v[218:221], v[12:15]
	v_mfma_f32_16x16x32_bf16 v[48:51], v[170:173], v[186:189], v[48:51]
	v_mfma_f32_16x16x32_bf16 v[40:43], v[178:181], v[186:189], v[40:43]
	v_mfma_f32_16x16x32_bf16 v[32:35], v[170:173], v[198:201], v[32:35]
	v_mfma_f32_16x16x32_bf16 v[24:27], v[178:181], v[198:201], v[24:27]
	v_mfma_f32_16x16x32_bf16 v[16:19], v[170:173], v[206:209], v[16:19]
	v_mfma_f32_16x16x32_bf16 v[8:11], v[178:181], v[206:209], v[8:11]
	v_mfma_f32_16x16x32_bf16 v[4:7], v[170:173], v[214:217], v[4:7]
	v_mfma_f32_16x16x32_bf16 v[0:3], v[178:181], v[214:217], v[0:3]
	v_mfma_f32_16x16x32_bf16 v[48:51], v[174:177], v[194:197], v[48:51]
	v_mfma_f32_16x16x32_bf16 v[40:43], v[182:185], v[194:197], v[40:43]
	v_mfma_f32_16x16x32_bf16 v[32:35], v[174:177], v[202:205], v[32:35]
	v_mfma_f32_16x16x32_bf16 v[24:27], v[182:185], v[202:205], v[24:27]
	v_mfma_f32_16x16x32_bf16 v[16:19], v[174:177], v[210:213], v[16:19]
	v_mfma_f32_16x16x32_bf16 v[8:11], v[182:185], v[210:213], v[8:11]
	v_mfma_f32_16x16x32_bf16 v[4:7], v[174:177], v[218:221], v[4:7]
	v_mfma_f32_16x16x32_bf16 v[0:3], v[182:185], v[218:221], v[0:3]
	s_barrier
	s_setprio 1
	s_add_i32 s50, s50, 2
	s_add_u32 s22, s22, 0x100
	s_addc_u32 s23, s23, 0
	s_add_u32 s48, s48, 0x100
	s_addc_u32 s49, s49, 0
	s_cmp_gt_u32 s50, 29
	s_cbranch_scc0 .LBB0_216
.Lkpeel_216_exit:
	s_setprio 0
	s_and_b64 vcc, exec, s[10:11]
	s_cbranch_vccz .LBB0_219
	s_barrier

; #define PG8_STAGE(bufoff, gbase, voff) do { _Pragma("unroll") for (int _i = 0; _i < 2; ++_i) \
;         __builtin_amdgcn_global_load_lds((const unsigned*)((const char*)(gbase) + (voff)[_i]), (LAS unsigned*)(lds + (bufoff) + ldsw + _i * 8192), 16, 0, 0); } while (0)
; #define PG8_LDA(dst, b, h) do { _Pragma("unroll") for (int m = 0; m < 4; ++m) _Pragma("unroll") for (int k = 0; k < 2; ++k) dst[m][k] = *(const LAS bf16x8*)(lds + PG8_SA(b, h) + aoff + m * 2048 + k * 1024); } while (0)
; #define PG8_LDB(dst, b, h) do { _Pragma("unroll") for (int n = 0; n < 2; ++n) _Pragma("unroll") for (int k = 0; k < 2; ++k) dst[n][k] = *(const LAS bf16x8*)(lds + PG8_SB(b, h) + boff + n * 2048 + k * 1024); } while (0)
; #define PG8_WAIT_V(n) asm volatile("s_waitcnt vmcnt(" #n ")" ::: "memory")
; #define PG8_WAIT_L(n) asm volatile("s_waitcnt lgkmcnt(" #n ")" ::: "memory")
; #define PG8_BAR __builtin_amdgcn_s_barrier()
; #define PG8_SCHED __builtin_amdgcn_sched_barrier(0)
; template <class Epi, class Sched = StaticOrder, class EpiSub = NoSub, bool FAST = false>
; __device__ __forceinline__ void gemm_phase(LAS unsigned char* lds, const Gemm g, const Sched& S, const Epi& E, const EpiSub& ES = EpiSub()) {
;     ...
;         const bool has_next = S.next(ui + 1, nxt);
;         const size_t nko = (has_next && nxt.kb >= 0) ? nxt.kb * ksubB : 0;
;         const char* nA = has_next ? (const char*)g.A + (size_t)nxt.pm * tstepA + (size_t)nxt.pn * g.acs + nko : cA; const char* nB = has_next ? (const char*)g.Bt + (size_t)nxt.pn * tstepB + nko : cB;
;         const int nt = cur.kb < 0 ? ntMain : ntSub;
;         for (int t = 0; t < nt; t += 2) {
;             const bool last = (t == nt - 2);
;             const char* a1 = cA + (size_t)(t + 1) * kstep;
;             const char* a2 = last ? nA : cA + (size_t)(t + 2) * kstep; const char* b2 = last ? nB : cB + (size_t)(t + 2) * kstep;
;             const char* a3 = a2 + kstep; const char* b3 = b2 + kstep;
;             if constexpr (FAST && PG8_SP2) {
;             PG8_LDB(B0, 0, 0); PG8_LDB(B1, 0, 1); PG8_SCHED; PG8_LDA(At, 0, 0); PG8_STAGE(PG8_SA(1, 1), a1 + hstepA, voffA);
;             PG8_WAIT_V(8); PG8_WAIT_L(0); PG8_BAR; PG8_MMA(0, 0, At, B0); PG8_MMA(0, 1, At, B1); PG8_BAR; PG8_SCHED;
;             PG8_LDA(At, 0, 1); PG8_STAGE(PG8_SB(0, 0), b2, voffB); PG8_STAGE(PG8_SB(0, 1), b2 + hstepB, voffB); PG8_STAGE(PG8_SA(0, 0), a2, voffA);
.LBB0_599:
	s_cmp_gt_i32 s8, -1
	s_cselect_b64 s[30:31], -1, 0
	s_and_b64 s[30:31], s[28:29], s[30:31]
	s_lshl_b64 s[36:37], s[8:9], 9
	s_and_b64 s[30:31], s[30:31], exec
	s_cselect_b32 s7, s37, 0
	s_cselect_b32 s33, s36, 0
	s_ashr_i32 s27, s26, 31
	s_lshl_b64 s[30:31], s[26:27], 19
	s_add_u32 s1, s78, s30
	s_addc_u32 s5, s79, s31
	s_add_u32 s30, s1, s33
	s_addc_u32 s31, s5, s7
	s_and_b64 s[36:37], s[28:29], exec
	s_cselect_b32 s1, s31, s41
	s_cselect_b32 s5, s30, s40
	s_ashr_i32 s25, s24, 31
	s_lshl_b64 s[36:37], s[24:25], 19
	s_add_u32 s25, s2, s36
	s_addc_u32 s27, s3, s37
	s_add_u32 s36, s25, s33
	s_addc_u32 s37, s27, s7
	s_and_b64 s[38:39], s[28:29], exec
	s_cselect_b32 s7, s37, s43
	s_cselect_b32 s25, s36, s42
	s_cmp_gt_i32 s0, -1
	s_cselect_b64 s[38:39], -1, 0
	s_cmp_lt_i32 s0, 0
	s_cselect_b32 s27, 16, 4
	s_add_i32 s33, s27, -2
	s_add_u32 s40, s40, 0x40080
	s_addc_u32 s41, s41, 0
	s_add_u32 s48, s42, 0x100
	s_mov_b32 s50, 0
	s_addc_u32 s49, s43, 0
	ds_read_b128 v[100:103], v186
	ds_read_b128 v[112:115], v186 offset:1024
	ds_read_b128 v[124:127], v186 offset:2048
	ds_read_b128 v[136:139], v186 offset:3072
	ds_read_b128 v[144:147], v187
	ds_read_b128 v[148:151], v187 offset:1024
	ds_read_b128 v[152:155], v187 offset:2048
	ds_read_b128 v[170:173], v187 offset:3072
	s_add_i32 s51, s50, 2
	s_add_u32 s42, s40, 0xfffc0080
	s_addc_u32 s43, s41, -1
	s_cmp_eq_u32 s33, s50
	s_cselect_b32 s53, s1, s43
	s_cselect_b32 s52, s5, s42
	s_cselect_b32 s43, s7, s49
	s_cselect_b32 s42, s25, s48
	v_lshl_add_u64 v[190:191], s[40:41], 0, v[164:165]
	s_add_i32 m0, s55, 0xc000
	ds_read_b128 v[174:177], v188
	ds_read_b128 v[178:181], v188 offset:1024
	ds_read_b128 v[194:197], v188 offset:2048
	ds_read_b128 v[198:201], v188 offset:3072
	ds_read_b128 v[202:205], v188 offset:4096
	ds_read_b128 v[206:209], v188 offset:5120
	ds_read_b128 v[210:213], v188 offset:6144
	ds_read_b128 v[214:217], v188 offset:7168
	global_load_lds_dwordx4 v[190:191], off
	v_lshl_add_u64 v[190:191], s[40:41], 0, v[166:167]
	s_add_i32 m0, s55, 0xe000
	s_nop 0
	global_load_lds_dwordx4 v[190:191], off
	s_waitcnt vmcnt(8)
	s_waitcnt lgkmcnt(0)
	s_setprio 0
	s_barrier
	v_mfma_f32_16x16x32_bf16 v[140:143], v[100:103], v[174:177], 0
	v_mfma_f32_16x16x32_bf16 v[132:135], v[124:127], v[174:177], 0
	v_mfma_f32_16x16x32_bf16 v[116:119], v[100:103], v[194:197], 0
	v_mfma_f32_16x16x32_bf16 v[108:111], v[124:127], v[194:197], 0
	v_mfma_f32_16x16x32_bf16 v[92:95], v[100:103], v[202:205], 0
	v_mfma_f32_16x16x32_bf16 v[88:91], v[124:127], v[202:205], 0
	v_mfma_f32_16x16x32_bf16 v[76:79], v[100:103], v[210:213], 0
	v_mfma_f32_16x16x32_bf16 v[72:75], v[124:127], v[210:213], 0
	v_mfma_f32_16x16x32_bf16 v[140:143], v[112:115], v[178:181], v[140:143]
	v_mfma_f32_16x16x32_bf16 v[132:135], v[136:139], v[178:181], v[132:135]
	v_mfma_f32_16x16x32_bf16 v[116:119], v[112:115], v[198:201], v[116:119]
	v_mfma_f32_16x16x32_bf16 v[108:111], v[136:139], v[198:201], v[108:111]
	v_mfma_f32_16x16x32_bf16 v[92:95], v[112:115], v[206:209], v[92:95]
	v_mfma_f32_16x16x32_bf16 v[88:91], v[136:139], v[206:209], v[88:91]
	v_mfma_f32_16x16x32_bf16 v[76:79], v[112:115], v[214:217], v[76:79]
	v_mfma_f32_16x16x32_bf16 v[72:75], v[136:139], v[214:217], v[72:75]
	v_mfma_f32_16x16x32_bf16 v[128:131], v[144:147], v[174:177], 0
	v_mfma_f32_16x16x32_bf16 v[120:123], v[152:155], v[174:177], 0
	v_mfma_f32_16x16x32_bf16 v[104:107], v[144:147], v[194:197], 0
	v_mfma_f32_16x16x32_bf16 v[96:99], v[152:155], v[194:197], 0
	v_mfma_f32_16x16x32_bf16 v[84:87], v[144:147], v[202:205], 0
	v_mfma_f32_16x16x32_bf16 v[80:83], v[152:155], v[202:205], 0
	v_mfma_f32_16x16x32_bf16 v[68:71], v[144:147], v[210:213], 0
	v_mfma_f32_16x16x32_bf16 v[64:67], v[152:155], v[210:213], 0
	v_mfma_f32_16x16x32_bf16 v[128:131], v[148:151], v[178:181], v[128:131]
	v_mfma_f32_16x16x32_bf16 v[120:123], v[170:173], v[178:181], v[120:123]
	v_mfma_f32_16x16x32_bf16 v[104:107], v[148:151], v[198:201], v[104:107]
	v_mfma_f32_16x16x32_bf16 v[96:99], v[170:173], v[198:201], v[96:99]
	v_mfma_f32_16x16x32_bf16 v[84:87], v[148:151], v[206:209], v[84:87]
	v_mfma_f32_16x16x32_bf16 v[80:83], v[170:173], v[206:209], v[80:83]
	v_mfma_f32_16x16x32_bf16 v[68:71], v[148:151], v[214:217], v[68:71]
	v_mfma_f32_16x16x32_bf16 v[64:67], v[170:173], v[214:217], v[64:67]
	s_barrier
	s_setprio 1
	s_add_i32 s50, s75, s54
	v_lshl_add_u64 v[190:191], s[42:43], 0, v[158:159]
	s_mov_b32 m0, s50
	ds_read_b128 v[174:177], v188 offset:16384
	ds_read_b128 v[178:181], v188 offset:17408
	ds_read_b128 v[194:197], v188 offset:18432
	ds_read_b128 v[198:201], v188 offset:19456
	ds_read_b128 v[202:205], v188 offset:20480
	ds_read_b128 v[206:209], v188 offset:21504
	ds_read_b128 v[210:213], v188 offset:22528
	ds_read_b128 v[214:217], v188 offset:23552
	global_load_lds_dwordx4 v[190:191], off
	s_add_i32 m0, s50, 0x2000
	s_add_u32 s70, s42, 0x40000
	v_lshl_add_u64 v[218:219], s[42:43], 0, v[162:163]
	s_addc_u32 s71, s43, 0
	s_add_i32 s50, s80, s54
	global_load_lds_dwordx4 v[218:219], off
	v_lshl_add_u64 v[220:221], s[70:71], 0, v[158:159]
	s_mov_b32 m0, s50
	v_lshl_add_u64 v[222:223], s[52:53], 0, v[160:161]
	global_load_lds_dwordx4 v[220:221], off
	v_lshl_add_u64 v[220:221], s[70:71], 0, v[162:163]
	s_add_i32 m0, s50, 0x2000
	s_nop 0
	global_load_lds_dwordx4 v[220:221], off
	v_lshl_add_u64 v[220:221], s[52:53], 0, v[156:157]
	s_mov_b32 m0, s55
	s_nop 0
	global_load_lds_dwordx4 v[220:221], off
	s_mov_b32 m0, s56
	s_nop 0
	global_load_lds_dwordx4 v[222:223], off
	s_waitcnt vmcnt(8)
	s_waitcnt lgkmcnt(0)
	s_setprio 0
	s_barrier
; #define PG8_STAGE(bufoff, gbase, voff) do { _Pragma("unroll") for (int _i = 0; _i < 2; ++_i) \
;         __builtin_amdgcn_global_load_lds((const unsigned*)((const char*)(gbase) + (voff)[_i]), (LAS unsigned*)(lds + (bufoff) + ldsw + _i * 8192), 16, 0, 0); } while (0)
; #define PG8_LDA(dst, b, h) do { _Pragma("unroll") for (int m = 0; m < 4; ++m) _Pragma("unroll") for (int k = 0; k < 2; ++k) dst[m][k] = *(const LAS bf16x8*)(lds + PG8_SA(b, h) + aoff + m * 2048 + k * 1024); } while (0)
; #define PG8_LDB(dst, b, h) do { _Pragma("unroll") for (int n = 0; n < 2; ++n) _Pragma("unroll") for (int k = 0; k < 2; ++k) dst[n][k] = *(const LAS bf16x8*)(lds + PG8_SB(b, h) + boff + n * 2048 + k * 1024); } while (0)
; #define PG8_MMA(ai, bj, At, Bt) do { __builtin_amdgcn_s_setprio(1); _Pragma("unroll") for (int m = 0; m < 4; ++m) _Pragma("unroll") for (int n = 0; n < 2; ++n) _Pragma("unroll") for (int k = 0; k < 2; ++k) \
;         acc[ai][bj][m][n] = __builtin_amdgcn_mfma_f32_16x16x32_bf16(Bt[n][k], At[m][k], acc[ai][bj][m][n], 0, 0, 0); __builtin_amdgcn_s_setprio(0); } while (0)
; #define PG8_WAIT_V(n) asm volatile("s_waitcnt vmcnt(" #n ")" ::: "memory")
; #define PG8_WAIT_L(n) asm volatile("s_waitcnt lgkmcnt(" #n ")" ::: "memory")
; #define PG8_BAR __builtin_amdgcn_s_barrier()
; #define PG8_SCHED __builtin_amdgcn_sched_barrier(0)
; template <class Epi, class Sched = StaticOrder, class EpiSub = NoSub, bool FAST = false>
; __device__ __forceinline__ void gemm_phase(LAS unsigned char* lds, const Gemm g, const Sched& S, const Epi& E, const EpiSub& ES = EpiSub()) {
;     ...
;             PG8_WAIT_V(8); PG8_WAIT_L(0); PG8_BAR; PG8_MMA(1, 0, At, B0); PG8_MMA(1, 1, At, B1); PG8_BAR; PG8_SCHED;
;             PG8_LDB(B0, 1, 0); PG8_LDB(B1, 1, 1); PG8_SCHED; PG8_LDA(At, 1, 0); PG8_STAGE(PG8_SA(0, 1), a2 + hstepA, voffA);
;             PG8_WAIT_V(8); PG8_WAIT_L(0); PG8_BAR; PG8_MMA(0, 0, At, B0); PG8_MMA(0, 1, At, B1); PG8_BAR; PG8_SCHED;
	v_mfma_f32_16x16x32_bf16 v[60:63], v[100:103], v[174:177], 0
	v_mfma_f32_16x16x32_bf16 v[56:59], v[124:127], v[174:177], 0
	v_mfma_f32_16x16x32_bf16 v[44:47], v[100:103], v[194:197], 0
	v_mfma_f32_16x16x32_bf16 v[40:43], v[124:127], v[194:197], 0
	v_mfma_f32_16x16x32_bf16 v[28:31], v[100:103], v[202:205], 0
	v_mfma_f32_16x16x32_bf16 v[24:27], v[124:127], v[202:205], 0
	v_mfma_f32_16x16x32_bf16 v[12:15], v[100:103], v[210:213], 0
	v_mfma_f32_16x16x32_bf16 v[8:11], v[124:127], v[210:213], 0
	v_mfma_f32_16x16x32_bf16 v[60:63], v[112:115], v[178:181], v[60:63]
	v_mfma_f32_16x16x32_bf16 v[56:59], v[136:139], v[178:181], v[56:59]
	v_mfma_f32_16x16x32_bf16 v[44:47], v[112:115], v[198:201], v[44:47]
	v_mfma_f32_16x16x32_bf16 v[40:43], v[136:139], v[198:201], v[40:43]
	v_mfma_f32_16x16x32_bf16 v[28:31], v[112:115], v[206:209], v[28:31]
	v_mfma_f32_16x16x32_bf16 v[24:27], v[136:139], v[206:209], v[24:27]
	v_mfma_f32_16x16x32_bf16 v[12:15], v[112:115], v[214:217], v[12:15]
	v_mfma_f32_16x16x32_bf16 v[8:11], v[136:139], v[214:217], v[8:11]
	v_mfma_f32_16x16x32_bf16 v[52:55], v[144:147], v[174:177], 0
	v_mfma_f32_16x16x32_bf16 v[48:51], v[152:155], v[174:177], 0
	v_mfma_f32_16x16x32_bf16 v[36:39], v[144:147], v[194:197], 0
	v_mfma_f32_16x16x32_bf16 v[32:35], v[152:155], v[194:197], 0
	v_mfma_f32_16x16x32_bf16 v[20:23], v[144:147], v[202:205], 0
	v_mfma_f32_16x16x32_bf16 v[16:19], v[152:155], v[202:205], 0
	v_mfma_f32_16x16x32_bf16 v[4:7], v[144:147], v[210:213], 0
	v_mfma_f32_16x16x32_bf16 v[0:3], v[152:155], v[210:213], 0
	v_mfma_f32_16x16x32_bf16 v[52:55], v[148:151], v[178:181], v[52:55]
	v_mfma_f32_16x16x32_bf16 v[48:51], v[170:173], v[178:181], v[48:51]
	v_mfma_f32_16x16x32_bf16 v[36:39], v[148:151], v[198:201], v[36:39]
	v_mfma_f32_16x16x32_bf16 v[32:35], v[170:173], v[198:201], v[32:35]
	v_mfma_f32_16x16x32_bf16 v[20:23], v[148:151], v[206:209], v[20:23]
	v_mfma_f32_16x16x32_bf16 v[16:19], v[170:173], v[206:209], v[16:19]
	v_mfma_f32_16x16x32_bf16 v[4:7], v[148:151], v[214:217], v[4:7]
	v_mfma_f32_16x16x32_bf16 v[0:3], v[170:173], v[214:217], v[0:3]
	s_barrier
	s_setprio 1
	s_add_i32 s50, 0, 0x18000
	s_add_i32 s70, 0, 0x1c000
	v_add_u32_e32 v136, s50, v183
	v_add_u32_e32 v170, s70, v183
	ds_read_b128 v[100:103], v136
	ds_read_b128 v[112:115], v136 offset:1024
	ds_read_b128 v[124:127], v136 offset:2048
	ds_read_b128 v[136:139], v136 offset:3072
	ds_read_b128 v[144:147], v170
	ds_read_b128 v[148:151], v170 offset:1024
	ds_read_b128 v[152:155], v170 offset:2048
	ds_read_b128 v[170:173], v170 offset:3072
	s_add_u32 s52, s52, 0x40000
	s_addc_u32 s53, s53, 0
	s_mov_b32 m0, s57
	v_lshl_add_u64 v[224:225], s[52:53], 0, v[156:157]
	ds_read_b128 v[174:177], v188 offset:32768
	ds_read_b128 v[178:181], v188 offset:33792
	ds_read_b128 v[194:197], v188 offset:34816
	ds_read_b128 v[198:201], v188 offset:35840
	ds_read_b128 v[202:205], v188 offset:36864
	ds_read_b128 v[206:209], v188 offset:37888
	ds_read_b128 v[210:213], v188 offset:38912
	ds_read_b128 v[214:217], v188 offset:39936
	global_load_lds_dwordx4 v[224:225], off
	v_lshl_add_u64 v[224:225], s[52:53], 0, v[160:161]
	s_mov_b32 m0, s58
	s_nop 0
	global_load_lds_dwordx4 v[224:225], off
	s_waitcnt vmcnt(8)
	s_waitcnt lgkmcnt(0)
	s_setprio 0
	s_barrier
	v_mfma_f32_16x16x32_bf16 v[140:143], v[100:103], v[174:177], v[140:143]
	v_mfma_f32_16x16x32_bf16 v[132:135], v[124:127], v[174:177], v[132:135]
	v_mfma_f32_16x16x32_bf16 v[116:119], v[100:103], v[194:197], v[116:119]
	v_mfma_f32_16x16x32_bf16 v[108:111], v[124:127], v[194:197], v[108:111]
	v_mfma_f32_16x16x32_bf16 v[92:95], v[100:103], v[202:205], v[92:95]
	v_mfma_f32_16x16x32_bf16 v[88:91], v[124:127], v[202:205], v[88:91]
	v_mfma_f32_16x16x32_bf16 v[76:79], v[100:103], v[210:213], v[76:79]
	v_mfma_f32_16x16x32_bf16 v[72:75], v[124:127], v[210:213], v[72:75]
	v_mfma_f32_16x16x32_bf16 v[140:143], v[112:115], v[178:181], v[140:143]
	v_mfma_f32_16x16x32_bf16 v[132:135], v[136:139], v[178:181], v[132:135]
	v_mfma_f32_16x16x32_bf16 v[116:119], v[112:115], v[198:201], v[116:119]
	v_mfma_f32_16x16x32_bf16 v[108:111], v[136:139], v[198:201], v[108:111]
	v_mfma_f32_16x16x32_bf16 v[92:95], v[112:115], v[206:209], v[92:95]
	v_mfma_f32_16x16x32_bf16 v[88:91], v[136:139], v[206:209], v[88:91]
	v_mfma_f32_16x16x32_bf16 v[76:79], v[112:115], v[214:217], v[76:79]
	v_mfma_f32_16x16x32_bf16 v[72:75], v[136:139], v[214:217], v[72:75]
	v_mfma_f32_16x16x32_bf16 v[128:131], v[144:147], v[174:177], v[128:131]
	v_mfma_f32_16x16x32_bf16 v[120:123], v[152:155], v[174:177], v[120:123]
	v_mfma_f32_16x16x32_bf16 v[104:107], v[144:147], v[194:197], v[104:107]
	v_mfma_f32_16x16x32_bf16 v[96:99], v[152:155], v[194:197], v[96:99]
	v_mfma_f32_16x16x32_bf16 v[84:87], v[144:147], v[202:205], v[84:87]
	v_mfma_f32_16x16x32_bf16 v[80:83], v[152:155], v[202:205], v[80:83]
	v_mfma_f32_16x16x32_bf16 v[68:71], v[144:147], v[210:213], v[68:71]
	v_mfma_f32_16x16x32_bf16 v[64:67], v[152:155], v[210:213], v[64:67]
	v_mfma_f32_16x16x32_bf16 v[128:131], v[148:151], v[178:181], v[128:131]
	v_mfma_f32_16x16x32_bf16 v[120:123], v[170:173], v[178:181], v[120:123]
	v_mfma_f32_16x16x32_bf16 v[104:107], v[148:151], v[198:201], v[104:107]
	v_mfma_f32_16x16x32_bf16 v[96:99], v[170:173], v[198:201], v[96:99]
	v_mfma_f32_16x16x32_bf16 v[84:87], v[148:151], v[206:209], v[84:87]
	v_mfma_f32_16x16x32_bf16 v[80:83], v[170:173], v[206:209], v[80:83]
	v_mfma_f32_16x16x32_bf16 v[68:71], v[148:151], v[214:217], v[68:71]
	v_mfma_f32_16x16x32_bf16 v[64:67], v[170:173], v[214:217], v[64:67]
	s_barrier
; #define PG8_STAGE(bufoff, gbase, voff) do { _Pragma("unroll") for (int _i = 0; _i < 2; ++_i) \
;         __builtin_amdgcn_global_load_lds((const unsigned*)((const char*)(gbase) + (voff)[_i]), (LAS unsigned*)(lds + (bufoff) + ldsw + _i * 8192), 16, 0, 0); } while (0)
; #define PG8_LDA(dst, b, h) do { _Pragma("unroll") for (int m = 0; m < 4; ++m) _Pragma("unroll") for (int k = 0; k < 2; ++k) dst[m][k] = *(const LAS bf16x8*)(lds + PG8_SA(b, h) + aoff + m * 2048 + k * 1024); } while (0)
; #define PG8_LDB(dst, b, h) do { _Pragma("unroll") for (int n = 0; n < 2; ++n) _Pragma("unroll") for (int k = 0; k < 2; ++k) dst[n][k] = *(const LAS bf16x8*)(lds + PG8_SB(b, h) + boff + n * 2048 + k * 1024); } while (0)
; #define PG8_MMA(ai, bj, At, Bt) do { __builtin_amdgcn_s_setprio(1); _Pragma("unroll") for (int m = 0; m < 4; ++m) _Pragma("unroll") for (int n = 0; n < 2; ++n) _Pragma("unroll") for (int k = 0; k < 2; ++k) \
;         acc[ai][bj][m][n] = __builtin_amdgcn_mfma_f32_16x16x32_bf16(Bt[n][k], At[m][k], acc[ai][bj][m][n], 0, 0, 0); __builtin_amdgcn_s_setprio(0); } while (0)
; #define PG8_WAIT_V(n) asm volatile("s_waitcnt vmcnt(" #n ")" ::: "memory")
; #define PG8_WAIT_L(n) asm volatile("s_waitcnt lgkmcnt(" #n ")" ::: "memory")
; #define PG8_BAR __builtin_amdgcn_s_barrier()
; #define PG8_SCHED __builtin_amdgcn_sched_barrier(0)
; template <class Epi, class Sched = StaticOrder, class EpiSub = NoSub, bool FAST = false>
; __device__ __forceinline__ void gemm_phase(LAS unsigned char* lds, const Gemm g, const Sched& S, const Epi& E, const EpiSub& ES = EpiSub()) {
;     ...
;             PG8_LDB(B0, 0, 0); PG8_LDB(B1, 0, 1); PG8_SCHED; PG8_LDA(At, 0, 0); PG8_STAGE(PG8_SA(1, 1), a1 + hstepA, voffA);
;             PG8_WAIT_V(8); PG8_WAIT_L(0); PG8_BAR; PG8_MMA(0, 0, At, B0); PG8_MMA(0, 1, At, B1); PG8_BAR; PG8_SCHED;
;     ...
;             PG8_LDA(At, 1, 1); PG8_STAGE(PG8_SB(1, 0), b3, voffB); PG8_STAGE(PG8_SB(1, 1), b3 + hstepB, voffB); PG8_STAGE(PG8_SA(1, 0), a3, voffA);
;             PG8_WAIT_V(8); PG8_WAIT_L(0); PG8_BAR; PG8_MMA(1, 0, At, B0); PG8_MMA(1, 1, At, B1); PG8_BAR; PG8_SCHED;
	s_setprio 1
	s_add_i32 s50, s50, s54
	v_lshl_add_u64 v[190:191], v[190:191], 0, s[12:13]
	s_mov_b32 m0, s50
	ds_read_b128 v[174:177], v188 offset:49152
	ds_read_b128 v[178:181], v188 offset:50176
	ds_read_b128 v[194:197], v188 offset:51200
	ds_read_b128 v[198:201], v188 offset:52224
	ds_read_b128 v[202:205], v188 offset:53248
	ds_read_b128 v[206:209], v188 offset:54272
	ds_read_b128 v[210:213], v188 offset:55296
	ds_read_b128 v[214:217], v188 offset:56320
	global_load_lds_dwordx4 v[190:191], off
	s_add_i32 m0, s50, 0x2000
	s_add_u32 s42, s42, 0x40080
	v_lshl_add_u64 v[190:191], v[218:219], 0, s[12:13]
	s_addc_u32 s43, s43, 0
	s_add_i32 s50, s70, s54
	global_load_lds_dwordx4 v[190:191], off
	v_lshl_add_u64 v[190:191], s[42:43], 0, v[158:159]
	s_mov_b32 m0, s50
	s_nop 0
	global_load_lds_dwordx4 v[190:191], off
	v_lshl_add_u64 v[190:191], s[42:43], 0, v[162:163]
	s_add_i32 m0, s50, 0x2000
	s_nop 0
	global_load_lds_dwordx4 v[190:191], off
	v_lshl_add_u64 v[190:191], v[220:221], 0, s[12:13]
	s_mov_b32 m0, s69
	s_nop 0
	global_load_lds_dwordx4 v[190:191], off
	v_lshl_add_u64 v[190:191], v[222:223], 0, s[12:13]
	s_mov_b32 m0, s74
	s_nop 0
	global_load_lds_dwordx4 v[190:191], off
	s_waitcnt vmcnt(8)
	s_waitcnt lgkmcnt(0)
	s_setprio 0
	s_barrier
	v_mfma_f32_16x16x32_bf16 v[60:63], v[100:103], v[174:177], v[60:63]
	v_mfma_f32_16x16x32_bf16 v[56:59], v[124:127], v[174:177], v[56:59]
	v_mfma_f32_16x16x32_bf16 v[44:47], v[100:103], v[194:197], v[44:47]
	v_mfma_f32_16x16x32_bf16 v[40:43], v[124:127], v[194:197], v[40:43]
	v_mfma_f32_16x16x32_bf16 v[28:31], v[100:103], v[202:205], v[28:31]
	v_mfma_f32_16x16x32_bf16 v[24:27], v[124:127], v[202:205], v[24:27]
	v_mfma_f32_16x16x32_bf16 v[12:15], v[100:103], v[210:213], v[12:15]
	v_mfma_f32_16x16x32_bf16 v[8:11], v[124:127], v[210:213], v[8:11]
	v_mfma_f32_16x16x32_bf16 v[60:63], v[112:115], v[178:181], v[60:63]
	v_mfma_f32_16x16x32_bf16 v[56:59], v[136:139], v[178:181], v[56:59]
	v_mfma_f32_16x16x32_bf16 v[44:47], v[112:115], v[198:201], v[44:47]
	v_mfma_f32_16x16x32_bf16 v[40:43], v[136:139], v[198:201], v[40:43]
	v_mfma_f32_16x16x32_bf16 v[28:31], v[112:115], v[206:209], v[28:31]
	v_mfma_f32_16x16x32_bf16 v[24:27], v[136:139], v[206:209], v[24:27]
	v_mfma_f32_16x16x32_bf16 v[12:15], v[112:115], v[214:217], v[12:15]
	v_mfma_f32_16x16x32_bf16 v[8:11], v[136:139], v[214:217], v[8:11]
	v_mfma_f32_16x16x32_bf16 v[52:55], v[144:147], v[174:177], v[52:55]
	v_mfma_f32_16x16x32_bf16 v[48:51], v[152:155], v[174:177], v[48:51]
	v_mfma_f32_16x16x32_bf16 v[36:39], v[144:147], v[194:197], v[36:39]
	v_mfma_f32_16x16x32_bf16 v[32:35], v[152:155], v[194:197], v[32:35]
	v_mfma_f32_16x16x32_bf16 v[20:23], v[144:147], v[202:205], v[20:23]
	v_mfma_f32_16x16x32_bf16 v[16:19], v[152:155], v[202:205], v[16:19]
	v_mfma_f32_16x16x32_bf16 v[4:7], v[144:147], v[210:213], v[4:7]
	v_mfma_f32_16x16x32_bf16 v[0:3], v[152:155], v[210:213], v[0:3]
	v_mfma_f32_16x16x32_bf16 v[52:55], v[148:151], v[178:181], v[52:55]
	v_mfma_f32_16x16x32_bf16 v[48:51], v[170:173], v[178:181], v[48:51]
	v_mfma_f32_16x16x32_bf16 v[36:39], v[148:151], v[198:201], v[36:39]
	v_mfma_f32_16x16x32_bf16 v[32:35], v[170:173], v[198:201], v[32:35]
	v_mfma_f32_16x16x32_bf16 v[20:23], v[148:151], v[206:209], v[20:23]
	v_mfma_f32_16x16x32_bf16 v[16:19], v[170:173], v[206:209], v[16:19]
	v_mfma_f32_16x16x32_bf16 v[4:7], v[148:151], v[214:217], v[4:7]
	v_mfma_f32_16x16x32_bf16 v[0:3], v[170:173], v[214:217], v[0:3]
	s_barrier
	s_setprio 1
	s_add_u32 s40, s40, 0x100
	s_addc_u32 s41, s41, 0
	s_add_u32 s48, s48, 0x100
	s_addc_u32 s49, s49, 0
	s_cmp_ge_u32 s51, s27
	s_mov_b32 s50, s51
	s_cbranch_scc1 .Lkpeel_600_exit
.LBB0_600:
	ds_read_b128 v[100:103], v186
	ds_read_b128 v[112:115], v186 offset:1024
	ds_read_b128 v[124:127], v186 offset:2048
	ds_read_b128 v[136:139], v186 offset:3072
	ds_read_b128 v[144:147], v187
	ds_read_b128 v[148:151], v187 offset:1024
	ds_read_b128 v[152:155], v187 offset:2048
	ds_read_b128 v[170:173], v187 offset:3072
	s_add_i32 s51, s50, 2
	s_add_u32 s42, s40, 0xfffc0080
	s_addc_u32 s43, s41, -1
	s_cmp_eq_u32 s33, s50
	s_cselect_b32 s53, s1, s43
	s_cselect_b32 s52, s5, s42
	s_cselect_b32 s43, s7, s49
	s_cselect_b32 s42, s25, s48
	v_lshl_add_u64 v[190:191], s[40:41], 0, v[164:165]
	s_add_i32 m0, s55, 0xc000
	ds_read_b128 v[174:177], v188
	ds_read_b128 v[178:181], v188 offset:1024
	ds_read_b128 v[194:197], v188 offset:2048
	ds_read_b128 v[198:201], v188 offset:3072
	ds_read_b128 v[202:205], v188 offset:4096
	ds_read_b128 v[206:209], v188 offset:5120
	ds_read_b128 v[210:213], v188 offset:6144
	ds_read_b128 v[214:217], v188 offset:7168
	global_load_lds_dwordx4 v[190:191], off
	v_lshl_add_u64 v[190:191], s[40:41], 0, v[166:167]
	s_add_i32 m0, s55, 0xe000
	s_nop 0
	global_load_lds_dwordx4 v[190:191], off
	s_waitcnt vmcnt(8)
	s_waitcnt lgkmcnt(0)
	s_setprio 0
	s_barrier
; #define PG8_STAGE(bufoff, gbase, voff) do { _Pragma("unroll") for (int _i = 0; _i < 2; ++_i) \
;         __builtin_amdgcn_global_load_lds((const unsigned*)((const char*)(gbase) + (voff)[_i]), (LAS unsigned*)(lds + (bufoff) + ldsw + _i * 8192), 16, 0, 0); } while (0)
; #define PG8_LDA(dst, b, h) do { _Pragma("unroll") for (int m = 0; m < 4; ++m) _Pragma("unroll") for (int k = 0; k < 2; ++k) dst[m][k] = *(const LAS bf16x8*)(lds + PG8_SA(b, h) + aoff + m * 2048 + k * 1024); } while (0)
; #define PG8_MMA(ai, bj, At, Bt) do { __builtin_amdgcn_s_setprio(1); _Pragma("unroll") for (int m = 0; m < 4; ++m) _Pragma("unroll") for (int n = 0; n < 2; ++n) _Pragma("unroll") for (int k = 0; k < 2; ++k) \
;         acc[ai][bj][m][n] = __builtin_amdgcn_mfma_f32_16x16x32_bf16(Bt[n][k], At[m][k], acc[ai][bj][m][n], 0, 0, 0); __builtin_amdgcn_s_setprio(0); } while (0)
; #define PG8_WAIT_V(n) asm volatile("s_waitcnt vmcnt(" #n ")" ::: "memory")
; #define PG8_WAIT_L(n) asm volatile("s_waitcnt lgkmcnt(" #n ")" ::: "memory")
; #define PG8_BAR __builtin_amdgcn_s_barrier()
; #define PG8_SCHED __builtin_amdgcn_sched_barrier(0)
; template <class Epi, class Sched = StaticOrder, class EpiSub = NoSub, bool FAST = false>
; __device__ __forceinline__ void gemm_phase(LAS unsigned char* lds, const Gemm g, const Sched& S, const Epi& E, const EpiSub& ES = EpiSub()) {
;     ...
;             PG8_WAIT_V(8); PG8_WAIT_L(0); PG8_BAR; PG8_MMA(0, 0, At, B0); PG8_MMA(0, 1, At, B1); PG8_BAR; PG8_SCHED;
;             PG8_LDA(At, 0, 1); PG8_STAGE(PG8_SB(0, 0), b2, voffB); PG8_STAGE(PG8_SB(0, 1), b2 + hstepB, voffB); PG8_STAGE(PG8_SA(0, 0), a2, voffA);
;             PG8_WAIT_V(8); PG8_WAIT_L(0); PG8_BAR; PG8_MMA(1, 0, At, B0); PG8_MMA(1, 1, At, B1); PG8_BAR; PG8_SCHED;
	v_mfma_f32_16x16x32_bf16 v[140:143], v[100:103], v[174:177], v[140:143]
	v_mfma_f32_16x16x32_bf16 v[132:135], v[124:127], v[174:177], v[132:135]
	v_mfma_f32_16x16x32_bf16 v[116:119], v[100:103], v[194:197], v[116:119]
	v_mfma_f32_16x16x32_bf16 v[108:111], v[124:127], v[194:197], v[108:111]
	v_mfma_f32_16x16x32_bf16 v[92:95], v[100:103], v[202:205], v[92:95]
	v_mfma_f32_16x16x32_bf16 v[88:91], v[124:127], v[202:205], v[88:91]
	v_mfma_f32_16x16x32_bf16 v[76:79], v[100:103], v[210:213], v[76:79]
	v_mfma_f32_16x16x32_bf16 v[72:75], v[124:127], v[210:213], v[72:75]
	v_mfma_f32_16x16x32_bf16 v[140:143], v[112:115], v[178:181], v[140:143]
	v_mfma_f32_16x16x32_bf16 v[132:135], v[136:139], v[178:181], v[132:135]
	v_mfma_f32_16x16x32_bf16 v[116:119], v[112:115], v[198:201], v[116:119]
	v_mfma_f32_16x16x32_bf16 v[108:111], v[136:139], v[198:201], v[108:111]
	v_mfma_f32_16x16x32_bf16 v[92:95], v[112:115], v[206:209], v[92:95]
	v_mfma_f32_16x16x32_bf16 v[88:91], v[136:139], v[206:209], v[88:91]
	v_mfma_f32_16x16x32_bf16 v[76:79], v[112:115], v[214:217], v[76:79]
	v_mfma_f32_16x16x32_bf16 v[72:75], v[136:139], v[214:217], v[72:75]
	v_mfma_f32_16x16x32_bf16 v[128:131], v[144:147], v[174:177], v[128:131]
	v_mfma_f32_16x16x32_bf16 v[120:123], v[152:155], v[174:177], v[120:123]
	v_mfma_f32_16x16x32_bf16 v[104:107], v[144:147], v[194:197], v[104:107]
	v_mfma_f32_16x16x32_bf16 v[96:99], v[152:155], v[194:197], v[96:99]
	v_mfma_f32_16x16x32_bf16 v[84:87], v[144:147], v[202:205], v[84:87]
	v_mfma_f32_16x16x32_bf16 v[80:83], v[152:155], v[202:205], v[80:83]
	v_mfma_f32_16x16x32_bf16 v[68:71], v[144:147], v[210:213], v[68:71]
	v_mfma_f32_16x16x32_bf16 v[64:67], v[152:155], v[210:213], v[64:67]
	v_mfma_f32_16x16x32_bf16 v[128:131], v[148:151], v[178:181], v[128:131]
	v_mfma_f32_16x16x32_bf16 v[120:123], v[170:173], v[178:181], v[120:123]
	v_mfma_f32_16x16x32_bf16 v[104:107], v[148:151], v[198:201], v[104:107]
	v_mfma_f32_16x16x32_bf16 v[96:99], v[170:173], v[198:201], v[96:99]
	v_mfma_f32_16x16x32_bf16 v[84:87], v[148:151], v[206:209], v[84:87]
	v_mfma_f32_16x16x32_bf16 v[80:83], v[170:173], v[206:209], v[80:83]
	v_mfma_f32_16x16x32_bf16 v[68:71], v[148:151], v[214:217], v[68:71]
	v_mfma_f32_16x16x32_bf16 v[64:67], v[170:173], v[214:217], v[64:67]
	s_barrier
	s_setprio 1
	s_add_i32 s50, s75, s54
	v_lshl_add_u64 v[190:191], s[42:43], 0, v[158:159]
	s_mov_b32 m0, s50
	ds_read_b128 v[174:177], v188 offset:16384
	ds_read_b128 v[178:181], v188 offset:17408
	ds_read_b128 v[194:197], v188 offset:18432
	ds_read_b128 v[198:201], v188 offset:19456
	ds_read_b128 v[202:205], v188 offset:20480
	ds_read_b128 v[206:209], v188 offset:21504
	ds_read_b128 v[210:213], v188 offset:22528
	ds_read_b128 v[214:217], v188 offset:23552
	global_load_lds_dwordx4 v[190:191], off
	s_add_i32 m0, s50, 0x2000
	s_add_u32 s70, s42, 0x40000
	v_lshl_add_u64 v[218:219], s[42:43], 0, v[162:163]
	s_addc_u32 s71, s43, 0
	s_add_i32 s50, s80, s54
	global_load_lds_dwordx4 v[218:219], off
	v_lshl_add_u64 v[220:221], s[70:71], 0, v[158:159]
	s_mov_b32 m0, s50
	v_lshl_add_u64 v[222:223], s[52:53], 0, v[160:161]
	global_load_lds_dwordx4 v[220:221], off
	v_lshl_add_u64 v[220:221], s[70:71], 0, v[162:163]
	s_add_i32 m0, s50, 0x2000
	s_nop 0
	global_load_lds_dwordx4 v[220:221], off
	v_lshl_add_u64 v[220:221], s[52:53], 0, v[156:157]
	s_mov_b32 m0, s55
	s_nop 0
	global_load_lds_dwordx4 v[220:221], off
	s_mov_b32 m0, s56
	s_nop 0
	global_load_lds_dwordx4 v[222:223], off
	s_waitcnt vmcnt(8)
	s_waitcnt lgkmcnt(0)
	s_setprio 0
	s_barrier
	v_mfma_f32_16x16x32_bf16 v[60:63], v[100:103], v[174:177], v[60:63]
	v_mfma_f32_16x16x32_bf16 v[56:59], v[124:127], v[174:177], v[56:59]
	v_mfma_f32_16x16x32_bf16 v[44:47], v[100:103], v[194:197], v[44:47]
	v_mfma_f32_16x16x32_bf16 v[40:43], v[124:127], v[194:197], v[40:43]
	v_mfma_f32_16x16x32_bf16 v[28:31], v[100:103], v[202:205], v[28:31]
	v_mfma_f32_16x16x32_bf16 v[24:27], v[124:127], v[202:205], v[24:27]
	v_mfma_f32_16x16x32_bf16 v[12:15], v[100:103], v[210:213], v[12:15]
	v_mfma_f32_16x16x32_bf16 v[8:11], v[124:127], v[210:213], v[8:11]
	v_mfma_f32_16x16x32_bf16 v[60:63], v[112:115], v[178:181], v[60:63]
	v_mfma_f32_16x16x32_bf16 v[56:59], v[136:139], v[178:181], v[56:59]
	v_mfma_f32_16x16x32_bf16 v[44:47], v[112:115], v[198:201], v[44:47]
	v_mfma_f32_16x16x32_bf16 v[40:43], v[136:139], v[198:201], v[40:43]
	v_mfma_f32_16x16x32_bf16 v[28:31], v[112:115], v[206:209], v[28:31]
	v_mfma_f32_16x16x32_bf16 v[24:27], v[136:139], v[206:209], v[24:27]
	v_mfma_f32_16x16x32_bf16 v[12:15], v[112:115], v[214:217], v[12:15]
	v_mfma_f32_16x16x32_bf16 v[8:11], v[136:139], v[214:217], v[8:11]
	v_mfma_f32_16x16x32_bf16 v[52:55], v[144:147], v[174:177], v[52:55]
	v_mfma_f32_16x16x32_bf16 v[48:51], v[152:155], v[174:177], v[48:51]
	v_mfma_f32_16x16x32_bf16 v[36:39], v[144:147], v[194:197], v[36:39]
	v_mfma_f32_16x16x32_bf16 v[32:35], v[152:155], v[194:197], v[32:35]
	v_mfma_f32_16x16x32_bf16 v[20:23], v[144:147], v[202:205], v[20:23]
	v_mfma_f32_16x16x32_bf16 v[16:19], v[152:155], v[202:205], v[16:19]
	v_mfma_f32_16x16x32_bf16 v[4:7], v[144:147], v[210:213], v[4:7]
	v_mfma_f32_16x16x32_bf16 v[0:3], v[152:155], v[210:213], v[0:3]
	v_mfma_f32_16x16x32_bf16 v[52:55], v[148:151], v[178:181], v[52:55]
	v_mfma_f32_16x16x32_bf16 v[48:51], v[170:173], v[178:181], v[48:51]
	v_mfma_f32_16x16x32_bf16 v[36:39], v[148:151], v[198:201], v[36:39]
	v_mfma_f32_16x16x32_bf16 v[32:35], v[170:173], v[198:201], v[32:35]
	v_mfma_f32_16x16x32_bf16 v[20:23], v[148:151], v[206:209], v[20:23]
	v_mfma_f32_16x16x32_bf16 v[16:19], v[170:173], v[206:209], v[16:19]
	v_mfma_f32_16x16x32_bf16 v[4:7], v[148:151], v[214:217], v[4:7]
	v_mfma_f32_16x16x32_bf16 v[0:3], v[170:173], v[214:217], v[0:3]
	s_barrier
; #define PG8_STAGE(bufoff, gbase, voff) do { _Pragma("unroll") for (int _i = 0; _i < 2; ++_i) \
;         __builtin_amdgcn_global_load_lds((const unsigned*)((const char*)(gbase) + (voff)[_i]), (LAS unsigned*)(lds + (bufoff) + ldsw + _i * 8192), 16, 0, 0); } while (0)
; #define PG8_LDA(dst, b, h) do { _Pragma("unroll") for (int m = 0; m < 4; ++m) _Pragma("unroll") for (int k = 0; k < 2; ++k) dst[m][k] = *(const LAS bf16x8*)(lds + PG8_SA(b, h) + aoff + m * 2048 + k * 1024); } while (0)
; #define PG8_LDB(dst, b, h) do { _Pragma("unroll") for (int n = 0; n < 2; ++n) _Pragma("unroll") for (int k = 0; k < 2; ++k) dst[n][k] = *(const LAS bf16x8*)(lds + PG8_SB(b, h) + boff + n * 2048 + k * 1024); } while (0)
; #define PG8_MMA(ai, bj, At, Bt) do { __builtin_amdgcn_s_setprio(1); _Pragma("unroll") for (int m = 0; m < 4; ++m) _Pragma("unroll") for (int n = 0; n < 2; ++n) _Pragma("unroll") for (int k = 0; k < 2; ++k) \
;         acc[ai][bj][m][n] = __builtin_amdgcn_mfma_f32_16x16x32_bf16(Bt[n][k], At[m][k], acc[ai][bj][m][n], 0, 0, 0); __builtin_amdgcn_s_setprio(0); } while (0)
; #define PG8_WAIT_V(n) asm volatile("s_waitcnt vmcnt(" #n ")" ::: "memory")
; #define PG8_WAIT_L(n) asm volatile("s_waitcnt lgkmcnt(" #n ")" ::: "memory")
; #define PG8_BAR __builtin_amdgcn_s_barrier()
; #define PG8_SCHED __builtin_amdgcn_sched_barrier(0)
; template <class Epi, class Sched = StaticOrder, class EpiSub = NoSub, bool FAST = false>
; __device__ __forceinline__ void gemm_phase(LAS unsigned char* lds, const Gemm g, const Sched& S, const Epi& E, const EpiSub& ES = EpiSub()) {
;     ...
;             PG8_LDB(B0, 1, 0); PG8_LDB(B1, 1, 1); PG8_SCHED; PG8_LDA(At, 1, 0); PG8_STAGE(PG8_SA(0, 1), a2 + hstepA, voffA);
;             PG8_WAIT_V(8); PG8_WAIT_L(0); PG8_BAR; PG8_MMA(0, 0, At, B0); PG8_MMA(0, 1, At, B1); PG8_BAR; PG8_SCHED;
	s_setprio 1
	s_add_i32 s50, 0, 0x18000
	s_add_i32 s70, 0, 0x1c000
	v_add_u32_e32 v136, s50, v183
	v_add_u32_e32 v170, s70, v183
	ds_read_b128 v[100:103], v136
	ds_read_b128 v[112:115], v136 offset:1024
	ds_read_b128 v[124:127], v136 offset:2048
	ds_read_b128 v[136:139], v136 offset:3072
	ds_read_b128 v[144:147], v170
	ds_read_b128 v[148:151], v170 offset:1024
	ds_read_b128 v[152:155], v170 offset:2048
	ds_read_b128 v[170:173], v170 offset:3072
	s_add_u32 s52, s52, 0x40000
	s_addc_u32 s53, s53, 0
	s_mov_b32 m0, s57
	v_lshl_add_u64 v[224:225], s[52:53], 0, v[156:157]
	ds_read_b128 v[174:177], v188 offset:32768
	ds_read_b128 v[178:181], v188 offset:33792
	ds_read_b128 v[194:197], v188 offset:34816
	ds_read_b128 v[198:201], v188 offset:35840
	ds_read_b128 v[202:205], v188 offset:36864
	ds_read_b128 v[206:209], v188 offset:37888
	ds_read_b128 v[210:213], v188 offset:38912
	ds_read_b128 v[214:217], v188 offset:39936
	global_load_lds_dwordx4 v[224:225], off
	v_lshl_add_u64 v[224:225], s[52:53], 0, v[160:161]
	s_mov_b32 m0, s58
	s_nop 0
	global_load_lds_dwordx4 v[224:225], off
	s_waitcnt vmcnt(8)
	s_waitcnt lgkmcnt(0)
	s_setprio 0
	s_barrier
	v_mfma_f32_16x16x32_bf16 v[140:143], v[100:103], v[174:177], v[140:143]
	v_mfma_f32_16x16x32_bf16 v[132:135], v[124:127], v[174:177], v[132:135]
	v_mfma_f32_16x16x32_bf16 v[116:119], v[100:103], v[194:197], v[116:119]
	v_mfma_f32_16x16x32_bf16 v[108:111], v[124:127], v[194:197], v[108:111]
	v_mfma_f32_16x16x32_bf16 v[92:95], v[100:103], v[202:205], v[92:95]
	v_mfma_f32_16x16x32_bf16 v[88:91], v[124:127], v[202:205], v[88:91]
	v_mfma_f32_16x16x32_bf16 v[76:79], v[100:103], v[210:213], v[76:79]
	v_mfma_f32_16x16x32_bf16 v[72:75], v[124:127], v[210:213], v[72:75]
	v_mfma_f32_16x16x32_bf16 v[140:143], v[112:115], v[178:181], v[140:143]
	v_mfma_f32_16x16x32_bf16 v[132:135], v[136:139], v[178:181], v[132:135]
	v_mfma_f32_16x16x32_bf16 v[116:119], v[112:115], v[198:201], v[116:119]
	v_mfma_f32_16x16x32_bf16 v[108:111], v[136:139], v[198:201], v[108:111]
	v_mfma_f32_16x16x32_bf16 v[92:95], v[112:115], v[206:209], v[92:95]
	v_mfma_f32_16x16x32_bf16 v[88:91], v[136:139], v[206:209], v[88:91]
	v_mfma_f32_16x16x32_bf16 v[76:79], v[112:115], v[214:217], v[76:79]
	v_mfma_f32_16x16x32_bf16 v[72:75], v[136:139], v[214:217], v[72:75]
	v_mfma_f32_16x16x32_bf16 v[128:131], v[144:147], v[174:177], v[128:131]
	v_mfma_f32_16x16x32_bf16 v[120:123], v[152:155], v[174:177], v[120:123]
	v_mfma_f32_16x16x32_bf16 v[104:107], v[144:147], v[194:197], v[104:107]
	v_mfma_f32_16x16x32_bf16 v[96:99], v[152:155], v[194:197], v[96:99]
	v_mfma_f32_16x16x32_bf16 v[84:87], v[144:147], v[202:205], v[84:87]
	v_mfma_f32_16x16x32_bf16 v[80:83], v[152:155], v[202:205], v[80:83]
	v_mfma_f32_16x16x32_bf16 v[68:71], v[144:147], v[210:213], v[68:71]
	v_mfma_f32_16x16x32_bf16 v[64:67], v[152:155], v[210:213], v[64:67]
	v_mfma_f32_16x16x32_bf16 v[128:131], v[148:151], v[178:181], v[128:131]
	v_mfma_f32_16x16x32_bf16 v[120:123], v[170:173], v[178:181], v[120:123]
	v_mfma_f32_16x16x32_bf16 v[104:107], v[148:151], v[198:201], v[104:107]
	v_mfma_f32_16x16x32_bf16 v[96:99], v[170:173], v[198:201], v[96:99]
	v_mfma_f32_16x16x32_bf16 v[84:87], v[148:151], v[206:209], v[84:87]
	v_mfma_f32_16x16x32_bf16 v[80:83], v[170:173], v[206:209], v[80:83]
	v_mfma_f32_16x16x32_bf16 v[68:71], v[148:151], v[214:217], v[68:71]
	v_mfma_f32_16x16x32_bf16 v[64:67], v[170:173], v[214:217], v[64:67]
	s_barrier
; #define PG8_STAGE(bufoff, gbase, voff) do { _Pragma("unroll") for (int _i = 0; _i < 2; ++_i) \
;         __builtin_amdgcn_global_load_lds((const unsigned*)((const char*)(gbase) + (voff)[_i]), (LAS unsigned*)(lds + (bufoff) + ldsw + _i * 8192), 16, 0, 0); } while (0)
; #define PG8_LDA(dst, b, h) do { _Pragma("unroll") for (int m = 0; m < 4; ++m) _Pragma("unroll") for (int k = 0; k < 2; ++k) dst[m][k] = *(const LAS bf16x8*)(lds + PG8_SA(b, h) + aoff + m * 2048 + k * 1024); } while (0)
; #define PG8_MMA(ai, bj, At, Bt) do { __builtin_amdgcn_s_setprio(1); _Pragma("unroll") for (int m = 0; m < 4; ++m) _Pragma("unroll") for (int n = 0; n < 2; ++n) _Pragma("unroll") for (int k = 0; k < 2; ++k) \
;         acc[ai][bj][m][n] = __builtin_amdgcn_mfma_f32_16x16x32_bf16(Bt[n][k], At[m][k], acc[ai][bj][m][n], 0, 0, 0); __builtin_amdgcn_s_setprio(0); } while (0)
; #define PG8_WAIT_V(n) asm volatile("s_waitcnt vmcnt(" #n ")" ::: "memory")
; #define PG8_WAIT_L(n) asm volatile("s_waitcnt lgkmcnt(" #n ")" ::: "memory")
; #define PG8_BAR __builtin_amdgcn_s_barrier()
; #define PG8_SCHED __builtin_amdgcn_sched_barrier(0)
; template <class Epi, class Sched = StaticOrder, class EpiSub = NoSub, bool FAST = false>
; __device__ __forceinline__ void gemm_phase(LAS unsigned char* lds, const Gemm g, const Sched& S, const Epi& E, const EpiSub& ES = EpiSub()) {
;     ...
;             PG8_LDA(At, 1, 1); PG8_STAGE(PG8_SB(1, 0), b3, voffB); PG8_STAGE(PG8_SB(1, 1), b3 + hstepB, voffB); PG8_STAGE(PG8_SA(1, 0), a3, voffA);
;             PG8_WAIT_V(8); PG8_WAIT_L(0); PG8_BAR; PG8_MMA(1, 0, At, B0); PG8_MMA(1, 1, At, B1); PG8_BAR; PG8_SCHED;
;     ...
;         if constexpr (FAST && PG8_ALIGN) { if (wr == 0) PG8_BAR; }
	s_setprio 1
	s_add_i32 s50, s50, s54
	v_lshl_add_u64 v[190:191], v[190:191], 0, s[12:13]
	s_mov_b32 m0, s50
	ds_read_b128 v[174:177], v188 offset:49152
	ds_read_b128 v[178:181], v188 offset:50176
	ds_read_b128 v[194:197], v188 offset:51200
	ds_read_b128 v[198:201], v188 offset:52224
	ds_read_b128 v[202:205], v188 offset:53248
	ds_read_b128 v[206:209], v188 offset:54272
	ds_read_b128 v[210:213], v188 offset:55296
	ds_read_b128 v[214:217], v188 offset:56320
	global_load_lds_dwordx4 v[190:191], off
	s_add_i32 m0, s50, 0x2000
	s_add_u32 s42, s42, 0x40080
	v_lshl_add_u64 v[190:191], v[218:219], 0, s[12:13]
	s_addc_u32 s43, s43, 0
	s_add_i32 s50, s70, s54
	global_load_lds_dwordx4 v[190:191], off
	v_lshl_add_u64 v[190:191], s[42:43], 0, v[158:159]
	s_mov_b32 m0, s50
	s_nop 0
	global_load_lds_dwordx4 v[190:191], off
	v_lshl_add_u64 v[190:191], s[42:43], 0, v[162:163]
	s_add_i32 m0, s50, 0x2000
	s_nop 0
	global_load_lds_dwordx4 v[190:191], off
	v_lshl_add_u64 v[190:191], v[220:221], 0, s[12:13]
	s_mov_b32 m0, s69
	s_nop 0
	global_load_lds_dwordx4 v[190:191], off
	v_lshl_add_u64 v[190:191], v[222:223], 0, s[12:13]
	s_mov_b32 m0, s74
	s_nop 0
	global_load_lds_dwordx4 v[190:191], off
	s_waitcnt vmcnt(8)
	s_waitcnt lgkmcnt(0)
	s_setprio 0
	s_barrier
	v_mfma_f32_16x16x32_bf16 v[60:63], v[100:103], v[174:177], v[60:63]
	v_mfma_f32_16x16x32_bf16 v[56:59], v[124:127], v[174:177], v[56:59]
	v_mfma_f32_16x16x32_bf16 v[44:47], v[100:103], v[194:197], v[44:47]
	v_mfma_f32_16x16x32_bf16 v[40:43], v[124:127], v[194:197], v[40:43]
	v_mfma_f32_16x16x32_bf16 v[28:31], v[100:103], v[202:205], v[28:31]
	v_mfma_f32_16x16x32_bf16 v[24:27], v[124:127], v[202:205], v[24:27]
	v_mfma_f32_16x16x32_bf16 v[12:15], v[100:103], v[210:213], v[12:15]
	v_mfma_f32_16x16x32_bf16 v[8:11], v[124:127], v[210:213], v[8:11]
	v_mfma_f32_16x16x32_bf16 v[60:63], v[112:115], v[178:181], v[60:63]
	v_mfma_f32_16x16x32_bf16 v[56:59], v[136:139], v[178:181], v[56:59]
	v_mfma_f32_16x16x32_bf16 v[44:47], v[112:115], v[198:201], v[44:47]
	v_mfma_f32_16x16x32_bf16 v[40:43], v[136:139], v[198:201], v[40:43]
	v_mfma_f32_16x16x32_bf16 v[28:31], v[112:115], v[206:209], v[28:31]
	v_mfma_f32_16x16x32_bf16 v[24:27], v[136:139], v[206:209], v[24:27]
	v_mfma_f32_16x16x32_bf16 v[12:15], v[112:115], v[214:217], v[12:15]
	v_mfma_f32_16x16x32_bf16 v[8:11], v[136:139], v[214:217], v[8:11]
	v_mfma_f32_16x16x32_bf16 v[52:55], v[144:147], v[174:177], v[52:55]
	v_mfma_f32_16x16x32_bf16 v[48:51], v[152:155], v[174:177], v[48:51]
	v_mfma_f32_16x16x32_bf16 v[36:39], v[144:147], v[194:197], v[36:39]
	v_mfma_f32_16x16x32_bf16 v[32:35], v[152:155], v[194:197], v[32:35]
	v_mfma_f32_16x16x32_bf16 v[20:23], v[144:147], v[202:205], v[20:23]
	v_mfma_f32_16x16x32_bf16 v[16:19], v[152:155], v[202:205], v[16:19]
	v_mfma_f32_16x16x32_bf16 v[4:7], v[144:147], v[210:213], v[4:7]
	v_mfma_f32_16x16x32_bf16 v[0:3], v[152:155], v[210:213], v[0:3]
	v_mfma_f32_16x16x32_bf16 v[52:55], v[148:151], v[178:181], v[52:55]
	v_mfma_f32_16x16x32_bf16 v[48:51], v[170:173], v[178:181], v[48:51]
	v_mfma_f32_16x16x32_bf16 v[36:39], v[148:151], v[198:201], v[36:39]
	v_mfma_f32_16x16x32_bf16 v[32:35], v[170:173], v[198:201], v[32:35]
	v_mfma_f32_16x16x32_bf16 v[20:23], v[148:151], v[206:209], v[20:23]
	v_mfma_f32_16x16x32_bf16 v[16:19], v[170:173], v[206:209], v[16:19]
	v_mfma_f32_16x16x32_bf16 v[4:7], v[148:151], v[214:217], v[4:7]
	v_mfma_f32_16x16x32_bf16 v[0:3], v[170:173], v[214:217], v[0:3]
	s_barrier
	s_setprio 1
	s_add_u32 s40, s40, 0x100
	s_addc_u32 s41, s41, 0
	s_add_u32 s48, s48, 0x100
	s_addc_u32 s49, s49, 0
	s_cmp_ge_u32 s51, s27
	s_mov_b32 s50, s51
	s_cbranch_scc0 .LBB0_600
.Lkpeel_600_exit:
	s_setprio 0
	s_and_b64 vcc, exec, s[14:15]
	s_cbranch_vccz .LBB0_603
	s_barrier

; #define PG8_STAGE(bufoff, gbase, voff) do { _Pragma("unroll") for (int _i = 0; _i < 2; ++_i) \
;         __builtin_amdgcn_global_load_lds((const unsigned*)((const char*)(gbase) + (voff)[_i]), (LAS unsigned*)(lds + (bufoff) + ldsw + _i * 8192), 16, 0, 0); } while (0)
; #define PG8_LDA(dst, b, h) do { _Pragma("unroll") for (int m = 0; m < 4; ++m) _Pragma("unroll") for (int k = 0; k < 2; ++k) dst[m][k] = *(const LAS bf16x8*)(lds + PG8_SA(b, h) + aoff + m * 2048 + k * 1024); } while (0)
; #define PG8_LDB(dst, b, h) do { _Pragma("unroll") for (int n = 0; n < 2; ++n) _Pragma("unroll") for (int k = 0; k < 2; ++k) dst[n][k] = *(const LAS bf16x8*)(lds + PG8_SB(b, h) + boff + n * 2048 + k * 1024); } while (0)
; #define PG8_WAIT_V(n) asm volatile("s_waitcnt vmcnt(" #n ")" ::: "memory")
; #define PG8_WAIT_L(n) asm volatile("s_waitcnt lgkmcnt(" #n ")" ::: "memory")
; #define PG8_BAR __builtin_amdgcn_s_barrier()
; #define PG8_SCHED __builtin_amdgcn_sched_barrier(0)
; template <class Epi, class Sched = StaticOrder, class EpiSub = NoSub, bool FAST = false>
; __device__ __forceinline__ void gemm_phase(LAS unsigned char* lds, const Gemm g, const Sched& S, const Epi& E, const EpiSub& ES = EpiSub()) {
;     ...
;         const bool has_next = S.next(ui + 1, nxt);
;         const size_t nko = (has_next && nxt.kb >= 0) ? nxt.kb * ksubB : 0;
;         const char* nA = has_next ? (const char*)g.A + (size_t)nxt.pm * tstepA + (size_t)nxt.pn * g.acs + nko : cA; const char* nB = has_next ? (const char*)g.Bt + (size_t)nxt.pn * tstepB + nko : cB;
;         const int nt = cur.kb < 0 ? ntMain : ntSub;
;         for (int t = 0; t < nt; t += 2) {
;             const bool last = (t == nt - 2);
;             const char* a1 = cA + (size_t)(t + 1) * kstep;
;             const char* a2 = last ? nA : cA + (size_t)(t + 2) * kstep; const char* b2 = last ? nB : cB + (size_t)(t + 2) * kstep;
;             const char* a3 = a2 + kstep; const char* b3 = b2 + kstep;
;             if constexpr (FAST && PG8_SP2) {
;             PG8_LDB(B0, 0, 0); PG8_LDB(B1, 0, 1); PG8_SCHED; PG8_LDA(At, 0, 0); PG8_STAGE(PG8_SA(1, 1), a1 + hstepA, voffA);
;             PG8_WAIT_V(8); PG8_WAIT_L(0); PG8_BAR; PG8_MMA(0, 0, At, B0); PG8_MMA(0, 1, At, B1); PG8_BAR; PG8_SCHED;
;             PG8_LDA(At, 0, 1); PG8_STAGE(PG8_SB(0, 0), b2, voffB); PG8_STAGE(PG8_SB(0, 1), b2 + hstepB, voffB); PG8_STAGE(PG8_SA(0, 0), a2, voffA);
.LBB0_631:
	s_cmp_gt_i32 s8, -1
	s_cselect_b64 s[26:27], -1, 0
	s_and_b64 s[26:27], s[24:25], s[26:27]
	s_lshl_b64 s[28:29], s[8:9], 10
	s_and_b64 s[26:27], s[26:27], exec
	s_cselect_b32 s31, s29, 0
	s_cselect_b32 s33, s28, 0
	s_ashr_i32 s23, s22, 31
	s_lshl_b64 s[26:27], s[22:23], 20
	v_readlane_b32 s28, v254, 36
	v_readlane_b32 s29, v254, 37
	s_add_u32 s1, s28, s26
	s_addc_u32 s5, s29, s27
	s_add_u32 s26, s1, s33
	s_addc_u32 s27, s5, s31
	s_and_b64 s[28:29], s[24:25], exec
	s_cselect_b32 s1, s27, s39
	s_cselect_b32 s5, s26, s38
	s_ashr_i32 s21, s20, 31
	s_lshl_b64 s[28:29], s[20:21], 20
	s_add_u32 s21, s2, s28
	s_addc_u32 s23, s3, s29
	s_add_u32 s28, s21, s33
	s_addc_u32 s29, s23, s31
	s_and_b64 s[36:37], s[24:25], exec
	s_cselect_b32 s21, s29, s41
	s_cselect_b32 s23, s28, s40
	s_cmp_gt_i32 s0, -1
	s_cselect_b64 s[36:37], -1, 0
	s_cmp_lt_i32 s0, 0
	s_cselect_b32 s31, 32, 8
	s_add_i32 s33, s31, -2
	s_add_u32 s38, s38, 0x80080
	s_addc_u32 s39, s39, 0
	s_add_u32 s48, s40, 0x100
	s_mov_b32 s42, 0
	s_addc_u32 s49, s41, 0
	ds_read_b128 v[104:107], v224
	ds_read_b128 v[108:111], v224 offset:1024
	ds_read_b128 v[120:123], v224 offset:2048
	ds_read_b128 v[124:127], v224 offset:3072
	ds_read_b128 v[136:139], v225
	ds_read_b128 v[140:143], v225 offset:1024
	ds_read_b128 v[152:155], v225 offset:2048
	ds_read_b128 v[156:159], v225 offset:3072
	s_add_i32 s50, s42, 2
	s_add_u32 s40, s38, 0xfff80080
	s_addc_u32 s41, s39, -1
	s_cmp_eq_u32 s33, s42
	s_cselect_b32 s42, s5, s40
	s_cselect_b32 s43, s1, s41
	s_cselect_b32 s41, s21, s49
	s_cselect_b32 s40, s23, s48
	v_lshl_add_u64 v[208:209], s[38:39], 0, v[202:203]
	s_add_i32 m0, s53, 0xc000
	ds_read_b128 v[160:163], v226
	ds_read_b128 v[164:167], v226 offset:1024
	ds_read_b128 v[168:171], v226 offset:2048
	ds_read_b128 v[172:175], v226 offset:3072
	ds_read_b128 v[176:179], v226 offset:4096
	ds_read_b128 v[180:183], v226 offset:5120
	ds_read_b128 v[184:187], v226 offset:6144
	ds_read_b128 v[188:191], v226 offset:7168
	global_load_lds_dwordx4 v[208:209], off
	v_lshl_add_u64 v[208:209], s[38:39], 0, v[204:205]
	s_add_i32 m0, s53, 0xe000
	s_nop 0
	global_load_lds_dwordx4 v[208:209], off
	s_waitcnt vmcnt(8)
	s_waitcnt lgkmcnt(0)
	s_setprio 0
	s_barrier
	v_mfma_f32_16x16x32_bf16 v[148:151], v[104:107], v[160:163], 0
	v_mfma_f32_16x16x32_bf16 v[144:147], v[120:123], v[160:163], 0
	v_mfma_f32_16x16x32_bf16 v[116:119], v[104:107], v[168:171], 0
	v_mfma_f32_16x16x32_bf16 v[112:115], v[120:123], v[168:171], 0
	v_mfma_f32_16x16x32_bf16 v[92:95], v[104:107], v[176:179], 0
	v_mfma_f32_16x16x32_bf16 v[88:91], v[120:123], v[176:179], 0
	v_mfma_f32_16x16x32_bf16 v[76:79], v[104:107], v[184:187], 0
	v_mfma_f32_16x16x32_bf16 v[72:75], v[120:123], v[184:187], 0
	v_mfma_f32_16x16x32_bf16 v[148:151], v[108:111], v[164:167], v[148:151]
	v_mfma_f32_16x16x32_bf16 v[144:147], v[124:127], v[164:167], v[144:147]
	v_mfma_f32_16x16x32_bf16 v[116:119], v[108:111], v[172:175], v[116:119]
	v_mfma_f32_16x16x32_bf16 v[112:115], v[124:127], v[172:175], v[112:115]
	v_mfma_f32_16x16x32_bf16 v[92:95], v[108:111], v[180:183], v[92:95]
	v_mfma_f32_16x16x32_bf16 v[88:91], v[124:127], v[180:183], v[88:91]
	v_mfma_f32_16x16x32_bf16 v[76:79], v[108:111], v[188:191], v[76:79]
	v_mfma_f32_16x16x32_bf16 v[72:75], v[124:127], v[188:191], v[72:75]
	v_mfma_f32_16x16x32_bf16 v[132:135], v[136:139], v[160:163], 0
	v_mfma_f32_16x16x32_bf16 v[128:131], v[152:155], v[160:163], 0
	v_mfma_f32_16x16x32_bf16 v[100:103], v[136:139], v[168:171], 0
	v_mfma_f32_16x16x32_bf16 v[96:99], v[152:155], v[168:171], 0
	v_mfma_f32_16x16x32_bf16 v[84:87], v[136:139], v[176:179], 0
	v_mfma_f32_16x16x32_bf16 v[80:83], v[152:155], v[176:179], 0
	v_mfma_f32_16x16x32_bf16 v[68:71], v[136:139], v[184:187], 0
	v_mfma_f32_16x16x32_bf16 v[64:67], v[152:155], v[184:187], 0
	v_mfma_f32_16x16x32_bf16 v[132:135], v[140:143], v[164:167], v[132:135]
	v_mfma_f32_16x16x32_bf16 v[128:131], v[156:159], v[164:167], v[128:131]
	v_mfma_f32_16x16x32_bf16 v[100:103], v[140:143], v[172:175], v[100:103]
	v_mfma_f32_16x16x32_bf16 v[96:99], v[156:159], v[172:175], v[96:99]
	v_mfma_f32_16x16x32_bf16 v[84:87], v[140:143], v[180:183], v[84:87]
	v_mfma_f32_16x16x32_bf16 v[80:83], v[156:159], v[180:183], v[80:83]
	v_mfma_f32_16x16x32_bf16 v[68:71], v[140:143], v[188:191], v[68:71]
	v_mfma_f32_16x16x32_bf16 v[64:67], v[156:159], v[188:191], v[64:67]
	s_barrier
	s_setprio 1
	s_add_i32 s51, s75, s52
	v_lshl_add_u64 v[208:209], s[40:41], 0, v[196:197]
	s_mov_b32 m0, s51
	ds_read_b128 v[160:163], v226 offset:16384
	ds_read_b128 v[164:167], v226 offset:17408
	ds_read_b128 v[168:171], v226 offset:18432
	ds_read_b128 v[172:175], v226 offset:19456
	ds_read_b128 v[176:179], v226 offset:20480
	ds_read_b128 v[180:183], v226 offset:21504
	ds_read_b128 v[184:187], v226 offset:22528
	ds_read_b128 v[188:191], v226 offset:23552
	global_load_lds_dwordx4 v[208:209], off
	s_add_i32 m0, s51, 0x2000
	s_add_u32 s70, s40, 0x80000
	v_lshl_add_u64 v[210:211], s[40:41], 0, v[200:201]
	s_addc_u32 s71, s41, 0
	s_add_i32 s51, s78, s52
	global_load_lds_dwordx4 v[210:211], off
	v_lshl_add_u64 v[212:213], s[70:71], 0, v[196:197]
	s_mov_b32 m0, s51
	v_lshl_add_u64 v[214:215], s[42:43], 0, v[198:199]
	global_load_lds_dwordx4 v[212:213], off
	v_lshl_add_u64 v[212:213], s[70:71], 0, v[200:201]
	s_add_i32 m0, s51, 0x2000
	s_nop 0
	global_load_lds_dwordx4 v[212:213], off
	v_lshl_add_u64 v[212:213], s[42:43], 0, v[194:195]
	s_mov_b32 m0, s53
	s_nop 0
	global_load_lds_dwordx4 v[212:213], off
	s_mov_b32 m0, s54
	s_nop 0
	global_load_lds_dwordx4 v[214:215], off
	s_waitcnt vmcnt(8)
	s_waitcnt lgkmcnt(0)
	s_setprio 0
	s_barrier
; #define PG8_STAGE(bufoff, gbase, voff) do { _Pragma("unroll") for (int _i = 0; _i < 2; ++_i) \
;         __builtin_amdgcn_global_load_lds((const unsigned*)((const char*)(gbase) + (voff)[_i]), (LAS unsigned*)(lds + (bufoff) + ldsw + _i * 8192), 16, 0, 0); } while (0)
; #define PG8_LDA(dst, b, h) do { _Pragma("unroll") for (int m = 0; m < 4; ++m) _Pragma("unroll") for (int k = 0; k < 2; ++k) dst[m][k] = *(const LAS bf16x8*)(lds + PG8_SA(b, h) + aoff + m * 2048 + k * 1024); } while (0)
; #define PG8_LDB(dst, b, h) do { _Pragma("unroll") for (int n = 0; n < 2; ++n) _Pragma("unroll") for (int k = 0; k < 2; ++k) dst[n][k] = *(const LAS bf16x8*)(lds + PG8_SB(b, h) + boff + n * 2048 + k * 1024); } while (0)
; #define PG8_MMA(ai, bj, At, Bt) do { __builtin_amdgcn_s_setprio(1); _Pragma("unroll") for (int m = 0; m < 4; ++m) _Pragma("unroll") for (int n = 0; n < 2; ++n) _Pragma("unroll") for (int k = 0; k < 2; ++k) \
;         acc[ai][bj][m][n] = __builtin_amdgcn_mfma_f32_16x16x32_bf16(Bt[n][k], At[m][k], acc[ai][bj][m][n], 0, 0, 0); __builtin_amdgcn_s_setprio(0); } while (0)
; #define PG8_WAIT_V(n) asm volatile("s_waitcnt vmcnt(" #n ")" ::: "memory")
; #define PG8_WAIT_L(n) asm volatile("s_waitcnt lgkmcnt(" #n ")" ::: "memory")
; #define PG8_BAR __builtin_amdgcn_s_barrier()
; #define PG8_SCHED __builtin_amdgcn_sched_barrier(0)
; template <class Epi, class Sched = StaticOrder, class EpiSub = NoSub, bool FAST = false>
; __device__ __forceinline__ void gemm_phase(LAS unsigned char* lds, const Gemm g, const Sched& S, const Epi& E, const EpiSub& ES = EpiSub()) {
;     ...
;             PG8_WAIT_V(8); PG8_WAIT_L(0); PG8_BAR; PG8_MMA(1, 0, At, B0); PG8_MMA(1, 1, At, B1); PG8_BAR; PG8_SCHED;
;             PG8_LDB(B0, 1, 0); PG8_LDB(B1, 1, 1); PG8_SCHED; PG8_LDA(At, 1, 0); PG8_STAGE(PG8_SA(0, 1), a2 + hstepA, voffA);
;             PG8_WAIT_V(8); PG8_WAIT_L(0); PG8_BAR; PG8_MMA(0, 0, At, B0); PG8_MMA(0, 1, At, B1); PG8_BAR; PG8_SCHED;
	v_mfma_f32_16x16x32_bf16 v[60:63], v[104:107], v[160:163], 0
	v_mfma_f32_16x16x32_bf16 v[56:59], v[120:123], v[160:163], 0
	v_mfma_f32_16x16x32_bf16 v[44:47], v[104:107], v[168:171], 0
	v_mfma_f32_16x16x32_bf16 v[40:43], v[120:123], v[168:171], 0
	v_mfma_f32_16x16x32_bf16 v[28:31], v[104:107], v[176:179], 0
	v_mfma_f32_16x16x32_bf16 v[24:27], v[120:123], v[176:179], 0
	v_mfma_f32_16x16x32_bf16 v[12:15], v[104:107], v[184:187], 0
	v_mfma_f32_16x16x32_bf16 v[8:11], v[120:123], v[184:187], 0
	v_mfma_f32_16x16x32_bf16 v[60:63], v[108:111], v[164:167], v[60:63]
	v_mfma_f32_16x16x32_bf16 v[56:59], v[124:127], v[164:167], v[56:59]
	v_mfma_f32_16x16x32_bf16 v[44:47], v[108:111], v[172:175], v[44:47]
	v_mfma_f32_16x16x32_bf16 v[40:43], v[124:127], v[172:175], v[40:43]
	v_mfma_f32_16x16x32_bf16 v[28:31], v[108:111], v[180:183], v[28:31]
	v_mfma_f32_16x16x32_bf16 v[24:27], v[124:127], v[180:183], v[24:27]
	v_mfma_f32_16x16x32_bf16 v[12:15], v[108:111], v[188:191], v[12:15]
	v_mfma_f32_16x16x32_bf16 v[8:11], v[124:127], v[188:191], v[8:11]
	v_mfma_f32_16x16x32_bf16 v[52:55], v[136:139], v[160:163], 0
	v_mfma_f32_16x16x32_bf16 v[48:51], v[152:155], v[160:163], 0
	v_mfma_f32_16x16x32_bf16 v[36:39], v[136:139], v[168:171], 0
	v_mfma_f32_16x16x32_bf16 v[32:35], v[152:155], v[168:171], 0
	v_mfma_f32_16x16x32_bf16 v[20:23], v[136:139], v[176:179], 0
	v_mfma_f32_16x16x32_bf16 v[16:19], v[152:155], v[176:179], 0
	v_mfma_f32_16x16x32_bf16 v[4:7], v[136:139], v[184:187], 0
	v_mfma_f32_16x16x32_bf16 v[0:3], v[152:155], v[184:187], 0
	v_mfma_f32_16x16x32_bf16 v[52:55], v[140:143], v[164:167], v[52:55]
	v_mfma_f32_16x16x32_bf16 v[48:51], v[156:159], v[164:167], v[48:51]
	v_mfma_f32_16x16x32_bf16 v[36:39], v[140:143], v[172:175], v[36:39]
	v_mfma_f32_16x16x32_bf16 v[32:35], v[156:159], v[172:175], v[32:35]
	v_mfma_f32_16x16x32_bf16 v[20:23], v[140:143], v[180:183], v[20:23]
	v_mfma_f32_16x16x32_bf16 v[16:19], v[156:159], v[180:183], v[16:19]
	v_mfma_f32_16x16x32_bf16 v[4:7], v[140:143], v[188:191], v[4:7]
	v_mfma_f32_16x16x32_bf16 v[0:3], v[156:159], v[188:191], v[0:3]
	s_barrier
	s_setprio 1
	s_add_i32 s51, 0, 0x18000
	s_add_i32 s70, 0, 0x1c000
	v_add_u32_e32 v124, s51, v221
	v_add_u32_e32 v156, s70, v221
	ds_read_b128 v[104:107], v124
	ds_read_b128 v[108:111], v124 offset:1024
	ds_read_b128 v[120:123], v124 offset:2048
	ds_read_b128 v[124:127], v124 offset:3072
	ds_read_b128 v[136:139], v156
	ds_read_b128 v[140:143], v156 offset:1024
	ds_read_b128 v[152:155], v156 offset:2048
	ds_read_b128 v[156:159], v156 offset:3072
	s_add_u32 s42, s42, 0x80000
	s_addc_u32 s43, s43, 0
	s_mov_b32 m0, s55
	v_lshl_add_u64 v[216:217], s[42:43], 0, v[194:195]
	ds_read_b128 v[160:163], v226 offset:32768
	ds_read_b128 v[164:167], v226 offset:33792
	ds_read_b128 v[168:171], v226 offset:34816
	ds_read_b128 v[172:175], v226 offset:35840
	ds_read_b128 v[176:179], v226 offset:36864
	ds_read_b128 v[180:183], v226 offset:37888
	ds_read_b128 v[184:187], v226 offset:38912
	ds_read_b128 v[188:191], v226 offset:39936
	global_load_lds_dwordx4 v[216:217], off
	v_lshl_add_u64 v[216:217], s[42:43], 0, v[198:199]
	s_mov_b32 m0, s56
	s_nop 0
	global_load_lds_dwordx4 v[216:217], off
	s_waitcnt vmcnt(8)
	s_waitcnt lgkmcnt(0)
	s_setprio 0
	s_barrier
	v_mfma_f32_16x16x32_bf16 v[148:151], v[104:107], v[160:163], v[148:151]
	v_mfma_f32_16x16x32_bf16 v[144:147], v[120:123], v[160:163], v[144:147]
	v_mfma_f32_16x16x32_bf16 v[116:119], v[104:107], v[168:171], v[116:119]
	v_mfma_f32_16x16x32_bf16 v[112:115], v[120:123], v[168:171], v[112:115]
	v_mfma_f32_16x16x32_bf16 v[92:95], v[104:107], v[176:179], v[92:95]
	v_mfma_f32_16x16x32_bf16 v[88:91], v[120:123], v[176:179], v[88:91]
	v_mfma_f32_16x16x32_bf16 v[76:79], v[104:107], v[184:187], v[76:79]
	v_mfma_f32_16x16x32_bf16 v[72:75], v[120:123], v[184:187], v[72:75]
	v_mfma_f32_16x16x32_bf16 v[148:151], v[108:111], v[164:167], v[148:151]
	v_mfma_f32_16x16x32_bf16 v[144:147], v[124:127], v[164:167], v[144:147]
	v_mfma_f32_16x16x32_bf16 v[116:119], v[108:111], v[172:175], v[116:119]
	v_mfma_f32_16x16x32_bf16 v[112:115], v[124:127], v[172:175], v[112:115]
	v_mfma_f32_16x16x32_bf16 v[92:95], v[108:111], v[180:183], v[92:95]
	v_mfma_f32_16x16x32_bf16 v[88:91], v[124:127], v[180:183], v[88:91]
	v_mfma_f32_16x16x32_bf16 v[76:79], v[108:111], v[188:191], v[76:79]
	v_mfma_f32_16x16x32_bf16 v[72:75], v[124:127], v[188:191], v[72:75]
	v_mfma_f32_16x16x32_bf16 v[132:135], v[136:139], v[160:163], v[132:135]
	v_mfma_f32_16x16x32_bf16 v[128:131], v[152:155], v[160:163], v[128:131]
	v_mfma_f32_16x16x32_bf16 v[100:103], v[136:139], v[168:171], v[100:103]
	v_mfma_f32_16x16x32_bf16 v[96:99], v[152:155], v[168:171], v[96:99]
	v_mfma_f32_16x16x32_bf16 v[84:87], v[136:139], v[176:179], v[84:87]
	v_mfma_f32_16x16x32_bf16 v[80:83], v[152:155], v[176:179], v[80:83]
	v_mfma_f32_16x16x32_bf16 v[68:71], v[136:139], v[184:187], v[68:71]
	v_mfma_f32_16x16x32_bf16 v[64:67], v[152:155], v[184:187], v[64:67]
	v_mfma_f32_16x16x32_bf16 v[132:135], v[140:143], v[164:167], v[132:135]
	v_mfma_f32_16x16x32_bf16 v[128:131], v[156:159], v[164:167], v[128:131]
	v_mfma_f32_16x16x32_bf16 v[100:103], v[140:143], v[172:175], v[100:103]
	v_mfma_f32_16x16x32_bf16 v[96:99], v[156:159], v[172:175], v[96:99]
	v_mfma_f32_16x16x32_bf16 v[84:87], v[140:143], v[180:183], v[84:87]
	v_mfma_f32_16x16x32_bf16 v[80:83], v[156:159], v[180:183], v[80:83]
	v_mfma_f32_16x16x32_bf16 v[68:71], v[140:143], v[188:191], v[68:71]
	v_mfma_f32_16x16x32_bf16 v[64:67], v[156:159], v[188:191], v[64:67]
	s_barrier
; #define PG8_STAGE(bufoff, gbase, voff) do { _Pragma("unroll") for (int _i = 0; _i < 2; ++_i) \
;         __builtin_amdgcn_global_load_lds((const unsigned*)((const char*)(gbase) + (voff)[_i]), (LAS unsigned*)(lds + (bufoff) + ldsw + _i * 8192), 16, 0, 0); } while (0)
; #define PG8_LDA(dst, b, h) do { _Pragma("unroll") for (int m = 0; m < 4; ++m) _Pragma("unroll") for (int k = 0; k < 2; ++k) dst[m][k] = *(const LAS bf16x8*)(lds + PG8_SA(b, h) + aoff + m * 2048 + k * 1024); } while (0)
; #define PG8_LDB(dst, b, h) do { _Pragma("unroll") for (int n = 0; n < 2; ++n) _Pragma("unroll") for (int k = 0; k < 2; ++k) dst[n][k] = *(const LAS bf16x8*)(lds + PG8_SB(b, h) + boff + n * 2048 + k * 1024); } while (0)
; #define PG8_MMA(ai, bj, At, Bt) do { __builtin_amdgcn_s_setprio(1); _Pragma("unroll") for (int m = 0; m < 4; ++m) _Pragma("unroll") for (int n = 0; n < 2; ++n) _Pragma("unroll") for (int k = 0; k < 2; ++k) \
;         acc[ai][bj][m][n] = __builtin_amdgcn_mfma_f32_16x16x32_bf16(Bt[n][k], At[m][k], acc[ai][bj][m][n], 0, 0, 0); __builtin_amdgcn_s_setprio(0); } while (0)
; #define PG8_WAIT_V(n) asm volatile("s_waitcnt vmcnt(" #n ")" ::: "memory")
; #define PG8_WAIT_L(n) asm volatile("s_waitcnt lgkmcnt(" #n ")" ::: "memory")
; #define PG8_BAR __builtin_amdgcn_s_barrier()
; #define PG8_SCHED __builtin_amdgcn_sched_barrier(0)
; template <class Epi, class Sched = StaticOrder, class EpiSub = NoSub, bool FAST = false>
; __device__ __forceinline__ void gemm_phase(LAS unsigned char* lds, const Gemm g, const Sched& S, const Epi& E, const EpiSub& ES = EpiSub()) {
;     ...
;             PG8_LDB(B0, 0, 0); PG8_LDB(B1, 0, 1); PG8_SCHED; PG8_LDA(At, 0, 0); PG8_STAGE(PG8_SA(1, 1), a1 + hstepA, voffA);
;             PG8_WAIT_V(8); PG8_WAIT_L(0); PG8_BAR; PG8_MMA(0, 0, At, B0); PG8_MMA(0, 1, At, B1); PG8_BAR; PG8_SCHED;
;     ...
;             PG8_LDA(At, 1, 1); PG8_STAGE(PG8_SB(1, 0), b3, voffB); PG8_STAGE(PG8_SB(1, 1), b3 + hstepB, voffB); PG8_STAGE(PG8_SA(1, 0), a3, voffA);
;             PG8_WAIT_V(8); PG8_WAIT_L(0); PG8_BAR; PG8_MMA(1, 0, At, B0); PG8_MMA(1, 1, At, B1); PG8_BAR; PG8_SCHED;
	s_setprio 1
	s_add_i32 s42, s51, s52
	v_lshl_add_u64 v[208:209], v[208:209], 0, s[12:13]
	s_mov_b32 m0, s42
	ds_read_b128 v[160:163], v226 offset:49152
	ds_read_b128 v[164:167], v226 offset:50176
	ds_read_b128 v[168:171], v226 offset:51200
	ds_read_b128 v[172:175], v226 offset:52224
	ds_read_b128 v[176:179], v226 offset:53248
	ds_read_b128 v[180:183], v226 offset:54272
	ds_read_b128 v[184:187], v226 offset:55296
	ds_read_b128 v[188:191], v226 offset:56320
	global_load_lds_dwordx4 v[208:209], off
	s_add_i32 m0, s42, 0x2000
	s_add_u32 s40, s40, 0x80080
	v_lshl_add_u64 v[208:209], v[210:211], 0, s[12:13]
	s_addc_u32 s41, s41, 0
	s_add_i32 s42, s70, s52
	global_load_lds_dwordx4 v[208:209], off
	v_lshl_add_u64 v[208:209], s[40:41], 0, v[196:197]
	s_mov_b32 m0, s42
	s_nop 0
	global_load_lds_dwordx4 v[208:209], off
	v_lshl_add_u64 v[208:209], s[40:41], 0, v[200:201]
	s_add_i32 m0, s42, 0x2000
	s_nop 0
	global_load_lds_dwordx4 v[208:209], off
	v_lshl_add_u64 v[208:209], v[212:213], 0, s[12:13]
	s_mov_b32 m0, s69
	s_nop 0
	global_load_lds_dwordx4 v[208:209], off
	v_lshl_add_u64 v[208:209], v[214:215], 0, s[12:13]
	s_mov_b32 m0, s74
	s_nop 0
	global_load_lds_dwordx4 v[208:209], off
	s_waitcnt vmcnt(8)
	s_waitcnt lgkmcnt(0)
	s_setprio 0
	s_barrier
	v_mfma_f32_16x16x32_bf16 v[60:63], v[104:107], v[160:163], v[60:63]
	v_mfma_f32_16x16x32_bf16 v[56:59], v[120:123], v[160:163], v[56:59]
	v_mfma_f32_16x16x32_bf16 v[44:47], v[104:107], v[168:171], v[44:47]
	v_mfma_f32_16x16x32_bf16 v[40:43], v[120:123], v[168:171], v[40:43]
	v_mfma_f32_16x16x32_bf16 v[28:31], v[104:107], v[176:179], v[28:31]
	v_mfma_f32_16x16x32_bf16 v[24:27], v[120:123], v[176:179], v[24:27]
	v_mfma_f32_16x16x32_bf16 v[12:15], v[104:107], v[184:187], v[12:15]
	v_mfma_f32_16x16x32_bf16 v[8:11], v[120:123], v[184:187], v[8:11]
	v_mfma_f32_16x16x32_bf16 v[60:63], v[108:111], v[164:167], v[60:63]
	v_mfma_f32_16x16x32_bf16 v[56:59], v[124:127], v[164:167], v[56:59]
	v_mfma_f32_16x16x32_bf16 v[44:47], v[108:111], v[172:175], v[44:47]
	v_mfma_f32_16x16x32_bf16 v[40:43], v[124:127], v[172:175], v[40:43]
	v_mfma_f32_16x16x32_bf16 v[28:31], v[108:111], v[180:183], v[28:31]
	v_mfma_f32_16x16x32_bf16 v[24:27], v[124:127], v[180:183], v[24:27]
	v_mfma_f32_16x16x32_bf16 v[12:15], v[108:111], v[188:191], v[12:15]
	v_mfma_f32_16x16x32_bf16 v[8:11], v[124:127], v[188:191], v[8:11]
	v_mfma_f32_16x16x32_bf16 v[52:55], v[136:139], v[160:163], v[52:55]
	v_mfma_f32_16x16x32_bf16 v[48:51], v[152:155], v[160:163], v[48:51]
	v_mfma_f32_16x16x32_bf16 v[36:39], v[136:139], v[168:171], v[36:39]
	v_mfma_f32_16x16x32_bf16 v[32:35], v[152:155], v[168:171], v[32:35]
	v_mfma_f32_16x16x32_bf16 v[20:23], v[136:139], v[176:179], v[20:23]
	v_mfma_f32_16x16x32_bf16 v[16:19], v[152:155], v[176:179], v[16:19]
	v_mfma_f32_16x16x32_bf16 v[4:7], v[136:139], v[184:187], v[4:7]
	v_mfma_f32_16x16x32_bf16 v[0:3], v[152:155], v[184:187], v[0:3]
	v_mfma_f32_16x16x32_bf16 v[52:55], v[140:143], v[164:167], v[52:55]
	v_mfma_f32_16x16x32_bf16 v[48:51], v[156:159], v[164:167], v[48:51]
	v_mfma_f32_16x16x32_bf16 v[36:39], v[140:143], v[172:175], v[36:39]
	v_mfma_f32_16x16x32_bf16 v[32:35], v[156:159], v[172:175], v[32:35]
	v_mfma_f32_16x16x32_bf16 v[20:23], v[140:143], v[180:183], v[20:23]
	v_mfma_f32_16x16x32_bf16 v[16:19], v[156:159], v[180:183], v[16:19]
	v_mfma_f32_16x16x32_bf16 v[4:7], v[140:143], v[188:191], v[4:7]
	v_mfma_f32_16x16x32_bf16 v[0:3], v[156:159], v[188:191], v[0:3]
	s_barrier
	s_setprio 1
	s_add_u32 s38, s38, 0x100
	s_addc_u32 s39, s39, 0
	s_add_u32 s48, s48, 0x100
	s_addc_u32 s49, s49, 0
	s_cmp_ge_u32 s50, s31
	s_mov_b32 s42, s50
	s_cbranch_scc1 .Lkpeel_632_exit
.LBB0_632:
	ds_read_b128 v[104:107], v224
	ds_read_b128 v[108:111], v224 offset:1024
	ds_read_b128 v[120:123], v224 offset:2048
	ds_read_b128 v[124:127], v224 offset:3072
	ds_read_b128 v[136:139], v225
	ds_read_b128 v[140:143], v225 offset:1024
	ds_read_b128 v[152:155], v225 offset:2048
	ds_read_b128 v[156:159], v225 offset:3072
	s_add_i32 s50, s42, 2
	s_add_u32 s40, s38, 0xfff80080
	s_addc_u32 s41, s39, -1
	s_cmp_eq_u32 s33, s42
	s_cselect_b32 s42, s5, s40
	s_cselect_b32 s43, s1, s41
	s_cselect_b32 s41, s21, s49
	s_cselect_b32 s40, s23, s48
	v_lshl_add_u64 v[208:209], s[38:39], 0, v[202:203]
	s_add_i32 m0, s53, 0xc000
	ds_read_b128 v[160:163], v226
	ds_read_b128 v[164:167], v226 offset:1024
	ds_read_b128 v[168:171], v226 offset:2048
	ds_read_b128 v[172:175], v226 offset:3072
	ds_read_b128 v[176:179], v226 offset:4096
	ds_read_b128 v[180:183], v226 offset:5120
	ds_read_b128 v[184:187], v226 offset:6144
	ds_read_b128 v[188:191], v226 offset:7168
	global_load_lds_dwordx4 v[208:209], off
	v_lshl_add_u64 v[208:209], s[38:39], 0, v[204:205]
	s_add_i32 m0, s53, 0xe000
	s_nop 0
	global_load_lds_dwordx4 v[208:209], off
	s_waitcnt vmcnt(8)
	s_waitcnt lgkmcnt(0)
	s_setprio 0
	s_barrier
; #define PG8_STAGE(bufoff, gbase, voff) do { _Pragma("unroll") for (int _i = 0; _i < 2; ++_i) \
;         __builtin_amdgcn_global_load_lds((const unsigned*)((const char*)(gbase) + (voff)[_i]), (LAS unsigned*)(lds + (bufoff) + ldsw + _i * 8192), 16, 0, 0); } while (0)
; #define PG8_LDA(dst, b, h) do { _Pragma("unroll") for (int m = 0; m < 4; ++m) _Pragma("unroll") for (int k = 0; k < 2; ++k) dst[m][k] = *(const LAS bf16x8*)(lds + PG8_SA(b, h) + aoff + m * 2048 + k * 1024); } while (0)
; #define PG8_MMA(ai, bj, At, Bt) do { __builtin_amdgcn_s_setprio(1); _Pragma("unroll") for (int m = 0; m < 4; ++m) _Pragma("unroll") for (int n = 0; n < 2; ++n) _Pragma("unroll") for (int k = 0; k < 2; ++k) \
;         acc[ai][bj][m][n] = __builtin_amdgcn_mfma_f32_16x16x32_bf16(Bt[n][k], At[m][k], acc[ai][bj][m][n], 0, 0, 0); __builtin_amdgcn_s_setprio(0); } while (0)
; #define PG8_WAIT_V(n) asm volatile("s_waitcnt vmcnt(" #n ")" ::: "memory")
; #define PG8_WAIT_L(n) asm volatile("s_waitcnt lgkmcnt(" #n ")" ::: "memory")
; #define PG8_BAR __builtin_amdgcn_s_barrier()
; #define PG8_SCHED __builtin_amdgcn_sched_barrier(0)
; template <class Epi, class Sched = StaticOrder, class EpiSub = NoSub, bool FAST = false>
; __device__ __forceinline__ void gemm_phase(LAS unsigned char* lds, const Gemm g, const Sched& S, const Epi& E, const EpiSub& ES = EpiSub()) {
;     ...
;             PG8_WAIT_V(8); PG8_WAIT_L(0); PG8_BAR; PG8_MMA(0, 0, At, B0); PG8_MMA(0, 1, At, B1); PG8_BAR; PG8_SCHED;
;             PG8_LDA(At, 0, 1); PG8_STAGE(PG8_SB(0, 0), b2, voffB); PG8_STAGE(PG8_SB(0, 1), b2 + hstepB, voffB); PG8_STAGE(PG8_SA(0, 0), a2, voffA);
;             PG8_WAIT_V(8); PG8_WAIT_L(0); PG8_BAR; PG8_MMA(1, 0, At, B0); PG8_MMA(1, 1, At, B1); PG8_BAR; PG8_SCHED;
	v_mfma_f32_16x16x32_bf16 v[148:151], v[104:107], v[160:163], v[148:151]
	v_mfma_f32_16x16x32_bf16 v[144:147], v[120:123], v[160:163], v[144:147]
	v_mfma_f32_16x16x32_bf16 v[116:119], v[104:107], v[168:171], v[116:119]
	v_mfma_f32_16x16x32_bf16 v[112:115], v[120:123], v[168:171], v[112:115]
	v_mfma_f32_16x16x32_bf16 v[92:95], v[104:107], v[176:179], v[92:95]
	v_mfma_f32_16x16x32_bf16 v[88:91], v[120:123], v[176:179], v[88:91]
	v_mfma_f32_16x16x32_bf16 v[76:79], v[104:107], v[184:187], v[76:79]
	v_mfma_f32_16x16x32_bf16 v[72:75], v[120:123], v[184:187], v[72:75]
	v_mfma_f32_16x16x32_bf16 v[148:151], v[108:111], v[164:167], v[148:151]
	v_mfma_f32_16x16x32_bf16 v[144:147], v[124:127], v[164:167], v[144:147]
	v_mfma_f32_16x16x32_bf16 v[116:119], v[108:111], v[172:175], v[116:119]
	v_mfma_f32_16x16x32_bf16 v[112:115], v[124:127], v[172:175], v[112:115]
	v_mfma_f32_16x16x32_bf16 v[92:95], v[108:111], v[180:183], v[92:95]
	v_mfma_f32_16x16x32_bf16 v[88:91], v[124:127], v[180:183], v[88:91]
	v_mfma_f32_16x16x32_bf16 v[76:79], v[108:111], v[188:191], v[76:79]
	v_mfma_f32_16x16x32_bf16 v[72:75], v[124:127], v[188:191], v[72:75]
	v_mfma_f32_16x16x32_bf16 v[132:135], v[136:139], v[160:163], v[132:135]
	v_mfma_f32_16x16x32_bf16 v[128:131], v[152:155], v[160:163], v[128:131]
	v_mfma_f32_16x16x32_bf16 v[100:103], v[136:139], v[168:171], v[100:103]
	v_mfma_f32_16x16x32_bf16 v[96:99], v[152:155], v[168:171], v[96:99]
	v_mfma_f32_16x16x32_bf16 v[84:87], v[136:139], v[176:179], v[84:87]
	v_mfma_f32_16x16x32_bf16 v[80:83], v[152:155], v[176:179], v[80:83]
	v_mfma_f32_16x16x32_bf16 v[68:71], v[136:139], v[184:187], v[68:71]
	v_mfma_f32_16x16x32_bf16 v[64:67], v[152:155], v[184:187], v[64:67]
	v_mfma_f32_16x16x32_bf16 v[132:135], v[140:143], v[164:167], v[132:135]
	v_mfma_f32_16x16x32_bf16 v[128:131], v[156:159], v[164:167], v[128:131]
	v_mfma_f32_16x16x32_bf16 v[100:103], v[140:143], v[172:175], v[100:103]
	v_mfma_f32_16x16x32_bf16 v[96:99], v[156:159], v[172:175], v[96:99]
	v_mfma_f32_16x16x32_bf16 v[84:87], v[140:143], v[180:183], v[84:87]
	v_mfma_f32_16x16x32_bf16 v[80:83], v[156:159], v[180:183], v[80:83]
	v_mfma_f32_16x16x32_bf16 v[68:71], v[140:143], v[188:191], v[68:71]
	v_mfma_f32_16x16x32_bf16 v[64:67], v[156:159], v[188:191], v[64:67]
	s_barrier
	s_setprio 1
	s_add_i32 s51, s75, s52
	v_lshl_add_u64 v[208:209], s[40:41], 0, v[196:197]
	s_mov_b32 m0, s51
	ds_read_b128 v[160:163], v226 offset:16384
	ds_read_b128 v[164:167], v226 offset:17408
	ds_read_b128 v[168:171], v226 offset:18432
	ds_read_b128 v[172:175], v226 offset:19456
	ds_read_b128 v[176:179], v226 offset:20480
	ds_read_b128 v[180:183], v226 offset:21504
	ds_read_b128 v[184:187], v226 offset:22528
	ds_read_b128 v[188:191], v226 offset:23552
	global_load_lds_dwordx4 v[208:209], off
	s_add_i32 m0, s51, 0x2000
	s_add_u32 s70, s40, 0x80000
	v_lshl_add_u64 v[210:211], s[40:41], 0, v[200:201]
	s_addc_u32 s71, s41, 0
	s_add_i32 s51, s78, s52
	global_load_lds_dwordx4 v[210:211], off
	v_lshl_add_u64 v[212:213], s[70:71], 0, v[196:197]
	s_mov_b32 m0, s51
	v_lshl_add_u64 v[214:215], s[42:43], 0, v[198:199]
	global_load_lds_dwordx4 v[212:213], off
	v_lshl_add_u64 v[212:213], s[70:71], 0, v[200:201]
	s_add_i32 m0, s51, 0x2000
	s_nop 0
	global_load_lds_dwordx4 v[212:213], off
	v_lshl_add_u64 v[212:213], s[42:43], 0, v[194:195]
	s_mov_b32 m0, s53
	s_nop 0
	global_load_lds_dwordx4 v[212:213], off
	s_mov_b32 m0, s54
	s_nop 0
	global_load_lds_dwordx4 v[214:215], off
	s_waitcnt vmcnt(8)
	s_waitcnt lgkmcnt(0)
	s_setprio 0
	s_barrier
	v_mfma_f32_16x16x32_bf16 v[60:63], v[104:107], v[160:163], v[60:63]
	v_mfma_f32_16x16x32_bf16 v[56:59], v[120:123], v[160:163], v[56:59]
	v_mfma_f32_16x16x32_bf16 v[44:47], v[104:107], v[168:171], v[44:47]
	v_mfma_f32_16x16x32_bf16 v[40:43], v[120:123], v[168:171], v[40:43]
	v_mfma_f32_16x16x32_bf16 v[28:31], v[104:107], v[176:179], v[28:31]
	v_mfma_f32_16x16x32_bf16 v[24:27], v[120:123], v[176:179], v[24:27]
	v_mfma_f32_16x16x32_bf16 v[12:15], v[104:107], v[184:187], v[12:15]
	v_mfma_f32_16x16x32_bf16 v[8:11], v[120:123], v[184:187], v[8:11]
	v_mfma_f32_16x16x32_bf16 v[60:63], v[108:111], v[164:167], v[60:63]
	v_mfma_f32_16x16x32_bf16 v[56:59], v[124:127], v[164:167], v[56:59]
	v_mfma_f32_16x16x32_bf16 v[44:47], v[108:111], v[172:175], v[44:47]
	v_mfma_f32_16x16x32_bf16 v[40:43], v[124:127], v[172:175], v[40:43]
	v_mfma_f32_16x16x32_bf16 v[28:31], v[108:111], v[180:183], v[28:31]
	v_mfma_f32_16x16x32_bf16 v[24:27], v[124:127], v[180:183], v[24:27]
	v_mfma_f32_16x16x32_bf16 v[12:15], v[108:111], v[188:191], v[12:15]
	v_mfma_f32_16x16x32_bf16 v[8:11], v[124:127], v[188:191], v[8:11]
	v_mfma_f32_16x16x32_bf16 v[52:55], v[136:139], v[160:163], v[52:55]
	v_mfma_f32_16x16x32_bf16 v[48:51], v[152:155], v[160:163], v[48:51]
	v_mfma_f32_16x16x32_bf16 v[36:39], v[136:139], v[168:171], v[36:39]
	v_mfma_f32_16x16x32_bf16 v[32:35], v[152:155], v[168:171], v[32:35]
	v_mfma_f32_16x16x32_bf16 v[20:23], v[136:139], v[176:179], v[20:23]
	v_mfma_f32_16x16x32_bf16 v[16:19], v[152:155], v[176:179], v[16:19]
	v_mfma_f32_16x16x32_bf16 v[4:7], v[136:139], v[184:187], v[4:7]
	v_mfma_f32_16x16x32_bf16 v[0:3], v[152:155], v[184:187], v[0:3]
	v_mfma_f32_16x16x32_bf16 v[52:55], v[140:143], v[164:167], v[52:55]
	v_mfma_f32_16x16x32_bf16 v[48:51], v[156:159], v[164:167], v[48:51]
	v_mfma_f32_16x16x32_bf16 v[36:39], v[140:143], v[172:175], v[36:39]
	v_mfma_f32_16x16x32_bf16 v[32:35], v[156:159], v[172:175], v[32:35]
	v_mfma_f32_16x16x32_bf16 v[20:23], v[140:143], v[180:183], v[20:23]
	v_mfma_f32_16x16x32_bf16 v[16:19], v[156:159], v[180:183], v[16:19]
	v_mfma_f32_16x16x32_bf16 v[4:7], v[140:143], v[188:191], v[4:7]
	v_mfma_f32_16x16x32_bf16 v[0:3], v[156:159], v[188:191], v[0:3]
	s_barrier
; #define PG8_STAGE(bufoff, gbase, voff) do { _Pragma("unroll") for (int _i = 0; _i < 2; ++_i) \
;         __builtin_amdgcn_global_load_lds((const unsigned*)((const char*)(gbase) + (voff)[_i]), (LAS unsigned*)(lds + (bufoff) + ldsw + _i * 8192), 16, 0, 0); } while (0)
; #define PG8_LDA(dst, b, h) do { _Pragma("unroll") for (int m = 0; m < 4; ++m) _Pragma("unroll") for (int k = 0; k < 2; ++k) dst[m][k] = *(const LAS bf16x8*)(lds + PG8_SA(b, h) + aoff + m * 2048 + k * 1024); } while (0)
; #define PG8_LDB(dst, b, h) do { _Pragma("unroll") for (int n = 0; n < 2; ++n) _Pragma("unroll") for (int k = 0; k < 2; ++k) dst[n][k] = *(const LAS bf16x8*)(lds + PG8_SB(b, h) + boff + n * 2048 + k * 1024); } while (0)
; #define PG8_MMA(ai, bj, At, Bt) do { __builtin_amdgcn_s_setprio(1); _Pragma("unroll") for (int m = 0; m < 4; ++m) _Pragma("unroll") for (int n = 0; n < 2; ++n) _Pragma("unroll") for (int k = 0; k < 2; ++k) \
;         acc[ai][bj][m][n] = __builtin_amdgcn_mfma_f32_16x16x32_bf16(Bt[n][k], At[m][k], acc[ai][bj][m][n], 0, 0, 0); __builtin_amdgcn_s_setprio(0); } while (0)
; #define PG8_WAIT_V(n) asm volatile("s_waitcnt vmcnt(" #n ")" ::: "memory")
; #define PG8_WAIT_L(n) asm volatile("s_waitcnt lgkmcnt(" #n ")" ::: "memory")
; #define PG8_BAR __builtin_amdgcn_s_barrier()
; #define PG8_SCHED __builtin_amdgcn_sched_barrier(0)
; template <class Epi, class Sched = StaticOrder, class EpiSub = NoSub, bool FAST = false>
; __device__ __forceinline__ void gemm_phase(LAS unsigned char* lds, const Gemm g, const Sched& S, const Epi& E, const EpiSub& ES = EpiSub()) {
;     ...
;             PG8_LDB(B0, 1, 0); PG8_LDB(B1, 1, 1); PG8_SCHED; PG8_LDA(At, 1, 0); PG8_STAGE(PG8_SA(0, 1), a2 + hstepA, voffA);
;             PG8_WAIT_V(8); PG8_WAIT_L(0); PG8_BAR; PG8_MMA(0, 0, At, B0); PG8_MMA(0, 1, At, B1); PG8_BAR; PG8_SCHED;
	s_setprio 1
	s_add_i32 s51, 0, 0x18000
	s_add_i32 s70, 0, 0x1c000
	v_add_u32_e32 v124, s51, v221
	v_add_u32_e32 v156, s70, v221
	ds_read_b128 v[104:107], v124
	ds_read_b128 v[108:111], v124 offset:1024
	ds_read_b128 v[120:123], v124 offset:2048
	ds_read_b128 v[124:127], v124 offset:3072
	ds_read_b128 v[136:139], v156
	ds_read_b128 v[140:143], v156 offset:1024
	ds_read_b128 v[152:155], v156 offset:2048
	ds_read_b128 v[156:159], v156 offset:3072
	s_add_u32 s42, s42, 0x80000
	s_addc_u32 s43, s43, 0
	s_mov_b32 m0, s55
	v_lshl_add_u64 v[216:217], s[42:43], 0, v[194:195]
	ds_read_b128 v[160:163], v226 offset:32768
	ds_read_b128 v[164:167], v226 offset:33792
	ds_read_b128 v[168:171], v226 offset:34816
	ds_read_b128 v[172:175], v226 offset:35840
	ds_read_b128 v[176:179], v226 offset:36864
	ds_read_b128 v[180:183], v226 offset:37888
	ds_read_b128 v[184:187], v226 offset:38912
	ds_read_b128 v[188:191], v226 offset:39936
	global_load_lds_dwordx4 v[216:217], off
	v_lshl_add_u64 v[216:217], s[42:43], 0, v[198:199]
	s_mov_b32 m0, s56
	s_nop 0
	global_load_lds_dwordx4 v[216:217], off
	s_waitcnt vmcnt(8)
	s_waitcnt lgkmcnt(0)
	s_setprio 0
	s_barrier
	v_mfma_f32_16x16x32_bf16 v[148:151], v[104:107], v[160:163], v[148:151]
	v_mfma_f32_16x16x32_bf16 v[144:147], v[120:123], v[160:163], v[144:147]
	v_mfma_f32_16x16x32_bf16 v[116:119], v[104:107], v[168:171], v[116:119]
	v_mfma_f32_16x16x32_bf16 v[112:115], v[120:123], v[168:171], v[112:115]
	v_mfma_f32_16x16x32_bf16 v[92:95], v[104:107], v[176:179], v[92:95]
	v_mfma_f32_16x16x32_bf16 v[88:91], v[120:123], v[176:179], v[88:91]
	v_mfma_f32_16x16x32_bf16 v[76:79], v[104:107], v[184:187], v[76:79]
	v_mfma_f32_16x16x32_bf16 v[72:75], v[120:123], v[184:187], v[72:75]
	v_mfma_f32_16x16x32_bf16 v[148:151], v[108:111], v[164:167], v[148:151]
	v_mfma_f32_16x16x32_bf16 v[144:147], v[124:127], v[164:167], v[144:147]
	v_mfma_f32_16x16x32_bf16 v[116:119], v[108:111], v[172:175], v[116:119]
	v_mfma_f32_16x16x32_bf16 v[112:115], v[124:127], v[172:175], v[112:115]
	v_mfma_f32_16x16x32_bf16 v[92:95], v[108:111], v[180:183], v[92:95]
	v_mfma_f32_16x16x32_bf16 v[88:91], v[124:127], v[180:183], v[88:91]
	v_mfma_f32_16x16x32_bf16 v[76:79], v[108:111], v[188:191], v[76:79]
	v_mfma_f32_16x16x32_bf16 v[72:75], v[124:127], v[188:191], v[72:75]
	v_mfma_f32_16x16x32_bf16 v[132:135], v[136:139], v[160:163], v[132:135]
	v_mfma_f32_16x16x32_bf16 v[128:131], v[152:155], v[160:163], v[128:131]
	v_mfma_f32_16x16x32_bf16 v[100:103], v[136:139], v[168:171], v[100:103]
	v_mfma_f32_16x16x32_bf16 v[96:99], v[152:155], v[168:171], v[96:99]
	v_mfma_f32_16x16x32_bf16 v[84:87], v[136:139], v[176:179], v[84:87]
	v_mfma_f32_16x16x32_bf16 v[80:83], v[152:155], v[176:179], v[80:83]
	v_mfma_f32_16x16x32_bf16 v[68:71], v[136:139], v[184:187], v[68:71]
	v_mfma_f32_16x16x32_bf16 v[64:67], v[152:155], v[184:187], v[64:67]
	v_mfma_f32_16x16x32_bf16 v[132:135], v[140:143], v[164:167], v[132:135]
	v_mfma_f32_16x16x32_bf16 v[128:131], v[156:159], v[164:167], v[128:131]
	v_mfma_f32_16x16x32_bf16 v[100:103], v[140:143], v[172:175], v[100:103]
	v_mfma_f32_16x16x32_bf16 v[96:99], v[156:159], v[172:175], v[96:99]
	v_mfma_f32_16x16x32_bf16 v[84:87], v[140:143], v[180:183], v[84:87]
	v_mfma_f32_16x16x32_bf16 v[80:83], v[156:159], v[180:183], v[80:83]
	v_mfma_f32_16x16x32_bf16 v[68:71], v[140:143], v[188:191], v[68:71]
	v_mfma_f32_16x16x32_bf16 v[64:67], v[156:159], v[188:191], v[64:67]
	s_barrier
; #define PG8_STAGE(bufoff, gbase, voff) do { _Pragma("unroll") for (int _i = 0; _i < 2; ++_i) \
;         __builtin_amdgcn_global_load_lds((const unsigned*)((const char*)(gbase) + (voff)[_i]), (LAS unsigned*)(lds + (bufoff) + ldsw + _i * 8192), 16, 0, 0); } while (0)
; #define PG8_LDA(dst, b, h) do { _Pragma("unroll") for (int m = 0; m < 4; ++m) _Pragma("unroll") for (int k = 0; k < 2; ++k) dst[m][k] = *(const LAS bf16x8*)(lds + PG8_SA(b, h) + aoff + m * 2048 + k * 1024); } while (0)
; #define PG8_MMA(ai, bj, At, Bt) do { __builtin_amdgcn_s_setprio(1); _Pragma("unroll") for (int m = 0; m < 4; ++m) _Pragma("unroll") for (int n = 0; n < 2; ++n) _Pragma("unroll") for (int k = 0; k < 2; ++k) \
;         acc[ai][bj][m][n] = __builtin_amdgcn_mfma_f32_16x16x32_bf16(Bt[n][k], At[m][k], acc[ai][bj][m][n], 0, 0, 0); __builtin_amdgcn_s_setprio(0); } while (0)
; #define PG8_WAIT_V(n) asm volatile("s_waitcnt vmcnt(" #n ")" ::: "memory")
; #define PG8_WAIT_L(n) asm volatile("s_waitcnt lgkmcnt(" #n ")" ::: "memory")
; #define PG8_BAR __builtin_amdgcn_s_barrier()
; #define PG8_SCHED __builtin_amdgcn_sched_barrier(0)
; template <class Epi, class Sched = StaticOrder, class EpiSub = NoSub, bool FAST = false>
; __device__ __forceinline__ void gemm_phase(LAS unsigned char* lds, const Gemm g, const Sched& S, const Epi& E, const EpiSub& ES = EpiSub()) {
;     ...
;             PG8_LDA(At, 1, 1); PG8_STAGE(PG8_SB(1, 0), b3, voffB); PG8_STAGE(PG8_SB(1, 1), b3 + hstepB, voffB); PG8_STAGE(PG8_SA(1, 0), a3, voffA);
;             PG8_WAIT_V(8); PG8_WAIT_L(0); PG8_BAR; PG8_MMA(1, 0, At, B0); PG8_MMA(1, 1, At, B1); PG8_BAR; PG8_SCHED;
	s_setprio 1
	s_add_i32 s42, s51, s52
	v_lshl_add_u64 v[208:209], v[208:209], 0, s[12:13]
	s_mov_b32 m0, s42
	ds_read_b128 v[160:163], v226 offset:49152
	ds_read_b128 v[164:167], v226 offset:50176
	ds_read_b128 v[168:171], v226 offset:51200
	ds_read_b128 v[172:175], v226 offset:52224
	ds_read_b128 v[176:179], v226 offset:53248
	ds_read_b128 v[180:183], v226 offset:54272
	ds_read_b128 v[184:187], v226 offset:55296
	ds_read_b128 v[188:191], v226 offset:56320
	global_load_lds_dwordx4 v[208:209], off
	s_add_i32 m0, s42, 0x2000
	s_add_u32 s40, s40, 0x80080
	v_lshl_add_u64 v[208:209], v[210:211], 0, s[12:13]
	s_addc_u32 s41, s41, 0
	s_add_i32 s42, s70, s52
	global_load_lds_dwordx4 v[208:209], off
	v_lshl_add_u64 v[208:209], s[40:41], 0, v[196:197]
	s_mov_b32 m0, s42
	s_nop 0
	global_load_lds_dwordx4 v[208:209], off
	v_lshl_add_u64 v[208:209], s[40:41], 0, v[200:201]
	s_add_i32 m0, s42, 0x2000
	s_nop 0
	global_load_lds_dwordx4 v[208:209], off
	v_lshl_add_u64 v[208:209], v[212:213], 0, s[12:13]
	s_mov_b32 m0, s69
	s_nop 0
	global_load_lds_dwordx4 v[208:209], off
	v_lshl_add_u64 v[208:209], v[214:215], 0, s[12:13]
	s_mov_b32 m0, s74
	s_nop 0
	global_load_lds_dwordx4 v[208:209], off
	s_waitcnt vmcnt(8)
	s_waitcnt lgkmcnt(0)
	s_setprio 0
	s_barrier
	v_mfma_f32_16x16x32_bf16 v[60:63], v[104:107], v[160:163], v[60:63]
	v_mfma_f32_16x16x32_bf16 v[56:59], v[120:123], v[160:163], v[56:59]
	v_mfma_f32_16x16x32_bf16 v[44:47], v[104:107], v[168:171], v[44:47]
	v_mfma_f32_16x16x32_bf16 v[40:43], v[120:123], v[168:171], v[40:43]
	v_mfma_f32_16x16x32_bf16 v[28:31], v[104:107], v[176:179], v[28:31]
	v_mfma_f32_16x16x32_bf16 v[24:27], v[120:123], v[176:179], v[24:27]
	v_mfma_f32_16x16x32_bf16 v[12:15], v[104:107], v[184:187], v[12:15]
	v_mfma_f32_16x16x32_bf16 v[8:11], v[120:123], v[184:187], v[8:11]
	v_mfma_f32_16x16x32_bf16 v[60:63], v[108:111], v[164:167], v[60:63]
	v_mfma_f32_16x16x32_bf16 v[56:59], v[124:127], v[164:167], v[56:59]
	v_mfma_f32_16x16x32_bf16 v[44:47], v[108:111], v[172:175], v[44:47]
	v_mfma_f32_16x16x32_bf16 v[40:43], v[124:127], v[172:175], v[40:43]
	v_mfma_f32_16x16x32_bf16 v[28:31], v[108:111], v[180:183], v[28:31]
	v_mfma_f32_16x16x32_bf16 v[24:27], v[124:127], v[180:183], v[24:27]
	v_mfma_f32_16x16x32_bf16 v[12:15], v[108:111], v[188:191], v[12:15]
	v_mfma_f32_16x16x32_bf16 v[8:11], v[124:127], v[188:191], v[8:11]
	v_mfma_f32_16x16x32_bf16 v[52:55], v[136:139], v[160:163], v[52:55]
	v_mfma_f32_16x16x32_bf16 v[48:51], v[152:155], v[160:163], v[48:51]
	v_mfma_f32_16x16x32_bf16 v[36:39], v[136:139], v[168:171], v[36:39]
	v_mfma_f32_16x16x32_bf16 v[32:35], v[152:155], v[168:171], v[32:35]
	v_mfma_f32_16x16x32_bf16 v[20:23], v[136:139], v[176:179], v[20:23]
	v_mfma_f32_16x16x32_bf16 v[16:19], v[152:155], v[176:179], v[16:19]
	v_mfma_f32_16x16x32_bf16 v[4:7], v[136:139], v[184:187], v[4:7]
	v_mfma_f32_16x16x32_bf16 v[0:3], v[152:155], v[184:187], v[0:3]
	v_mfma_f32_16x16x32_bf16 v[52:55], v[140:143], v[164:167], v[52:55]
	v_mfma_f32_16x16x32_bf16 v[48:51], v[156:159], v[164:167], v[48:51]
	v_mfma_f32_16x16x32_bf16 v[36:39], v[140:143], v[172:175], v[36:39]
	v_mfma_f32_16x16x32_bf16 v[32:35], v[156:159], v[172:175], v[32:35]
	v_mfma_f32_16x16x32_bf16 v[20:23], v[140:143], v[180:183], v[20:23]
	v_mfma_f32_16x16x32_bf16 v[16:19], v[156:159], v[180:183], v[16:19]
	v_mfma_f32_16x16x32_bf16 v[4:7], v[140:143], v[188:191], v[4:7]
	v_mfma_f32_16x16x32_bf16 v[0:3], v[156:159], v[188:191], v[0:3]
	s_barrier
	s_setprio 1
	s_add_u32 s38, s38, 0x100
	s_addc_u32 s39, s39, 0
	s_add_u32 s48, s48, 0x100
	s_addc_u32 s49, s49, 0
	s_cmp_ge_u32 s50, s31
	s_mov_b32 s42, s50
	s_cbranch_scc0 .LBB0_632

; #define PG8_STAGE(bufoff, gbase, voff) do { _Pragma("unroll") for (int _i = 0; _i < 2; ++_i) \
;         __builtin_amdgcn_global_load_lds((const unsigned*)((const char*)(gbase) + (voff)[_i]), (LAS unsigned*)(lds + (bufoff) + ldsw + _i * 8192), 16, 0, 0); } while (0)
; #define PG8_LDA(dst, b, h) do { _Pragma("unroll") for (int m = 0; m < 4; ++m) _Pragma("unroll") for (int k = 0; k < 2; ++k) dst[m][k] = *(const LAS bf16x8*)(lds + PG8_SA(b, h) + aoff + m * 2048 + k * 1024); } while (0)
; #define PG8_LDB(dst, b, h) do { _Pragma("unroll") for (int n = 0; n < 2; ++n) _Pragma("unroll") for (int k = 0; k < 2; ++k) dst[n][k] = *(const LAS bf16x8*)(lds + PG8_SB(b, h) + boff + n * 2048 + k * 1024); } while (0)
; #define PG8_WAIT_V(n) asm volatile("s_waitcnt vmcnt(" #n ")" ::: "memory")
; #define PG8_WAIT_L(n) asm volatile("s_waitcnt lgkmcnt(" #n ")" ::: "memory")
; #define PG8_BAR __builtin_amdgcn_s_barrier()
; #define PG8_SCHED __builtin_amdgcn_sched_barrier(0)
; template <class Epi, class Sched = StaticOrder, class EpiSub = NoSub, bool FAST = false>
; __device__ __forceinline__ void gemm_phase(LAS unsigned char* lds, const Gemm g, const Sched& S, const Epi& E, const EpiSub& ES = EpiSub()) {
;     ...
;         const bool has_next = S.next(ui + 1, nxt);
;         const size_t nko = (has_next && nxt.kb >= 0) ? nxt.kb * ksubB : 0;
;         const char* nA = has_next ? (const char*)g.A + (size_t)nxt.pm * tstepA + (size_t)nxt.pn * g.acs + nko : cA; const char* nB = has_next ? (const char*)g.Bt + (size_t)nxt.pn * tstepB + nko : cB;
;         const int nt = cur.kb < 0 ? ntMain : ntSub;
;         for (int t = 0; t < nt; t += 2) {
;             const bool last = (t == nt - 2);
;             const char* a1 = cA + (size_t)(t + 1) * kstep;
;             const char* a2 = last ? nA : cA + (size_t)(t + 2) * kstep; const char* b2 = last ? nB : cB + (size_t)(t + 2) * kstep;
;             const char* a3 = a2 + kstep; const char* b3 = b2 + kstep;
;             if constexpr (FAST && PG8_SP2) {
;             PG8_LDB(B0, 0, 0); PG8_LDB(B1, 0, 1); PG8_SCHED; PG8_LDA(At, 0, 0); PG8_STAGE(PG8_SA(1, 1), a1 + hstepA, voffA);
;             PG8_WAIT_V(8); PG8_WAIT_L(0); PG8_BAR; PG8_MMA(0, 0, At, B0); PG8_MMA(0, 1, At, B1); PG8_BAR; PG8_SCHED;
;             PG8_LDA(At, 0, 1); PG8_STAGE(PG8_SB(0, 0), b2, voffB); PG8_STAGE(PG8_SB(0, 1), b2 + hstepB, voffB); PG8_STAGE(PG8_SA(0, 0), a2, voffA);
.LBB0_768:
	s_cmp_gt_i32 s6, -1
	s_cselect_b64 s[24:25], -1, 0
	s_and_b64 s[24:25], s[22:23], s[24:25]
	s_lshl_b64 s[26:27], s[6:7], 9
	s_and_b64 s[24:25], s[24:25], exec
	s_cselect_b32 s29, s27, 0
	s_cselect_b32 s30, s26, 0
	s_ashr_i32 s21, s20, 31
	s_lshl_b64 s[24:25], s[20:21], 20
	s_add_u32 s1, s84, s24
	s_addc_u32 s5, s85, s25
	s_add_u32 s24, s1, s30
	s_addc_u32 s25, s5, s29
	s_and_b64 s[26:27], s[22:23], exec
	s_cselect_b32 s1, s25, s39
	s_cselect_b32 s5, s24, s38
	s_ashr_i32 s19, s18, 31
	s_lshl_b64 s[26:27], s[18:19], 20
	s_add_u32 s19, s2, s26
	s_addc_u32 s21, s3, s27
	s_add_u32 s26, s19, s30
	s_addc_u32 s27, s21, s29
	s_and_b64 s[30:31], s[22:23], exec
	s_cselect_b32 s19, s27, s41
	s_cselect_b32 s21, s26, s40
	s_cmp_gt_i32 s4, -1
	s_cselect_b64 s[30:31], -1, 0
	s_cmp_lt_i32 s4, 0
	s_cselect_b32 s29, 32, 4
	s_add_i32 s33, s29, -2
	s_add_u32 s38, s38, 0x80080
	s_addc_u32 s39, s39, 0
	s_add_u32 s70, s40, 0x100
	s_mov_b32 s42, 0
	s_addc_u32 s71, s41, 0
	ds_read_b128 v[96:99], v215
	ds_read_b128 v[100:103], v215 offset:1024
	ds_read_b128 v[112:115], v215 offset:2048
	ds_read_b128 v[116:119], v215 offset:3072
	ds_read_b128 v[144:147], v216
	ds_read_b128 v[148:151], v216 offset:1024
	ds_read_b128 v[152:155], v216 offset:2048
	ds_read_b128 v[156:159], v216 offset:3072
	s_add_i32 s72, s42, 2
	s_add_u32 s40, s38, 0xfff80080
	s_addc_u32 s41, s39, -1
	s_cmp_eq_u32 s33, s42
	s_cselect_b32 s42, s5, s40
	s_cselect_b32 s43, s1, s41
	s_cselect_b32 s41, s19, s71
	s_cselect_b32 s40, s21, s70
	v_lshl_add_u64 v[208:209], s[38:39], 0, v[194:195]
	s_add_i32 m0, s48, 0xc000
	ds_read_b128 v[160:163], v217
	ds_read_b128 v[164:167], v217 offset:1024
	ds_read_b128 v[168:171], v217 offset:2048
	ds_read_b128 v[172:175], v217 offset:3072
	ds_read_b128 v[176:179], v217 offset:4096
	ds_read_b128 v[180:183], v217 offset:5120
	ds_read_b128 v[200:203], v217 offset:6144
	ds_read_b128 v[204:207], v217 offset:7168
	global_load_lds_dwordx4 v[208:209], off
	v_lshl_add_u64 v[208:209], s[38:39], 0, v[196:197]
	s_add_i32 m0, s48, 0xe000
	s_nop 0
	global_load_lds_dwordx4 v[208:209], off
	s_waitcnt vmcnt(8)
	s_waitcnt lgkmcnt(0)
	s_setprio 0
	s_barrier
	v_mfma_f32_16x16x32_bf16 v[140:143], v[96:99], v[160:163], 0
	v_mfma_f32_16x16x32_bf16 v[136:139], v[112:115], v[160:163], 0
	v_mfma_f32_16x16x32_bf16 v[124:127], v[96:99], v[168:171], 0
	v_mfma_f32_16x16x32_bf16 v[120:123], v[112:115], v[168:171], 0
	v_mfma_f32_16x16x32_bf16 v[92:95], v[96:99], v[176:179], 0
	v_mfma_f32_16x16x32_bf16 v[88:91], v[112:115], v[176:179], 0
	v_mfma_f32_16x16x32_bf16 v[76:79], v[96:99], v[200:203], 0
	v_mfma_f32_16x16x32_bf16 v[72:75], v[112:115], v[200:203], 0
	v_mfma_f32_16x16x32_bf16 v[140:143], v[100:103], v[164:167], v[140:143]
	v_mfma_f32_16x16x32_bf16 v[136:139], v[116:119], v[164:167], v[136:139]
	v_mfma_f32_16x16x32_bf16 v[124:127], v[100:103], v[172:175], v[124:127]
	v_mfma_f32_16x16x32_bf16 v[120:123], v[116:119], v[172:175], v[120:123]
	v_mfma_f32_16x16x32_bf16 v[92:95], v[100:103], v[180:183], v[92:95]
	v_mfma_f32_16x16x32_bf16 v[88:91], v[116:119], v[180:183], v[88:91]
	v_mfma_f32_16x16x32_bf16 v[76:79], v[100:103], v[204:207], v[76:79]
	v_mfma_f32_16x16x32_bf16 v[72:75], v[116:119], v[204:207], v[72:75]
	v_mfma_f32_16x16x32_bf16 v[132:135], v[144:147], v[160:163], 0
	v_mfma_f32_16x16x32_bf16 v[128:131], v[152:155], v[160:163], 0
	v_mfma_f32_16x16x32_bf16 v[108:111], v[144:147], v[168:171], 0
	v_mfma_f32_16x16x32_bf16 v[104:107], v[152:155], v[168:171], 0
	v_mfma_f32_16x16x32_bf16 v[84:87], v[144:147], v[176:179], 0
	v_mfma_f32_16x16x32_bf16 v[80:83], v[152:155], v[176:179], 0
	v_mfma_f32_16x16x32_bf16 v[68:71], v[144:147], v[200:203], 0
	v_mfma_f32_16x16x32_bf16 v[64:67], v[152:155], v[200:203], 0
	v_mfma_f32_16x16x32_bf16 v[132:135], v[148:151], v[164:167], v[132:135]
	v_mfma_f32_16x16x32_bf16 v[128:131], v[156:159], v[164:167], v[128:131]
	v_mfma_f32_16x16x32_bf16 v[108:111], v[148:151], v[172:175], v[108:111]
	v_mfma_f32_16x16x32_bf16 v[104:107], v[156:159], v[172:175], v[104:107]
	v_mfma_f32_16x16x32_bf16 v[84:87], v[148:151], v[180:183], v[84:87]
	v_mfma_f32_16x16x32_bf16 v[80:83], v[156:159], v[180:183], v[80:83]
	v_mfma_f32_16x16x32_bf16 v[68:71], v[148:151], v[204:207], v[68:71]
	v_mfma_f32_16x16x32_bf16 v[64:67], v[156:159], v[204:207], v[64:67]
	s_barrier
	s_setprio 1
	s_add_i32 s73, s58, s17
	v_lshl_add_u64 v[208:209], s[40:41], 0, v[186:187]
	s_mov_b32 m0, s73
	ds_read_b128 v[160:163], v217 offset:16384
	ds_read_b128 v[164:167], v217 offset:17408
	ds_read_b128 v[168:171], v217 offset:18432
	ds_read_b128 v[172:175], v217 offset:19456
	ds_read_b128 v[176:179], v217 offset:20480
	ds_read_b128 v[180:183], v217 offset:21504
	ds_read_b128 v[200:203], v217 offset:22528
	ds_read_b128 v[204:207], v217 offset:23552
	global_load_lds_dwordx4 v[208:209], off
	s_add_i32 m0, s73, 0x2000
	s_add_u32 s76, s40, 0x80000
	v_lshl_add_u64 v[210:211], s[40:41], 0, v[190:191]
	s_addc_u32 s77, s41, 0
	s_add_i32 s73, s59, s17
	global_load_lds_dwordx4 v[210:211], off
	v_lshl_add_u64 v[218:219], s[76:77], 0, v[186:187]
	s_mov_b32 m0, s73
	v_lshl_add_u64 v[220:221], s[42:43], 0, v[188:189]
	global_load_lds_dwordx4 v[218:219], off
	v_lshl_add_u64 v[218:219], s[76:77], 0, v[190:191]
	s_add_i32 m0, s73, 0x2000
	s_nop 0
	global_load_lds_dwordx4 v[218:219], off
	v_lshl_add_u64 v[218:219], s[42:43], 0, v[184:185]
	s_mov_b32 m0, s48
	s_nop 0
	global_load_lds_dwordx4 v[218:219], off
	s_mov_b32 m0, s49
	s_nop 0
	global_load_lds_dwordx4 v[220:221], off
	s_waitcnt vmcnt(8)
	s_waitcnt lgkmcnt(0)
	s_setprio 0
	s_barrier
; #define PG8_STAGE(bufoff, gbase, voff) do { _Pragma("unroll") for (int _i = 0; _i < 2; ++_i) \
;         __builtin_amdgcn_global_load_lds((const unsigned*)((const char*)(gbase) + (voff)[_i]), (LAS unsigned*)(lds + (bufoff) + ldsw + _i * 8192), 16, 0, 0); } while (0)
; #define PG8_LDA(dst, b, h) do { _Pragma("unroll") for (int m = 0; m < 4; ++m) _Pragma("unroll") for (int k = 0; k < 2; ++k) dst[m][k] = *(const LAS bf16x8*)(lds + PG8_SA(b, h) + aoff + m * 2048 + k * 1024); } while (0)
; #define PG8_LDB(dst, b, h) do { _Pragma("unroll") for (int n = 0; n < 2; ++n) _Pragma("unroll") for (int k = 0; k < 2; ++k) dst[n][k] = *(const LAS bf16x8*)(lds + PG8_SB(b, h) + boff + n * 2048 + k * 1024); } while (0)
; #define PG8_MMA(ai, bj, At, Bt) do { __builtin_amdgcn_s_setprio(1); _Pragma("unroll") for (int m = 0; m < 4; ++m) _Pragma("unroll") for (int n = 0; n < 2; ++n) _Pragma("unroll") for (int k = 0; k < 2; ++k) \
;         acc[ai][bj][m][n] = __builtin_amdgcn_mfma_f32_16x16x32_bf16(Bt[n][k], At[m][k], acc[ai][bj][m][n], 0, 0, 0); __builtin_amdgcn_s_setprio(0); } while (0)
; #define PG8_WAIT_V(n) asm volatile("s_waitcnt vmcnt(" #n ")" ::: "memory")
; #define PG8_WAIT_L(n) asm volatile("s_waitcnt lgkmcnt(" #n ")" ::: "memory")
; #define PG8_BAR __builtin_amdgcn_s_barrier()
; #define PG8_SCHED __builtin_amdgcn_sched_barrier(0)
; template <class Epi, class Sched = StaticOrder, class EpiSub = NoSub, bool FAST = false>
; __device__ __forceinline__ void gemm_phase(LAS unsigned char* lds, const Gemm g, const Sched& S, const Epi& E, const EpiSub& ES = EpiSub()) {
;     ...
;             PG8_WAIT_V(8); PG8_WAIT_L(0); PG8_BAR; PG8_MMA(1, 0, At, B0); PG8_MMA(1, 1, At, B1); PG8_BAR; PG8_SCHED;
;             PG8_LDB(B0, 1, 0); PG8_LDB(B1, 1, 1); PG8_SCHED; PG8_LDA(At, 1, 0); PG8_STAGE(PG8_SA(0, 1), a2 + hstepA, voffA);
;             PG8_WAIT_V(8); PG8_WAIT_L(0); PG8_BAR; PG8_MMA(0, 0, At, B0); PG8_MMA(0, 1, At, B1); PG8_BAR; PG8_SCHED;
	v_mfma_f32_16x16x32_bf16 v[60:63], v[96:99], v[160:163], 0
	v_mfma_f32_16x16x32_bf16 v[56:59], v[112:115], v[160:163], 0
	v_mfma_f32_16x16x32_bf16 v[44:47], v[96:99], v[168:171], 0
	v_mfma_f32_16x16x32_bf16 v[40:43], v[112:115], v[168:171], 0
	v_mfma_f32_16x16x32_bf16 v[28:31], v[96:99], v[176:179], 0
	v_mfma_f32_16x16x32_bf16 v[24:27], v[112:115], v[176:179], 0
	v_mfma_f32_16x16x32_bf16 v[12:15], v[96:99], v[200:203], 0
	v_mfma_f32_16x16x32_bf16 v[8:11], v[112:115], v[200:203], 0
	v_mfma_f32_16x16x32_bf16 v[60:63], v[100:103], v[164:167], v[60:63]
	v_mfma_f32_16x16x32_bf16 v[56:59], v[116:119], v[164:167], v[56:59]
	v_mfma_f32_16x16x32_bf16 v[44:47], v[100:103], v[172:175], v[44:47]
	v_mfma_f32_16x16x32_bf16 v[40:43], v[116:119], v[172:175], v[40:43]
	v_mfma_f32_16x16x32_bf16 v[28:31], v[100:103], v[180:183], v[28:31]
	v_mfma_f32_16x16x32_bf16 v[24:27], v[116:119], v[180:183], v[24:27]
	v_mfma_f32_16x16x32_bf16 v[12:15], v[100:103], v[204:207], v[12:15]
	v_mfma_f32_16x16x32_bf16 v[8:11], v[116:119], v[204:207], v[8:11]
	v_mfma_f32_16x16x32_bf16 v[52:55], v[144:147], v[160:163], 0
	v_mfma_f32_16x16x32_bf16 v[48:51], v[152:155], v[160:163], 0
	v_mfma_f32_16x16x32_bf16 v[36:39], v[144:147], v[168:171], 0
	v_mfma_f32_16x16x32_bf16 v[32:35], v[152:155], v[168:171], 0
	v_mfma_f32_16x16x32_bf16 v[20:23], v[144:147], v[176:179], 0
	v_mfma_f32_16x16x32_bf16 v[16:19], v[152:155], v[176:179], 0
	v_mfma_f32_16x16x32_bf16 v[4:7], v[144:147], v[200:203], 0
	v_mfma_f32_16x16x32_bf16 v[0:3], v[152:155], v[200:203], 0
	v_mfma_f32_16x16x32_bf16 v[52:55], v[148:151], v[164:167], v[52:55]
	v_mfma_f32_16x16x32_bf16 v[48:51], v[156:159], v[164:167], v[48:51]
	v_mfma_f32_16x16x32_bf16 v[36:39], v[148:151], v[172:175], v[36:39]
	v_mfma_f32_16x16x32_bf16 v[32:35], v[156:159], v[172:175], v[32:35]
	v_mfma_f32_16x16x32_bf16 v[20:23], v[148:151], v[180:183], v[20:23]
	v_mfma_f32_16x16x32_bf16 v[16:19], v[156:159], v[180:183], v[16:19]
	v_mfma_f32_16x16x32_bf16 v[4:7], v[148:151], v[204:207], v[4:7]
	v_mfma_f32_16x16x32_bf16 v[0:3], v[156:159], v[204:207], v[0:3]
	s_barrier
	s_setprio 1
	s_add_i32 s73, 0, 0x18000
	s_add_i32 s76, 0, 0x1c000
	v_add_u32_e32 v116, s73, v212
	v_add_u32_e32 v156, s76, v212
	ds_read_b128 v[96:99], v116
	ds_read_b128 v[100:103], v116 offset:1024
	ds_read_b128 v[112:115], v116 offset:2048
	ds_read_b128 v[116:119], v116 offset:3072
	ds_read_b128 v[144:147], v156
	ds_read_b128 v[148:151], v156 offset:1024
	ds_read_b128 v[152:155], v156 offset:2048
	ds_read_b128 v[156:159], v156 offset:3072
	s_add_u32 s42, s42, 0x80000
	s_addc_u32 s43, s43, 0
	s_mov_b32 m0, s50
	v_lshl_add_u64 v[222:223], s[42:43], 0, v[184:185]
	ds_read_b128 v[160:163], v217 offset:32768
	ds_read_b128 v[164:167], v217 offset:33792
	ds_read_b128 v[168:171], v217 offset:34816
	ds_read_b128 v[172:175], v217 offset:35840
	ds_read_b128 v[176:179], v217 offset:36864
	ds_read_b128 v[180:183], v217 offset:37888
	ds_read_b128 v[200:203], v217 offset:38912
	ds_read_b128 v[204:207], v217 offset:39936
	global_load_lds_dwordx4 v[222:223], off
	v_lshl_add_u64 v[222:223], s[42:43], 0, v[188:189]
	s_mov_b32 m0, s51
	s_nop 0
	global_load_lds_dwordx4 v[222:223], off
	s_waitcnt vmcnt(8)
	s_waitcnt lgkmcnt(0)
	s_setprio 0
	s_barrier
	v_mfma_f32_16x16x32_bf16 v[140:143], v[96:99], v[160:163], v[140:143]
	v_mfma_f32_16x16x32_bf16 v[136:139], v[112:115], v[160:163], v[136:139]
	v_mfma_f32_16x16x32_bf16 v[124:127], v[96:99], v[168:171], v[124:127]
	v_mfma_f32_16x16x32_bf16 v[120:123], v[112:115], v[168:171], v[120:123]
	v_mfma_f32_16x16x32_bf16 v[92:95], v[96:99], v[176:179], v[92:95]
	v_mfma_f32_16x16x32_bf16 v[88:91], v[112:115], v[176:179], v[88:91]
	v_mfma_f32_16x16x32_bf16 v[76:79], v[96:99], v[200:203], v[76:79]
	v_mfma_f32_16x16x32_bf16 v[72:75], v[112:115], v[200:203], v[72:75]
	v_mfma_f32_16x16x32_bf16 v[140:143], v[100:103], v[164:167], v[140:143]
	v_mfma_f32_16x16x32_bf16 v[136:139], v[116:119], v[164:167], v[136:139]
	v_mfma_f32_16x16x32_bf16 v[124:127], v[100:103], v[172:175], v[124:127]
	v_mfma_f32_16x16x32_bf16 v[120:123], v[116:119], v[172:175], v[120:123]
	v_mfma_f32_16x16x32_bf16 v[92:95], v[100:103], v[180:183], v[92:95]
	v_mfma_f32_16x16x32_bf16 v[88:91], v[116:119], v[180:183], v[88:91]
	v_mfma_f32_16x16x32_bf16 v[76:79], v[100:103], v[204:207], v[76:79]
	v_mfma_f32_16x16x32_bf16 v[72:75], v[116:119], v[204:207], v[72:75]
	v_mfma_f32_16x16x32_bf16 v[132:135], v[144:147], v[160:163], v[132:135]
	v_mfma_f32_16x16x32_bf16 v[128:131], v[152:155], v[160:163], v[128:131]
	v_mfma_f32_16x16x32_bf16 v[108:111], v[144:147], v[168:171], v[108:111]
	v_mfma_f32_16x16x32_bf16 v[104:107], v[152:155], v[168:171], v[104:107]
	v_mfma_f32_16x16x32_bf16 v[84:87], v[144:147], v[176:179], v[84:87]
	v_mfma_f32_16x16x32_bf16 v[80:83], v[152:155], v[176:179], v[80:83]
	v_mfma_f32_16x16x32_bf16 v[68:71], v[144:147], v[200:203], v[68:71]
	v_mfma_f32_16x16x32_bf16 v[64:67], v[152:155], v[200:203], v[64:67]
	v_mfma_f32_16x16x32_bf16 v[132:135], v[148:151], v[164:167], v[132:135]
	v_mfma_f32_16x16x32_bf16 v[128:131], v[156:159], v[164:167], v[128:131]
	v_mfma_f32_16x16x32_bf16 v[108:111], v[148:151], v[172:175], v[108:111]
	v_mfma_f32_16x16x32_bf16 v[104:107], v[156:159], v[172:175], v[104:107]
	v_mfma_f32_16x16x32_bf16 v[84:87], v[148:151], v[180:183], v[84:87]
	v_mfma_f32_16x16x32_bf16 v[80:83], v[156:159], v[180:183], v[80:83]
	v_mfma_f32_16x16x32_bf16 v[68:71], v[148:151], v[204:207], v[68:71]
	v_mfma_f32_16x16x32_bf16 v[64:67], v[156:159], v[204:207], v[64:67]
	s_barrier
; #define PG8_STAGE(bufoff, gbase, voff) do { _Pragma("unroll") for (int _i = 0; _i < 2; ++_i) \
;         __builtin_amdgcn_global_load_lds((const unsigned*)((const char*)(gbase) + (voff)[_i]), (LAS unsigned*)(lds + (bufoff) + ldsw + _i * 8192), 16, 0, 0); } while (0)
; #define PG8_LDA(dst, b, h) do { _Pragma("unroll") for (int m = 0; m < 4; ++m) _Pragma("unroll") for (int k = 0; k < 2; ++k) dst[m][k] = *(const LAS bf16x8*)(lds + PG8_SA(b, h) + aoff + m * 2048 + k * 1024); } while (0)
; #define PG8_LDB(dst, b, h) do { _Pragma("unroll") for (int n = 0; n < 2; ++n) _Pragma("unroll") for (int k = 0; k < 2; ++k) dst[n][k] = *(const LAS bf16x8*)(lds + PG8_SB(b, h) + boff + n * 2048 + k * 1024); } while (0)
; template <class Epi, class Sched = StaticOrder, class EpiSub = NoSub, bool FAST = false>
; __device__ __forceinline__ void gemm_phase(LAS unsigned char* lds, const Gemm g, const Sched& S, const Epi& E, const EpiSub& ES = EpiSub()) {
;     ...
;         for (int t = 0; t < nt; t += 2) {
;             const bool last = (t == nt - 2);
;             const char* a1 = cA + (size_t)(t + 1) * kstep;
;             const char* a2 = last ? nA : cA + (size_t)(t + 2) * kstep; const char* b2 = last ? nB : cB + (size_t)(t + 2) * kstep;
;             const char* a3 = a2 + kstep; const char* b3 = b2 + kstep;
;             if constexpr (FAST && PG8_SP2) {
;             PG8_LDB(B0, 0, 0); PG8_LDB(B1, 0, 1); PG8_SCHED; PG8_LDA(At, 0, 0); PG8_STAGE(PG8_SA(1, 1), a1 + hstepA, voffA);
;             PG8_WAIT_V(8); PG8_WAIT_L(0); PG8_BAR; PG8_MMA(0, 0, At, B0); PG8_MMA(0, 1, At, B1); PG8_BAR; PG8_SCHED;
;             PG8_LDA(At, 0, 1); PG8_STAGE(PG8_SB(0, 0), b2, voffB); PG8_STAGE(PG8_SB(0, 1), b2 + hstepB, voffB); PG8_STAGE(PG8_SA(0, 0), a2, voffA);
;             PG8_WAIT_V(8); PG8_WAIT_L(0); PG8_BAR; PG8_MMA(1, 0, At, B0); PG8_MMA(1, 1, At, B1); PG8_BAR; PG8_SCHED;
;             PG8_LDB(B0, 1, 0); PG8_LDB(B1, 1, 1); PG8_SCHED; PG8_LDA(At, 1, 0); PG8_STAGE(PG8_SA(0, 1), a2 + hstepA, voffA);
;             PG8_WAIT_V(8); PG8_WAIT_L(0); PG8_BAR; PG8_MMA(0, 0, At, B0); PG8_MMA(0, 1, At, B1); PG8_BAR; PG8_SCHED;
;             PG8_LDA(At, 1, 1); PG8_STAGE(PG8_SB(1, 0), b3, voffB); PG8_STAGE(PG8_SB(1, 1), b3 + hstepB, voffB); PG8_STAGE(PG8_SA(1, 0), a3, voffA);
;             PG8_WAIT_V(8); PG8_WAIT_L(0); PG8_BAR; PG8_MMA(1, 0, At, B0); PG8_MMA(1, 1, At, B1); PG8_BAR; PG8_SCHED;
	s_setprio 1
	s_add_i32 s42, s73, s17
	v_lshl_add_u64 v[208:209], v[208:209], 0, s[12:13]
	s_mov_b32 m0, s42
	ds_read_b128 v[160:163], v217 offset:49152
	ds_read_b128 v[164:167], v217 offset:50176
	ds_read_b128 v[168:171], v217 offset:51200
	ds_read_b128 v[172:175], v217 offset:52224
	ds_read_b128 v[176:179], v217 offset:53248
	ds_read_b128 v[180:183], v217 offset:54272
	ds_read_b128 v[200:203], v217 offset:55296
	ds_read_b128 v[204:207], v217 offset:56320
	global_load_lds_dwordx4 v[208:209], off
	s_add_i32 m0, s42, 0x2000
	s_add_u32 s40, s40, 0x80080
	v_lshl_add_u64 v[208:209], v[210:211], 0, s[12:13]
	s_addc_u32 s41, s41, 0
	s_add_i32 s42, s76, s17
	global_load_lds_dwordx4 v[208:209], off
	v_lshl_add_u64 v[208:209], s[40:41], 0, v[186:187]
	s_mov_b32 m0, s42
	s_nop 0
	global_load_lds_dwordx4 v[208:209], off
	v_lshl_add_u64 v[208:209], s[40:41], 0, v[190:191]
	s_add_i32 m0, s42, 0x2000
	s_nop 0
	global_load_lds_dwordx4 v[208:209], off
	v_lshl_add_u64 v[208:209], v[218:219], 0, s[12:13]
	s_mov_b32 m0, s55
	s_nop 0
	global_load_lds_dwordx4 v[208:209], off
	v_lshl_add_u64 v[208:209], v[220:221], 0, s[12:13]
	s_mov_b32 m0, s56
	s_nop 0
	global_load_lds_dwordx4 v[208:209], off
	s_waitcnt vmcnt(8)
	s_waitcnt lgkmcnt(0)
	s_setprio 0
	s_barrier
	v_mfma_f32_16x16x32_bf16 v[60:63], v[96:99], v[160:163], v[60:63]
	v_mfma_f32_16x16x32_bf16 v[56:59], v[112:115], v[160:163], v[56:59]
	v_mfma_f32_16x16x32_bf16 v[44:47], v[96:99], v[168:171], v[44:47]
	v_mfma_f32_16x16x32_bf16 v[40:43], v[112:115], v[168:171], v[40:43]
	v_mfma_f32_16x16x32_bf16 v[28:31], v[96:99], v[176:179], v[28:31]
	v_mfma_f32_16x16x32_bf16 v[24:27], v[112:115], v[176:179], v[24:27]
	v_mfma_f32_16x16x32_bf16 v[12:15], v[96:99], v[200:203], v[12:15]
	v_mfma_f32_16x16x32_bf16 v[8:11], v[112:115], v[200:203], v[8:11]
	v_mfma_f32_16x16x32_bf16 v[60:63], v[100:103], v[164:167], v[60:63]
	v_mfma_f32_16x16x32_bf16 v[56:59], v[116:119], v[164:167], v[56:59]
	v_mfma_f32_16x16x32_bf16 v[44:47], v[100:103], v[172:175], v[44:47]
	v_mfma_f32_16x16x32_bf16 v[40:43], v[116:119], v[172:175], v[40:43]
	v_mfma_f32_16x16x32_bf16 v[28:31], v[100:103], v[180:183], v[28:31]
	v_mfma_f32_16x16x32_bf16 v[24:27], v[116:119], v[180:183], v[24:27]
	v_mfma_f32_16x16x32_bf16 v[12:15], v[100:103], v[204:207], v[12:15]
	v_mfma_f32_16x16x32_bf16 v[8:11], v[116:119], v[204:207], v[8:11]
	v_mfma_f32_16x16x32_bf16 v[52:55], v[144:147], v[160:163], v[52:55]
	v_mfma_f32_16x16x32_bf16 v[48:51], v[152:155], v[160:163], v[48:51]
	v_mfma_f32_16x16x32_bf16 v[36:39], v[144:147], v[168:171], v[36:39]
	v_mfma_f32_16x16x32_bf16 v[32:35], v[152:155], v[168:171], v[32:35]
	v_mfma_f32_16x16x32_bf16 v[20:23], v[144:147], v[176:179], v[20:23]
	v_mfma_f32_16x16x32_bf16 v[16:19], v[152:155], v[176:179], v[16:19]
	v_mfma_f32_16x16x32_bf16 v[4:7], v[144:147], v[200:203], v[4:7]
	v_mfma_f32_16x16x32_bf16 v[0:3], v[152:155], v[200:203], v[0:3]
	v_mfma_f32_16x16x32_bf16 v[52:55], v[148:151], v[164:167], v[52:55]
	v_mfma_f32_16x16x32_bf16 v[48:51], v[156:159], v[164:167], v[48:51]
	v_mfma_f32_16x16x32_bf16 v[36:39], v[148:151], v[172:175], v[36:39]
	v_mfma_f32_16x16x32_bf16 v[32:35], v[156:159], v[172:175], v[32:35]
	v_mfma_f32_16x16x32_bf16 v[20:23], v[148:151], v[180:183], v[20:23]
	v_mfma_f32_16x16x32_bf16 v[16:19], v[156:159], v[180:183], v[16:19]
	v_mfma_f32_16x16x32_bf16 v[4:7], v[148:151], v[204:207], v[4:7]
	v_mfma_f32_16x16x32_bf16 v[0:3], v[156:159], v[204:207], v[0:3]
	s_barrier
	s_setprio 1
	s_add_u32 s38, s38, 0x100
	s_addc_u32 s39, s39, 0
	s_add_u32 s70, s70, 0x100
	s_addc_u32 s71, s71, 0
	s_cmp_ge_u32 s72, s29
	s_mov_b32 s42, s72
	s_cbranch_scc1 .Lkpeel_769_exit
.LBB0_769:
	ds_read_b128 v[96:99], v215
	ds_read_b128 v[100:103], v215 offset:1024
	ds_read_b128 v[112:115], v215 offset:2048
	ds_read_b128 v[116:119], v215 offset:3072
	ds_read_b128 v[144:147], v216
	ds_read_b128 v[148:151], v216 offset:1024
	ds_read_b128 v[152:155], v216 offset:2048
	ds_read_b128 v[156:159], v216 offset:3072
	s_add_i32 s72, s42, 2
	s_add_u32 s40, s38, 0xfff80080
	s_addc_u32 s41, s39, -1
	s_cmp_eq_u32 s33, s42
	s_cselect_b32 s42, s5, s40
	s_cselect_b32 s43, s1, s41
	s_cselect_b32 s41, s19, s71
	s_cselect_b32 s40, s21, s70
	v_lshl_add_u64 v[208:209], s[38:39], 0, v[194:195]
	s_add_i32 m0, s48, 0xc000
	ds_read_b128 v[160:163], v217
	ds_read_b128 v[164:167], v217 offset:1024
	ds_read_b128 v[168:171], v217 offset:2048
	ds_read_b128 v[172:175], v217 offset:3072
	ds_read_b128 v[176:179], v217 offset:4096
	ds_read_b128 v[180:183], v217 offset:5120
	ds_read_b128 v[200:203], v217 offset:6144
	ds_read_b128 v[204:207], v217 offset:7168
	global_load_lds_dwordx4 v[208:209], off
	v_lshl_add_u64 v[208:209], s[38:39], 0, v[196:197]
	s_add_i32 m0, s48, 0xe000
	s_nop 0
	global_load_lds_dwordx4 v[208:209], off
	s_waitcnt vmcnt(8)
	s_waitcnt lgkmcnt(0)
	s_setprio 0
	s_barrier
; #define PG8_STAGE(bufoff, gbase, voff) do { _Pragma("unroll") for (int _i = 0; _i < 2; ++_i) \
;         __builtin_amdgcn_global_load_lds((const unsigned*)((const char*)(gbase) + (voff)[_i]), (LAS unsigned*)(lds + (bufoff) + ldsw + _i * 8192), 16, 0, 0); } while (0)
; #define PG8_LDA(dst, b, h) do { _Pragma("unroll") for (int m = 0; m < 4; ++m) _Pragma("unroll") for (int k = 0; k < 2; ++k) dst[m][k] = *(const LAS bf16x8*)(lds + PG8_SA(b, h) + aoff + m * 2048 + k * 1024); } while (0)
; #define PG8_LDB(dst, b, h) do { _Pragma("unroll") for (int n = 0; n < 2; ++n) _Pragma("unroll") for (int k = 0; k < 2; ++k) dst[n][k] = *(const LAS bf16x8*)(lds + PG8_SB(b, h) + boff + n * 2048 + k * 1024); } while (0)
; #define PG8_MMA(ai, bj, At, Bt) do { __builtin_amdgcn_s_setprio(1); _Pragma("unroll") for (int m = 0; m < 4; ++m) _Pragma("unroll") for (int n = 0; n < 2; ++n) _Pragma("unroll") for (int k = 0; k < 2; ++k) \
;         acc[ai][bj][m][n] = __builtin_amdgcn_mfma_f32_16x16x32_bf16(Bt[n][k], At[m][k], acc[ai][bj][m][n], 0, 0, 0); __builtin_amdgcn_s_setprio(0); } while (0)
; #define PG8_WAIT_V(n) asm volatile("s_waitcnt vmcnt(" #n ")" ::: "memory")
; #define PG8_WAIT_L(n) asm volatile("s_waitcnt lgkmcnt(" #n ")" ::: "memory")
; #define PG8_BAR __builtin_amdgcn_s_barrier()
; #define PG8_SCHED __builtin_amdgcn_sched_barrier(0)
; template <class Epi, class Sched = StaticOrder, class EpiSub = NoSub, bool FAST = false>
; __device__ __forceinline__ void gemm_phase(LAS unsigned char* lds, const Gemm g, const Sched& S, const Epi& E, const EpiSub& ES = EpiSub()) {
;     ...
;             PG8_LDB(B0, 0, 0); PG8_LDB(B1, 0, 1); PG8_SCHED; PG8_LDA(At, 0, 0); PG8_STAGE(PG8_SA(1, 1), a1 + hstepA, voffA);
;             PG8_WAIT_V(8); PG8_WAIT_L(0); PG8_BAR; PG8_MMA(0, 0, At, B0); PG8_MMA(0, 1, At, B1); PG8_BAR; PG8_SCHED;
;             PG8_LDA(At, 0, 1); PG8_STAGE(PG8_SB(0, 0), b2, voffB); PG8_STAGE(PG8_SB(0, 1), b2 + hstepB, voffB); PG8_STAGE(PG8_SA(0, 0), a2, voffA);
;             PG8_WAIT_V(8); PG8_WAIT_L(0); PG8_BAR; PG8_MMA(1, 0, At, B0); PG8_MMA(1, 1, At, B1); PG8_BAR; PG8_SCHED;
	v_mfma_f32_16x16x32_bf16 v[140:143], v[96:99], v[160:163], v[140:143]
	v_mfma_f32_16x16x32_bf16 v[136:139], v[112:115], v[160:163], v[136:139]
	v_mfma_f32_16x16x32_bf16 v[124:127], v[96:99], v[168:171], v[124:127]
	v_mfma_f32_16x16x32_bf16 v[120:123], v[112:115], v[168:171], v[120:123]
	v_mfma_f32_16x16x32_bf16 v[92:95], v[96:99], v[176:179], v[92:95]
	v_mfma_f32_16x16x32_bf16 v[88:91], v[112:115], v[176:179], v[88:91]
	v_mfma_f32_16x16x32_bf16 v[76:79], v[96:99], v[200:203], v[76:79]
	v_mfma_f32_16x16x32_bf16 v[72:75], v[112:115], v[200:203], v[72:75]
	v_mfma_f32_16x16x32_bf16 v[140:143], v[100:103], v[164:167], v[140:143]
	v_mfma_f32_16x16x32_bf16 v[136:139], v[116:119], v[164:167], v[136:139]
	v_mfma_f32_16x16x32_bf16 v[124:127], v[100:103], v[172:175], v[124:127]
	v_mfma_f32_16x16x32_bf16 v[120:123], v[116:119], v[172:175], v[120:123]
	v_mfma_f32_16x16x32_bf16 v[92:95], v[100:103], v[180:183], v[92:95]
	v_mfma_f32_16x16x32_bf16 v[88:91], v[116:119], v[180:183], v[88:91]
	v_mfma_f32_16x16x32_bf16 v[76:79], v[100:103], v[204:207], v[76:79]
	v_mfma_f32_16x16x32_bf16 v[72:75], v[116:119], v[204:207], v[72:75]
	v_mfma_f32_16x16x32_bf16 v[132:135], v[144:147], v[160:163], v[132:135]
	v_mfma_f32_16x16x32_bf16 v[128:131], v[152:155], v[160:163], v[128:131]
	v_mfma_f32_16x16x32_bf16 v[108:111], v[144:147], v[168:171], v[108:111]
	v_mfma_f32_16x16x32_bf16 v[104:107], v[152:155], v[168:171], v[104:107]
	v_mfma_f32_16x16x32_bf16 v[84:87], v[144:147], v[176:179], v[84:87]
	v_mfma_f32_16x16x32_bf16 v[80:83], v[152:155], v[176:179], v[80:83]
	v_mfma_f32_16x16x32_bf16 v[68:71], v[144:147], v[200:203], v[68:71]
	v_mfma_f32_16x16x32_bf16 v[64:67], v[152:155], v[200:203], v[64:67]
	v_mfma_f32_16x16x32_bf16 v[132:135], v[148:151], v[164:167], v[132:135]
	v_mfma_f32_16x16x32_bf16 v[128:131], v[156:159], v[164:167], v[128:131]
	v_mfma_f32_16x16x32_bf16 v[108:111], v[148:151], v[172:175], v[108:111]
	v_mfma_f32_16x16x32_bf16 v[104:107], v[156:159], v[172:175], v[104:107]
	v_mfma_f32_16x16x32_bf16 v[84:87], v[148:151], v[180:183], v[84:87]
	v_mfma_f32_16x16x32_bf16 v[80:83], v[156:159], v[180:183], v[80:83]
	v_mfma_f32_16x16x32_bf16 v[68:71], v[148:151], v[204:207], v[68:71]
	v_mfma_f32_16x16x32_bf16 v[64:67], v[156:159], v[204:207], v[64:67]
	s_barrier
	s_setprio 1
	s_add_i32 s73, s58, s17
	v_lshl_add_u64 v[208:209], s[40:41], 0, v[186:187]
	s_mov_b32 m0, s73
	ds_read_b128 v[160:163], v217 offset:16384
	ds_read_b128 v[164:167], v217 offset:17408
	ds_read_b128 v[168:171], v217 offset:18432
	ds_read_b128 v[172:175], v217 offset:19456
	ds_read_b128 v[176:179], v217 offset:20480
	ds_read_b128 v[180:183], v217 offset:21504
	ds_read_b128 v[200:203], v217 offset:22528
	ds_read_b128 v[204:207], v217 offset:23552
	global_load_lds_dwordx4 v[208:209], off
	s_add_i32 m0, s73, 0x2000
	s_add_u32 s76, s40, 0x80000
	v_lshl_add_u64 v[210:211], s[40:41], 0, v[190:191]
	s_addc_u32 s77, s41, 0
	s_add_i32 s73, s59, s17
	global_load_lds_dwordx4 v[210:211], off
	v_lshl_add_u64 v[218:219], s[76:77], 0, v[186:187]
	s_mov_b32 m0, s73
	v_lshl_add_u64 v[220:221], s[42:43], 0, v[188:189]
	global_load_lds_dwordx4 v[218:219], off
	v_lshl_add_u64 v[218:219], s[76:77], 0, v[190:191]
	s_add_i32 m0, s73, 0x2000
	s_nop 0
	global_load_lds_dwordx4 v[218:219], off
	v_lshl_add_u64 v[218:219], s[42:43], 0, v[184:185]
	s_mov_b32 m0, s48
	s_nop 0
	global_load_lds_dwordx4 v[218:219], off
	s_mov_b32 m0, s49
	s_nop 0
	global_load_lds_dwordx4 v[220:221], off
	s_waitcnt vmcnt(8)
	s_waitcnt lgkmcnt(0)
	s_setprio 0
	s_barrier
	v_mfma_f32_16x16x32_bf16 v[60:63], v[96:99], v[160:163], v[60:63]
	v_mfma_f32_16x16x32_bf16 v[56:59], v[112:115], v[160:163], v[56:59]
	v_mfma_f32_16x16x32_bf16 v[44:47], v[96:99], v[168:171], v[44:47]
	v_mfma_f32_16x16x32_bf16 v[40:43], v[112:115], v[168:171], v[40:43]
	v_mfma_f32_16x16x32_bf16 v[28:31], v[96:99], v[176:179], v[28:31]
	v_mfma_f32_16x16x32_bf16 v[24:27], v[112:115], v[176:179], v[24:27]
	v_mfma_f32_16x16x32_bf16 v[12:15], v[96:99], v[200:203], v[12:15]
	v_mfma_f32_16x16x32_bf16 v[8:11], v[112:115], v[200:203], v[8:11]
	v_mfma_f32_16x16x32_bf16 v[60:63], v[100:103], v[164:167], v[60:63]
	v_mfma_f32_16x16x32_bf16 v[56:59], v[116:119], v[164:167], v[56:59]
	v_mfma_f32_16x16x32_bf16 v[44:47], v[100:103], v[172:175], v[44:47]
	v_mfma_f32_16x16x32_bf16 v[40:43], v[116:119], v[172:175], v[40:43]
	v_mfma_f32_16x16x32_bf16 v[28:31], v[100:103], v[180:183], v[28:31]
	v_mfma_f32_16x16x32_bf16 v[24:27], v[116:119], v[180:183], v[24:27]
	v_mfma_f32_16x16x32_bf16 v[12:15], v[100:103], v[204:207], v[12:15]
	v_mfma_f32_16x16x32_bf16 v[8:11], v[116:119], v[204:207], v[8:11]
	v_mfma_f32_16x16x32_bf16 v[52:55], v[144:147], v[160:163], v[52:55]
	v_mfma_f32_16x16x32_bf16 v[48:51], v[152:155], v[160:163], v[48:51]
	v_mfma_f32_16x16x32_bf16 v[36:39], v[144:147], v[168:171], v[36:39]
	v_mfma_f32_16x16x32_bf16 v[32:35], v[152:155], v[168:171], v[32:35]
	v_mfma_f32_16x16x32_bf16 v[20:23], v[144:147], v[176:179], v[20:23]
	v_mfma_f32_16x16x32_bf16 v[16:19], v[152:155], v[176:179], v[16:19]
	v_mfma_f32_16x16x32_bf16 v[4:7], v[144:147], v[200:203], v[4:7]
	v_mfma_f32_16x16x32_bf16 v[0:3], v[152:155], v[200:203], v[0:3]
	v_mfma_f32_16x16x32_bf16 v[52:55], v[148:151], v[164:167], v[52:55]
	v_mfma_f32_16x16x32_bf16 v[48:51], v[156:159], v[164:167], v[48:51]
	v_mfma_f32_16x16x32_bf16 v[36:39], v[148:151], v[172:175], v[36:39]
	v_mfma_f32_16x16x32_bf16 v[32:35], v[156:159], v[172:175], v[32:35]
	v_mfma_f32_16x16x32_bf16 v[20:23], v[148:151], v[180:183], v[20:23]
	v_mfma_f32_16x16x32_bf16 v[16:19], v[156:159], v[180:183], v[16:19]
	v_mfma_f32_16x16x32_bf16 v[4:7], v[148:151], v[204:207], v[4:7]
	v_mfma_f32_16x16x32_bf16 v[0:3], v[156:159], v[204:207], v[0:3]
	s_barrier
; #define PG8_STAGE(bufoff, gbase, voff) do { _Pragma("unroll") for (int _i = 0; _i < 2; ++_i) \
;         __builtin_amdgcn_global_load_lds((const unsigned*)((const char*)(gbase) + (voff)[_i]), (LAS unsigned*)(lds + (bufoff) + ldsw + _i * 8192), 16, 0, 0); } while (0)
; #define PG8_LDA(dst, b, h) do { _Pragma("unroll") for (int m = 0; m < 4; ++m) _Pragma("unroll") for (int k = 0; k < 2; ++k) dst[m][k] = *(const LAS bf16x8*)(lds + PG8_SA(b, h) + aoff + m * 2048 + k * 1024); } while (0)
; #define PG8_LDB(dst, b, h) do { _Pragma("unroll") for (int n = 0; n < 2; ++n) _Pragma("unroll") for (int k = 0; k < 2; ++k) dst[n][k] = *(const LAS bf16x8*)(lds + PG8_SB(b, h) + boff + n * 2048 + k * 1024); } while (0)
; #define PG8_MMA(ai, bj, At, Bt) do { __builtin_amdgcn_s_setprio(1); _Pragma("unroll") for (int m = 0; m < 4; ++m) _Pragma("unroll") for (int n = 0; n < 2; ++n) _Pragma("unroll") for (int k = 0; k < 2; ++k) \
;         acc[ai][bj][m][n] = __builtin_amdgcn_mfma_f32_16x16x32_bf16(Bt[n][k], At[m][k], acc[ai][bj][m][n], 0, 0, 0); __builtin_amdgcn_s_setprio(0); } while (0)
; #define PG8_WAIT_V(n) asm volatile("s_waitcnt vmcnt(" #n ")" ::: "memory")
; #define PG8_WAIT_L(n) asm volatile("s_waitcnt lgkmcnt(" #n ")" ::: "memory")
; #define PG8_BAR __builtin_amdgcn_s_barrier()
; #define PG8_SCHED __builtin_amdgcn_sched_barrier(0)
; template <class Epi, class Sched = StaticOrder, class EpiSub = NoSub, bool FAST = false>
; __device__ __forceinline__ void gemm_phase(LAS unsigned char* lds, const Gemm g, const Sched& S, const Epi& E, const EpiSub& ES = EpiSub()) {
;     ...
;             PG8_LDB(B0, 1, 0); PG8_LDB(B1, 1, 1); PG8_SCHED; PG8_LDA(At, 1, 0); PG8_STAGE(PG8_SA(0, 1), a2 + hstepA, voffA);
;             PG8_WAIT_V(8); PG8_WAIT_L(0); PG8_BAR; PG8_MMA(0, 0, At, B0); PG8_MMA(0, 1, At, B1); PG8_BAR; PG8_SCHED;
	s_setprio 1
	s_add_i32 s73, 0, 0x18000
	s_add_i32 s76, 0, 0x1c000
	v_add_u32_e32 v116, s73, v212
	v_add_u32_e32 v156, s76, v212
	ds_read_b128 v[96:99], v116
	ds_read_b128 v[100:103], v116 offset:1024
	ds_read_b128 v[112:115], v116 offset:2048
	ds_read_b128 v[116:119], v116 offset:3072
	ds_read_b128 v[144:147], v156
	ds_read_b128 v[148:151], v156 offset:1024
	ds_read_b128 v[152:155], v156 offset:2048
	ds_read_b128 v[156:159], v156 offset:3072
	s_add_u32 s42, s42, 0x80000
	s_addc_u32 s43, s43, 0
	s_mov_b32 m0, s50
	v_lshl_add_u64 v[222:223], s[42:43], 0, v[184:185]
	ds_read_b128 v[160:163], v217 offset:32768
	ds_read_b128 v[164:167], v217 offset:33792
	ds_read_b128 v[168:171], v217 offset:34816
	ds_read_b128 v[172:175], v217 offset:35840
	ds_read_b128 v[176:179], v217 offset:36864
	ds_read_b128 v[180:183], v217 offset:37888
	ds_read_b128 v[200:203], v217 offset:38912
	ds_read_b128 v[204:207], v217 offset:39936
	global_load_lds_dwordx4 v[222:223], off
	v_lshl_add_u64 v[222:223], s[42:43], 0, v[188:189]
	s_mov_b32 m0, s51
	s_nop 0
	global_load_lds_dwordx4 v[222:223], off
	s_waitcnt vmcnt(8)
	s_waitcnt lgkmcnt(0)
	s_setprio 0
	s_barrier
	v_mfma_f32_16x16x32_bf16 v[140:143], v[96:99], v[160:163], v[140:143]
	v_mfma_f32_16x16x32_bf16 v[136:139], v[112:115], v[160:163], v[136:139]
	v_mfma_f32_16x16x32_bf16 v[124:127], v[96:99], v[168:171], v[124:127]
	v_mfma_f32_16x16x32_bf16 v[120:123], v[112:115], v[168:171], v[120:123]
	v_mfma_f32_16x16x32_bf16 v[92:95], v[96:99], v[176:179], v[92:95]
	v_mfma_f32_16x16x32_bf16 v[88:91], v[112:115], v[176:179], v[88:91]
	v_mfma_f32_16x16x32_bf16 v[76:79], v[96:99], v[200:203], v[76:79]
	v_mfma_f32_16x16x32_bf16 v[72:75], v[112:115], v[200:203], v[72:75]
	v_mfma_f32_16x16x32_bf16 v[140:143], v[100:103], v[164:167], v[140:143]
	v_mfma_f32_16x16x32_bf16 v[136:139], v[116:119], v[164:167], v[136:139]
	v_mfma_f32_16x16x32_bf16 v[124:127], v[100:103], v[172:175], v[124:127]
	v_mfma_f32_16x16x32_bf16 v[120:123], v[116:119], v[172:175], v[120:123]
	v_mfma_f32_16x16x32_bf16 v[92:95], v[100:103], v[180:183], v[92:95]
	v_mfma_f32_16x16x32_bf16 v[88:91], v[116:119], v[180:183], v[88:91]
	v_mfma_f32_16x16x32_bf16 v[76:79], v[100:103], v[204:207], v[76:79]
	v_mfma_f32_16x16x32_bf16 v[72:75], v[116:119], v[204:207], v[72:75]
	v_mfma_f32_16x16x32_bf16 v[132:135], v[144:147], v[160:163], v[132:135]
	v_mfma_f32_16x16x32_bf16 v[128:131], v[152:155], v[160:163], v[128:131]
	v_mfma_f32_16x16x32_bf16 v[108:111], v[144:147], v[168:171], v[108:111]
	v_mfma_f32_16x16x32_bf16 v[104:107], v[152:155], v[168:171], v[104:107]
	v_mfma_f32_16x16x32_bf16 v[84:87], v[144:147], v[176:179], v[84:87]
	v_mfma_f32_16x16x32_bf16 v[80:83], v[152:155], v[176:179], v[80:83]
	v_mfma_f32_16x16x32_bf16 v[68:71], v[144:147], v[200:203], v[68:71]
	v_mfma_f32_16x16x32_bf16 v[64:67], v[152:155], v[200:203], v[64:67]
	v_mfma_f32_16x16x32_bf16 v[132:135], v[148:151], v[164:167], v[132:135]
	v_mfma_f32_16x16x32_bf16 v[128:131], v[156:159], v[164:167], v[128:131]
	v_mfma_f32_16x16x32_bf16 v[108:111], v[148:151], v[172:175], v[108:111]
	v_mfma_f32_16x16x32_bf16 v[104:107], v[156:159], v[172:175], v[104:107]
	v_mfma_f32_16x16x32_bf16 v[84:87], v[148:151], v[180:183], v[84:87]
	v_mfma_f32_16x16x32_bf16 v[80:83], v[156:159], v[180:183], v[80:83]
	v_mfma_f32_16x16x32_bf16 v[68:71], v[148:151], v[204:207], v[68:71]
	v_mfma_f32_16x16x32_bf16 v[64:67], v[156:159], v[204:207], v[64:67]
	s_barrier
; #define PG8_STAGE(bufoff, gbase, voff) do { _Pragma("unroll") for (int _i = 0; _i < 2; ++_i) \
;         __builtin_amdgcn_global_load_lds((const unsigned*)((const char*)(gbase) + (voff)[_i]), (LAS unsigned*)(lds + (bufoff) + ldsw + _i * 8192), 16, 0, 0); } while (0)
; #define PG8_LDA(dst, b, h) do { _Pragma("unroll") for (int m = 0; m < 4; ++m) _Pragma("unroll") for (int k = 0; k < 2; ++k) dst[m][k] = *(const LAS bf16x8*)(lds + PG8_SA(b, h) + aoff + m * 2048 + k * 1024); } while (0)
; #define PG8_MMA(ai, bj, At, Bt) do { __builtin_amdgcn_s_setprio(1); _Pragma("unroll") for (int m = 0; m < 4; ++m) _Pragma("unroll") for (int n = 0; n < 2; ++n) _Pragma("unroll") for (int k = 0; k < 2; ++k) \
;         acc[ai][bj][m][n] = __builtin_amdgcn_mfma_f32_16x16x32_bf16(Bt[n][k], At[m][k], acc[ai][bj][m][n], 0, 0, 0); __builtin_amdgcn_s_setprio(0); } while (0)
; #define PG8_WAIT_V(n) asm volatile("s_waitcnt vmcnt(" #n ")" ::: "memory")
; #define PG8_WAIT_L(n) asm volatile("s_waitcnt lgkmcnt(" #n ")" ::: "memory")
; #define PG8_BAR __builtin_amdgcn_s_barrier()
; #define PG8_SCHED __builtin_amdgcn_sched_barrier(0)
; template <class Epi, class Sched = StaticOrder, class EpiSub = NoSub, bool FAST = false>
; __device__ __forceinline__ void gemm_phase(LAS unsigned char* lds, const Gemm g, const Sched& S, const Epi& E, const EpiSub& ES = EpiSub()) {
;     ...
;             PG8_LDA(At, 1, 1); PG8_STAGE(PG8_SB(1, 0), b3, voffB); PG8_STAGE(PG8_SB(1, 1), b3 + hstepB, voffB); PG8_STAGE(PG8_SA(1, 0), a3, voffA);
;             PG8_WAIT_V(8); PG8_WAIT_L(0); PG8_BAR; PG8_MMA(1, 0, At, B0); PG8_MMA(1, 1, At, B1); PG8_BAR; PG8_SCHED;
	s_setprio 1
	s_add_i32 s42, s73, s17
	v_lshl_add_u64 v[208:209], v[208:209], 0, s[12:13]
	s_mov_b32 m0, s42
	ds_read_b128 v[160:163], v217 offset:49152
	ds_read_b128 v[164:167], v217 offset:50176
	ds_read_b128 v[168:171], v217 offset:51200
	ds_read_b128 v[172:175], v217 offset:52224
	ds_read_b128 v[176:179], v217 offset:53248
	ds_read_b128 v[180:183], v217 offset:54272
	ds_read_b128 v[200:203], v217 offset:55296
	ds_read_b128 v[204:207], v217 offset:56320
	global_load_lds_dwordx4 v[208:209], off
	s_add_i32 m0, s42, 0x2000
	s_add_u32 s40, s40, 0x80080
	v_lshl_add_u64 v[208:209], v[210:211], 0, s[12:13]
	s_addc_u32 s41, s41, 0
	s_add_i32 s42, s76, s17
	global_load_lds_dwordx4 v[208:209], off
	v_lshl_add_u64 v[208:209], s[40:41], 0, v[186:187]
	s_mov_b32 m0, s42
	s_nop 0
	global_load_lds_dwordx4 v[208:209], off
	v_lshl_add_u64 v[208:209], s[40:41], 0, v[190:191]
	s_add_i32 m0, s42, 0x2000
	s_nop 0
	global_load_lds_dwordx4 v[208:209], off
	v_lshl_add_u64 v[208:209], v[218:219], 0, s[12:13]
	s_mov_b32 m0, s55
	s_nop 0
	global_load_lds_dwordx4 v[208:209], off
	v_lshl_add_u64 v[208:209], v[220:221], 0, s[12:13]
	s_mov_b32 m0, s56
	s_nop 0
	global_load_lds_dwordx4 v[208:209], off
	s_waitcnt vmcnt(8)
	s_waitcnt lgkmcnt(0)
	s_setprio 0
	s_barrier
	v_mfma_f32_16x16x32_bf16 v[60:63], v[96:99], v[160:163], v[60:63]
	v_mfma_f32_16x16x32_bf16 v[56:59], v[112:115], v[160:163], v[56:59]
	v_mfma_f32_16x16x32_bf16 v[44:47], v[96:99], v[168:171], v[44:47]
	v_mfma_f32_16x16x32_bf16 v[40:43], v[112:115], v[168:171], v[40:43]
	v_mfma_f32_16x16x32_bf16 v[28:31], v[96:99], v[176:179], v[28:31]
	v_mfma_f32_16x16x32_bf16 v[24:27], v[112:115], v[176:179], v[24:27]
	v_mfma_f32_16x16x32_bf16 v[12:15], v[96:99], v[200:203], v[12:15]
	v_mfma_f32_16x16x32_bf16 v[8:11], v[112:115], v[200:203], v[8:11]
	v_mfma_f32_16x16x32_bf16 v[60:63], v[100:103], v[164:167], v[60:63]
	v_mfma_f32_16x16x32_bf16 v[56:59], v[116:119], v[164:167], v[56:59]
	v_mfma_f32_16x16x32_bf16 v[44:47], v[100:103], v[172:175], v[44:47]
	v_mfma_f32_16x16x32_bf16 v[40:43], v[116:119], v[172:175], v[40:43]
	v_mfma_f32_16x16x32_bf16 v[28:31], v[100:103], v[180:183], v[28:31]
	v_mfma_f32_16x16x32_bf16 v[24:27], v[116:119], v[180:183], v[24:27]
	v_mfma_f32_16x16x32_bf16 v[12:15], v[100:103], v[204:207], v[12:15]
	v_mfma_f32_16x16x32_bf16 v[8:11], v[116:119], v[204:207], v[8:11]
	v_mfma_f32_16x16x32_bf16 v[52:55], v[144:147], v[160:163], v[52:55]
	v_mfma_f32_16x16x32_bf16 v[48:51], v[152:155], v[160:163], v[48:51]
	v_mfma_f32_16x16x32_bf16 v[36:39], v[144:147], v[168:171], v[36:39]
	v_mfma_f32_16x16x32_bf16 v[32:35], v[152:155], v[168:171], v[32:35]
	v_mfma_f32_16x16x32_bf16 v[20:23], v[144:147], v[176:179], v[20:23]
	v_mfma_f32_16x16x32_bf16 v[16:19], v[152:155], v[176:179], v[16:19]
	v_mfma_f32_16x16x32_bf16 v[4:7], v[144:147], v[200:203], v[4:7]
	v_mfma_f32_16x16x32_bf16 v[0:3], v[152:155], v[200:203], v[0:3]
	v_mfma_f32_16x16x32_bf16 v[52:55], v[148:151], v[164:167], v[52:55]
	v_mfma_f32_16x16x32_bf16 v[48:51], v[156:159], v[164:167], v[48:51]
	v_mfma_f32_16x16x32_bf16 v[36:39], v[148:151], v[172:175], v[36:39]
	v_mfma_f32_16x16x32_bf16 v[32:35], v[156:159], v[172:175], v[32:35]
	v_mfma_f32_16x16x32_bf16 v[20:23], v[148:151], v[180:183], v[20:23]
	v_mfma_f32_16x16x32_bf16 v[16:19], v[156:159], v[180:183], v[16:19]
	v_mfma_f32_16x16x32_bf16 v[4:7], v[148:151], v[204:207], v[4:7]
	v_mfma_f32_16x16x32_bf16 v[0:3], v[156:159], v[204:207], v[0:3]
	s_barrier
	s_setprio 1
	s_add_u32 s38, s38, 0x100
	s_addc_u32 s39, s39, 0
	s_add_u32 s70, s70, 0x100
	s_addc_u32 s71, s71, 0
	s_cmp_ge_u32 s72, s29
	s_mov_b32 s42, s72
	s_cbranch_scc0 .LBB0_769

; #define PG8_STAGE(bufoff, gbase, voff) do { _Pragma("unroll") for (int _i = 0; _i < 2; ++_i) \
;         __builtin_amdgcn_global_load_lds((const unsigned*)((const char*)(gbase) + (voff)[_i]), (LAS unsigned*)(lds + (bufoff) + ldsw + _i * 8192), 16, 0, 0); } while (0)
; #define PG8_LDA(dst, b, h) do { _Pragma("unroll") for (int m = 0; m < 4; ++m) _Pragma("unroll") for (int k = 0; k < 2; ++k) dst[m][k] = *(const LAS bf16x8*)(lds + PG8_SA(b, h) + aoff + m * 2048 + k * 1024); } while (0)
; #define PG8_LDB(dst, b, h) do { _Pragma("unroll") for (int n = 0; n < 2; ++n) _Pragma("unroll") for (int k = 0; k < 2; ++k) dst[n][k] = *(const LAS bf16x8*)(lds + PG8_SB(b, h) + boff + n * 2048 + k * 1024); } while (0)
; #define PG8_WAIT_V(n) asm volatile("s_waitcnt vmcnt(" #n ")" ::: "memory")
; #define PG8_BAR __builtin_amdgcn_s_barrier()
; template <class Epi, class Sched = StaticOrder, class EpiSub = NoSub, bool FAST = false>
; __device__ __forceinline__ void gemm_phase(LAS unsigned char* lds, const Gemm g, const Sched& S, const Epi& E, const EpiSub& ES = EpiSub()) {
;     ...
;         const bool has_next = S.next(ui + 1, nxt);
;         const size_t nko = (has_next && nxt.kb >= 0) ? nxt.kb * ksubB : 0;
;         const char* nA = has_next ? (const char*)g.A + (size_t)nxt.pm * tstepA + (size_t)nxt.pn * g.acs + nko : cA; const char* nB = has_next ? (const char*)g.Bt + (size_t)nxt.pn * tstepB + nko : cB;
;         const int nt = cur.kb < 0 ? ntMain : ntSub;
;         for (int t = 0; t < nt; t += 2) {
;             const bool last = (t == nt - 2);
;             const char* a1 = cA + (size_t)(t + 1) * kstep;
;             const char* a2 = last ? nA : cA + (size_t)(t + 2) * kstep; const char* b2 = last ? nB : cB + (size_t)(t + 2) * kstep;
;             const char* a3 = a2 + kstep; const char* b3 = b2 + kstep;
;             if constexpr (FAST && PG8_SP2) {
;             PG8_LDB(B0, 0, 0); PG8_LDB(B1, 0, 1); PG8_SCHED; PG8_LDA(At, 0, 0); PG8_STAGE(PG8_SA(1, 1), a1 + hstepA, voffA);
;             PG8_WAIT_V(8); PG8_WAIT_L(0); PG8_BAR; PG8_MMA(0, 0, At, B0); PG8_MMA(0, 1, At, B1); PG8_BAR; PG8_SCHED;
;             PG8_LDA(At, 0, 1); PG8_STAGE(PG8_SB(0, 0), b2, voffB); PG8_STAGE(PG8_SB(0, 1), b2 + hstepB, voffB); PG8_STAGE(PG8_SA(0, 0), a2, voffA);
;             PG8_WAIT_V(8); PG8_WAIT_L(0); PG8_BAR; PG8_MMA(1, 0, At, B0); PG8_MMA(1, 1, At, B1); PG8_BAR; PG8_SCHED;
.LBB0_984:
	s_ashr_i32 s15, s14, 31
	s_lshl_b64 s[16:17], s[14:15], 20
	v_readlane_b32 s18, v254, 36
	v_readlane_b32 s19, v254, 37
	s_add_u32 s16, s18, s16
	s_addc_u32 s17, s19, s17
	s_and_b64 s[18:19], s[0:1], exec
	s_cselect_b32 s15, s17, s23
	s_cselect_b32 s45, s16, s22
	s_ashr_i32 s13, s12, 31
	s_lshl_b64 s[18:19], s[12:13], 20
	s_add_u32 s18, s2, s18
	s_addc_u32 s19, s3, s19
	s_and_b64 s[26:27], s[0:1], exec
	s_cselect_b32 s13, s19, s25
	s_cselect_b32 s46, s18, s24
	s_add_u32 s22, s22, 0x80080
	s_addc_u32 s23, s23, 0
	s_add_u32 s47, s24, 0x100
	s_addc_u32 s48, s25, 0
	s_mov_b32 s49, -2
	ds_read_b128 v[150:153], v147
	ds_read_b128 v[154:157], v147 offset:1024
	ds_read_b128 v[158:161], v147 offset:2048
	ds_read_b128 v[162:165], v147 offset:3072
	ds_read_b128 v[166:169], v148
	ds_read_b128 v[170:173], v148 offset:1024
	ds_read_b128 v[174:177], v148 offset:2048
	ds_read_b128 v[178:181], v148 offset:3072
	s_add_u32 s24, s22, 0xfff80080
	s_addc_u32 s25, s23, -1
	s_cmp_eq_u32 s49, 28
	s_cselect_b32 s27, s15, s25
	s_cselect_b32 s26, s45, s24
	s_cselect_b32 s25, s13, s48
	s_cselect_b32 s24, s46, s47
	v_lshl_add_u64 v[190:191], s[22:23], 0, v[136:137]
	s_add_i32 m0, s21, 0xc000
	ds_read_b128 v[182:185], v149
	ds_read_b128 v[186:189], v149 offset:1024
	ds_read_b128 v[194:197], v149 offset:2048
	ds_read_b128 v[198:201], v149 offset:3072
	ds_read_b128 v[202:205], v149 offset:4096
	ds_read_b128 v[206:209], v149 offset:5120
	ds_read_b128 v[210:213], v149 offset:6144
	ds_read_b128 v[214:217], v149 offset:7168
	global_load_lds_dwordx4 v[190:191], off
	v_lshl_add_u64 v[190:191], s[22:23], 0, v[138:139]
	s_add_i32 m0, s21, 0xe000
	s_nop 0
	global_load_lds_dwordx4 v[190:191], off
	s_waitcnt vmcnt(8)
	s_waitcnt lgkmcnt(0)
	s_setprio 0
	s_barrier
	v_mfma_f32_16x16x32_bf16 v[124:127], v[150:153], v[182:185], 0
	v_mfma_f32_16x16x32_bf16 v[116:119], v[158:161], v[182:185], 0
	v_mfma_f32_16x16x32_bf16 v[108:111], v[150:153], v[194:197], 0
	v_mfma_f32_16x16x32_bf16 v[100:103], v[158:161], v[194:197], 0
	v_mfma_f32_16x16x32_bf16 v[92:95], v[150:153], v[202:205], 0
	v_mfma_f32_16x16x32_bf16 v[84:87], v[158:161], v[202:205], 0
	v_mfma_f32_16x16x32_bf16 v[76:79], v[150:153], v[210:213], 0
	v_mfma_f32_16x16x32_bf16 v[68:71], v[158:161], v[210:213], 0
	v_mfma_f32_16x16x32_bf16 v[124:127], v[154:157], v[186:189], v[124:127]
	v_mfma_f32_16x16x32_bf16 v[116:119], v[162:165], v[186:189], v[116:119]
	v_mfma_f32_16x16x32_bf16 v[108:111], v[154:157], v[198:201], v[108:111]
	v_mfma_f32_16x16x32_bf16 v[100:103], v[162:165], v[198:201], v[100:103]
	v_mfma_f32_16x16x32_bf16 v[92:95], v[154:157], v[206:209], v[92:95]
	v_mfma_f32_16x16x32_bf16 v[84:87], v[162:165], v[206:209], v[84:87]
	v_mfma_f32_16x16x32_bf16 v[76:79], v[154:157], v[214:217], v[76:79]
	v_mfma_f32_16x16x32_bf16 v[68:71], v[162:165], v[214:217], v[68:71]
	v_mfma_f32_16x16x32_bf16 v[120:123], v[166:169], v[182:185], 0
	v_mfma_f32_16x16x32_bf16 v[112:115], v[174:177], v[182:185], 0
	v_mfma_f32_16x16x32_bf16 v[104:107], v[166:169], v[194:197], 0
	v_mfma_f32_16x16x32_bf16 v[96:99], v[174:177], v[194:197], 0
	v_mfma_f32_16x16x32_bf16 v[88:91], v[166:169], v[202:205], 0
	v_mfma_f32_16x16x32_bf16 v[80:83], v[174:177], v[202:205], 0
	v_mfma_f32_16x16x32_bf16 v[72:75], v[166:169], v[210:213], 0
	v_mfma_f32_16x16x32_bf16 v[64:67], v[174:177], v[210:213], 0
	v_mfma_f32_16x16x32_bf16 v[120:123], v[170:173], v[186:189], v[120:123]
	v_mfma_f32_16x16x32_bf16 v[112:115], v[178:181], v[186:189], v[112:115]
	v_mfma_f32_16x16x32_bf16 v[104:107], v[170:173], v[198:201], v[104:107]
	v_mfma_f32_16x16x32_bf16 v[96:99], v[178:181], v[198:201], v[96:99]
	v_mfma_f32_16x16x32_bf16 v[88:91], v[170:173], v[206:209], v[88:91]
	v_mfma_f32_16x16x32_bf16 v[80:83], v[178:181], v[206:209], v[80:83]
	v_mfma_f32_16x16x32_bf16 v[72:75], v[170:173], v[214:217], v[72:75]
	v_mfma_f32_16x16x32_bf16 v[64:67], v[178:181], v[214:217], v[64:67]
	s_barrier
	s_setprio 1
	s_add_i32 s50, s42, s28
	v_lshl_add_u64 v[190:191], s[24:25], 0, v[130:131]
	s_mov_b32 m0, s50
	ds_read_b128 v[182:185], v149 offset:16384
	ds_read_b128 v[186:189], v149 offset:17408
	ds_read_b128 v[194:197], v149 offset:18432
	ds_read_b128 v[198:201], v149 offset:19456
	ds_read_b128 v[202:205], v149 offset:20480
	ds_read_b128 v[206:209], v149 offset:21504
	ds_read_b128 v[210:213], v149 offset:22528
	ds_read_b128 v[214:217], v149 offset:23552
	global_load_lds_dwordx4 v[190:191], off
	s_add_i32 m0, s50, 0x2000
	s_add_u32 s50, s24, 0x80000
	v_lshl_add_u64 v[218:219], s[24:25], 0, v[134:135]
	s_addc_u32 s51, s25, 0
	s_add_i32 s52, s43, s28
	global_load_lds_dwordx4 v[218:219], off
	v_lshl_add_u64 v[220:221], s[50:51], 0, v[130:131]
	s_mov_b32 m0, s52
	v_lshl_add_u64 v[222:223], s[26:27], 0, v[132:133]
	global_load_lds_dwordx4 v[220:221], off
	v_lshl_add_u64 v[220:221], s[50:51], 0, v[134:135]
	s_add_i32 m0, s52, 0x2000
	s_nop 0
	global_load_lds_dwordx4 v[220:221], off
	v_lshl_add_u64 v[220:221], s[26:27], 0, v[128:129]
	s_mov_b32 m0, s21
	s_nop 0
	global_load_lds_dwordx4 v[220:221], off
	s_mov_b32 m0, s31
	s_nop 0
	global_load_lds_dwordx4 v[222:223], off
	s_waitcnt vmcnt(8)
	s_waitcnt lgkmcnt(0)
	s_setprio 0
	s_barrier
; #define PG8_STAGE(bufoff, gbase, voff) do { _Pragma("unroll") for (int _i = 0; _i < 2; ++_i) \
;         __builtin_amdgcn_global_load_lds((const unsigned*)((const char*)(gbase) + (voff)[_i]), (LAS unsigned*)(lds + (bufoff) + ldsw + _i * 8192), 16, 0, 0); } while (0)
; #define PG8_LDA(dst, b, h) do { _Pragma("unroll") for (int m = 0; m < 4; ++m) _Pragma("unroll") for (int k = 0; k < 2; ++k) dst[m][k] = *(const LAS bf16x8*)(lds + PG8_SA(b, h) + aoff + m * 2048 + k * 1024); } while (0)
; #define PG8_LDB(dst, b, h) do { _Pragma("unroll") for (int n = 0; n < 2; ++n) _Pragma("unroll") for (int k = 0; k < 2; ++k) dst[n][k] = *(const LAS bf16x8*)(lds + PG8_SB(b, h) + boff + n * 2048 + k * 1024); } while (0)
; #define PG8_MMA(ai, bj, At, Bt) do { __builtin_amdgcn_s_setprio(1); _Pragma("unroll") for (int m = 0; m < 4; ++m) _Pragma("unroll") for (int n = 0; n < 2; ++n) _Pragma("unroll") for (int k = 0; k < 2; ++k) \
;         acc[ai][bj][m][n] = __builtin_amdgcn_mfma_f32_16x16x32_bf16(Bt[n][k], At[m][k], acc[ai][bj][m][n], 0, 0, 0); __builtin_amdgcn_s_setprio(0); } while (0)
; #define PG8_WAIT_V(n) asm volatile("s_waitcnt vmcnt(" #n ")" ::: "memory")
; #define PG8_WAIT_L(n) asm volatile("s_waitcnt lgkmcnt(" #n ")" ::: "memory")
; #define PG8_BAR __builtin_amdgcn_s_barrier()
; #define PG8_SCHED __builtin_amdgcn_sched_barrier(0)
; template <class Epi, class Sched = StaticOrder, class EpiSub = NoSub, bool FAST = false>
; __device__ __forceinline__ void gemm_phase(LAS unsigned char* lds, const Gemm g, const Sched& S, const Epi& E, const EpiSub& ES = EpiSub()) {
;     ...
;             PG8_LDA(At, 0, 1); PG8_STAGE(PG8_SB(0, 0), b2, voffB); PG8_STAGE(PG8_SB(0, 1), b2 + hstepB, voffB); PG8_STAGE(PG8_SA(0, 0), a2, voffA);
;             PG8_WAIT_V(8); PG8_WAIT_L(0); PG8_BAR; PG8_MMA(1, 0, At, B0); PG8_MMA(1, 1, At, B1); PG8_BAR; PG8_SCHED;
;             PG8_LDB(B0, 1, 0); PG8_LDB(B1, 1, 1); PG8_SCHED; PG8_LDA(At, 1, 0); PG8_STAGE(PG8_SA(0, 1), a2 + hstepA, voffA);
;             PG8_WAIT_V(8); PG8_WAIT_L(0); PG8_BAR; PG8_MMA(0, 0, At, B0); PG8_MMA(0, 1, At, B1); PG8_BAR; PG8_SCHED;
	v_mfma_f32_16x16x32_bf16 v[60:63], v[150:153], v[182:185], 0
	v_mfma_f32_16x16x32_bf16 v[52:55], v[158:161], v[182:185], 0
	v_mfma_f32_16x16x32_bf16 v[44:47], v[150:153], v[194:197], 0
	v_mfma_f32_16x16x32_bf16 v[36:39], v[158:161], v[194:197], 0
	v_mfma_f32_16x16x32_bf16 v[28:31], v[150:153], v[202:205], 0
	v_mfma_f32_16x16x32_bf16 v[20:23], v[158:161], v[202:205], 0
	v_mfma_f32_16x16x32_bf16 v[12:15], v[150:153], v[210:213], 0
	v_mfma_f32_16x16x32_bf16 v[4:7], v[158:161], v[210:213], 0
	v_mfma_f32_16x16x32_bf16 v[60:63], v[154:157], v[186:189], v[60:63]
	v_mfma_f32_16x16x32_bf16 v[52:55], v[162:165], v[186:189], v[52:55]
	v_mfma_f32_16x16x32_bf16 v[44:47], v[154:157], v[198:201], v[44:47]
	v_mfma_f32_16x16x32_bf16 v[36:39], v[162:165], v[198:201], v[36:39]
	v_mfma_f32_16x16x32_bf16 v[28:31], v[154:157], v[206:209], v[28:31]
	v_mfma_f32_16x16x32_bf16 v[20:23], v[162:165], v[206:209], v[20:23]
	v_mfma_f32_16x16x32_bf16 v[12:15], v[154:157], v[214:217], v[12:15]
	v_mfma_f32_16x16x32_bf16 v[4:7], v[162:165], v[214:217], v[4:7]
	v_mfma_f32_16x16x32_bf16 v[56:59], v[166:169], v[182:185], 0
	v_mfma_f32_16x16x32_bf16 v[48:51], v[174:177], v[182:185], 0
	v_mfma_f32_16x16x32_bf16 v[40:43], v[166:169], v[194:197], 0
	v_mfma_f32_16x16x32_bf16 v[32:35], v[174:177], v[194:197], 0
	v_mfma_f32_16x16x32_bf16 v[24:27], v[166:169], v[202:205], 0
	v_mfma_f32_16x16x32_bf16 v[16:19], v[174:177], v[202:205], 0
	v_mfma_f32_16x16x32_bf16 v[8:11], v[166:169], v[210:213], 0
	v_mfma_f32_16x16x32_bf16 v[0:3], v[174:177], v[210:213], 0
	v_mfma_f32_16x16x32_bf16 v[56:59], v[170:173], v[186:189], v[56:59]
	v_mfma_f32_16x16x32_bf16 v[48:51], v[178:181], v[186:189], v[48:51]
	v_mfma_f32_16x16x32_bf16 v[40:43], v[170:173], v[198:201], v[40:43]
	v_mfma_f32_16x16x32_bf16 v[32:35], v[178:181], v[198:201], v[32:35]
	v_mfma_f32_16x16x32_bf16 v[24:27], v[170:173], v[206:209], v[24:27]
	v_mfma_f32_16x16x32_bf16 v[16:19], v[178:181], v[206:209], v[16:19]
	v_mfma_f32_16x16x32_bf16 v[8:11], v[170:173], v[214:217], v[8:11]
	v_mfma_f32_16x16x32_bf16 v[0:3], v[178:181], v[214:217], v[0:3]
	s_barrier
	s_setprio 1
	s_add_i32 s50, 0, 0x18000
	s_add_i32 s51, 0, 0x1c000
	v_add_u32_e32 v162, s50, v145
	v_add_u32_e32 v178, s51, v145
	ds_read_b128 v[150:153], v162
	ds_read_b128 v[154:157], v162 offset:1024
	ds_read_b128 v[158:161], v162 offset:2048
	ds_read_b128 v[162:165], v162 offset:3072
	ds_read_b128 v[166:169], v178
	ds_read_b128 v[170:173], v178 offset:1024
	ds_read_b128 v[174:177], v178 offset:2048
	ds_read_b128 v[178:181], v178 offset:3072
	s_add_u32 s26, s26, 0x80000
	s_addc_u32 s27, s27, 0
	s_mov_b32 m0, s36
	v_lshl_add_u64 v[224:225], s[26:27], 0, v[128:129]
	ds_read_b128 v[182:185], v149 offset:32768
	ds_read_b128 v[186:189], v149 offset:33792
	ds_read_b128 v[194:197], v149 offset:34816
	ds_read_b128 v[198:201], v149 offset:35840
	ds_read_b128 v[202:205], v149 offset:36864
	ds_read_b128 v[206:209], v149 offset:37888
	ds_read_b128 v[210:213], v149 offset:38912
	ds_read_b128 v[214:217], v149 offset:39936
	global_load_lds_dwordx4 v[224:225], off
	v_lshl_add_u64 v[224:225], s[26:27], 0, v[132:133]
	s_mov_b32 m0, s37
	s_nop 0
	global_load_lds_dwordx4 v[224:225], off
	s_waitcnt vmcnt(8)
	s_waitcnt lgkmcnt(0)
	s_setprio 0
	s_barrier
	v_mfma_f32_16x16x32_bf16 v[124:127], v[150:153], v[182:185], v[124:127]
	v_mfma_f32_16x16x32_bf16 v[116:119], v[158:161], v[182:185], v[116:119]
	v_mfma_f32_16x16x32_bf16 v[108:111], v[150:153], v[194:197], v[108:111]
	v_mfma_f32_16x16x32_bf16 v[100:103], v[158:161], v[194:197], v[100:103]
	v_mfma_f32_16x16x32_bf16 v[92:95], v[150:153], v[202:205], v[92:95]
	v_mfma_f32_16x16x32_bf16 v[84:87], v[158:161], v[202:205], v[84:87]
	v_mfma_f32_16x16x32_bf16 v[76:79], v[150:153], v[210:213], v[76:79]
	v_mfma_f32_16x16x32_bf16 v[68:71], v[158:161], v[210:213], v[68:71]
	v_mfma_f32_16x16x32_bf16 v[124:127], v[154:157], v[186:189], v[124:127]
	v_mfma_f32_16x16x32_bf16 v[116:119], v[162:165], v[186:189], v[116:119]
	v_mfma_f32_16x16x32_bf16 v[108:111], v[154:157], v[198:201], v[108:111]
	v_mfma_f32_16x16x32_bf16 v[100:103], v[162:165], v[198:201], v[100:103]
	v_mfma_f32_16x16x32_bf16 v[92:95], v[154:157], v[206:209], v[92:95]
	v_mfma_f32_16x16x32_bf16 v[84:87], v[162:165], v[206:209], v[84:87]
	v_mfma_f32_16x16x32_bf16 v[76:79], v[154:157], v[214:217], v[76:79]
	v_mfma_f32_16x16x32_bf16 v[68:71], v[162:165], v[214:217], v[68:71]
	v_mfma_f32_16x16x32_bf16 v[120:123], v[166:169], v[182:185], v[120:123]
	v_mfma_f32_16x16x32_bf16 v[112:115], v[174:177], v[182:185], v[112:115]
	v_mfma_f32_16x16x32_bf16 v[104:107], v[166:169], v[194:197], v[104:107]
	v_mfma_f32_16x16x32_bf16 v[96:99], v[174:177], v[194:197], v[96:99]
	v_mfma_f32_16x16x32_bf16 v[88:91], v[166:169], v[202:205], v[88:91]
	v_mfma_f32_16x16x32_bf16 v[80:83], v[174:177], v[202:205], v[80:83]
	v_mfma_f32_16x16x32_bf16 v[72:75], v[166:169], v[210:213], v[72:75]
	v_mfma_f32_16x16x32_bf16 v[64:67], v[174:177], v[210:213], v[64:67]
	v_mfma_f32_16x16x32_bf16 v[120:123], v[170:173], v[186:189], v[120:123]
	v_mfma_f32_16x16x32_bf16 v[112:115], v[178:181], v[186:189], v[112:115]
	v_mfma_f32_16x16x32_bf16 v[104:107], v[170:173], v[198:201], v[104:107]
	v_mfma_f32_16x16x32_bf16 v[96:99], v[178:181], v[198:201], v[96:99]
	v_mfma_f32_16x16x32_bf16 v[88:91], v[170:173], v[206:209], v[88:91]
	v_mfma_f32_16x16x32_bf16 v[80:83], v[178:181], v[206:209], v[80:83]
	v_mfma_f32_16x16x32_bf16 v[72:75], v[170:173], v[214:217], v[72:75]
	v_mfma_f32_16x16x32_bf16 v[64:67], v[178:181], v[214:217], v[64:67]
	s_barrier
; #define PG8_STAGE(bufoff, gbase, voff) do { _Pragma("unroll") for (int _i = 0; _i < 2; ++_i) \
;         __builtin_amdgcn_global_load_lds((const unsigned*)((const char*)(gbase) + (voff)[_i]), (LAS unsigned*)(lds + (bufoff) + ldsw + _i * 8192), 16, 0, 0); } while (0)
; #define PG8_LDA(dst, b, h) do { _Pragma("unroll") for (int m = 0; m < 4; ++m) _Pragma("unroll") for (int k = 0; k < 2; ++k) dst[m][k] = *(const LAS bf16x8*)(lds + PG8_SA(b, h) + aoff + m * 2048 + k * 1024); } while (0)
; #define PG8_LDB(dst, b, h) do { _Pragma("unroll") for (int n = 0; n < 2; ++n) _Pragma("unroll") for (int k = 0; k < 2; ++k) dst[n][k] = *(const LAS bf16x8*)(lds + PG8_SB(b, h) + boff + n * 2048 + k * 1024); } while (0)
; template <class Epi, class Sched = StaticOrder, class EpiSub = NoSub, bool FAST = false>
; __device__ __forceinline__ void gemm_phase(LAS unsigned char* lds, const Gemm g, const Sched& S, const Epi& E, const EpiSub& ES = EpiSub()) {
;     ...
;         for (int t = 0; t < nt; t += 2) {
;             const bool last = (t == nt - 2);
;             const char* a1 = cA + (size_t)(t + 1) * kstep;
;             const char* a2 = last ? nA : cA + (size_t)(t + 2) * kstep; const char* b2 = last ? nB : cB + (size_t)(t + 2) * kstep;
;             const char* a3 = a2 + kstep; const char* b3 = b2 + kstep;
;             if constexpr (FAST && PG8_SP2) {
;             PG8_LDB(B0, 0, 0); PG8_LDB(B1, 0, 1); PG8_SCHED; PG8_LDA(At, 0, 0); PG8_STAGE(PG8_SA(1, 1), a1 + hstepA, voffA);
;             PG8_WAIT_V(8); PG8_WAIT_L(0); PG8_BAR; PG8_MMA(0, 0, At, B0); PG8_MMA(0, 1, At, B1); PG8_BAR; PG8_SCHED;
;             PG8_LDA(At, 0, 1); PG8_STAGE(PG8_SB(0, 0), b2, voffB); PG8_STAGE(PG8_SB(0, 1), b2 + hstepB, voffB); PG8_STAGE(PG8_SA(0, 0), a2, voffA);
;             PG8_WAIT_V(8); PG8_WAIT_L(0); PG8_BAR; PG8_MMA(1, 0, At, B0); PG8_MMA(1, 1, At, B1); PG8_BAR; PG8_SCHED;
;             PG8_LDB(B0, 1, 0); PG8_LDB(B1, 1, 1); PG8_SCHED; PG8_LDA(At, 1, 0); PG8_STAGE(PG8_SA(0, 1), a2 + hstepA, voffA);
;             PG8_WAIT_V(8); PG8_WAIT_L(0); PG8_BAR; PG8_MMA(0, 0, At, B0); PG8_MMA(0, 1, At, B1); PG8_BAR; PG8_SCHED;
;             PG8_LDA(At, 1, 1); PG8_STAGE(PG8_SB(1, 0), b3, voffB); PG8_STAGE(PG8_SB(1, 1), b3 + hstepB, voffB); PG8_STAGE(PG8_SA(1, 0), a3, voffA);
;             PG8_WAIT_V(8); PG8_WAIT_L(0); PG8_BAR; PG8_MMA(1, 0, At, B0); PG8_MMA(1, 1, At, B1); PG8_BAR; PG8_SCHED;
	s_setprio 1
	s_add_i32 s26, s50, s28
	v_lshl_add_u64 v[190:191], v[190:191], 0, s[8:9]
	s_mov_b32 m0, s26
	ds_read_b128 v[182:185], v149 offset:49152
	ds_read_b128 v[186:189], v149 offset:50176
	ds_read_b128 v[194:197], v149 offset:51200
	ds_read_b128 v[198:201], v149 offset:52224
	ds_read_b128 v[202:205], v149 offset:53248
	ds_read_b128 v[206:209], v149 offset:54272
	ds_read_b128 v[210:213], v149 offset:55296
	ds_read_b128 v[214:217], v149 offset:56320
	global_load_lds_dwordx4 v[190:191], off
	s_add_i32 m0, s26, 0x2000
	s_add_u32 s24, s24, 0x80080
	v_lshl_add_u64 v[190:191], v[218:219], 0, s[8:9]
	s_addc_u32 s25, s25, 0
	s_add_i32 s26, s51, s28
	global_load_lds_dwordx4 v[190:191], off
	v_lshl_add_u64 v[190:191], s[24:25], 0, v[130:131]
	s_mov_b32 m0, s26
	s_nop 0
	global_load_lds_dwordx4 v[190:191], off
	v_lshl_add_u64 v[190:191], s[24:25], 0, v[134:135]
	s_add_i32 m0, s26, 0x2000
	s_nop 0
	global_load_lds_dwordx4 v[190:191], off
	v_lshl_add_u64 v[190:191], v[220:221], 0, s[8:9]
	s_mov_b32 m0, s40
	s_nop 0
	global_load_lds_dwordx4 v[190:191], off
	v_lshl_add_u64 v[190:191], v[222:223], 0, s[8:9]
	s_mov_b32 m0, s41
	s_nop 0
	global_load_lds_dwordx4 v[190:191], off
	s_waitcnt vmcnt(8)
	s_waitcnt lgkmcnt(0)
	s_setprio 0
	s_barrier
	v_mfma_f32_16x16x32_bf16 v[60:63], v[150:153], v[182:185], v[60:63]
	v_mfma_f32_16x16x32_bf16 v[52:55], v[158:161], v[182:185], v[52:55]
	v_mfma_f32_16x16x32_bf16 v[44:47], v[150:153], v[194:197], v[44:47]
	v_mfma_f32_16x16x32_bf16 v[36:39], v[158:161], v[194:197], v[36:39]
	v_mfma_f32_16x16x32_bf16 v[28:31], v[150:153], v[202:205], v[28:31]
	v_mfma_f32_16x16x32_bf16 v[20:23], v[158:161], v[202:205], v[20:23]
	v_mfma_f32_16x16x32_bf16 v[12:15], v[150:153], v[210:213], v[12:15]
	v_mfma_f32_16x16x32_bf16 v[4:7], v[158:161], v[210:213], v[4:7]
	v_mfma_f32_16x16x32_bf16 v[60:63], v[154:157], v[186:189], v[60:63]
	v_mfma_f32_16x16x32_bf16 v[52:55], v[162:165], v[186:189], v[52:55]
	v_mfma_f32_16x16x32_bf16 v[44:47], v[154:157], v[198:201], v[44:47]
	v_mfma_f32_16x16x32_bf16 v[36:39], v[162:165], v[198:201], v[36:39]
	v_mfma_f32_16x16x32_bf16 v[28:31], v[154:157], v[206:209], v[28:31]
	v_mfma_f32_16x16x32_bf16 v[20:23], v[162:165], v[206:209], v[20:23]
	v_mfma_f32_16x16x32_bf16 v[12:15], v[154:157], v[214:217], v[12:15]
	v_mfma_f32_16x16x32_bf16 v[4:7], v[162:165], v[214:217], v[4:7]
	v_mfma_f32_16x16x32_bf16 v[56:59], v[166:169], v[182:185], v[56:59]
	v_mfma_f32_16x16x32_bf16 v[48:51], v[174:177], v[182:185], v[48:51]
	v_mfma_f32_16x16x32_bf16 v[40:43], v[166:169], v[194:197], v[40:43]
	v_mfma_f32_16x16x32_bf16 v[32:35], v[174:177], v[194:197], v[32:35]
	v_mfma_f32_16x16x32_bf16 v[24:27], v[166:169], v[202:205], v[24:27]
	v_mfma_f32_16x16x32_bf16 v[16:19], v[174:177], v[202:205], v[16:19]
	v_mfma_f32_16x16x32_bf16 v[8:11], v[166:169], v[210:213], v[8:11]
	v_mfma_f32_16x16x32_bf16 v[0:3], v[174:177], v[210:213], v[0:3]
	v_mfma_f32_16x16x32_bf16 v[56:59], v[170:173], v[186:189], v[56:59]
	v_mfma_f32_16x16x32_bf16 v[48:51], v[178:181], v[186:189], v[48:51]
	v_mfma_f32_16x16x32_bf16 v[40:43], v[170:173], v[198:201], v[40:43]
	v_mfma_f32_16x16x32_bf16 v[32:35], v[178:181], v[198:201], v[32:35]
	v_mfma_f32_16x16x32_bf16 v[24:27], v[170:173], v[206:209], v[24:27]
	v_mfma_f32_16x16x32_bf16 v[16:19], v[178:181], v[206:209], v[16:19]
	v_mfma_f32_16x16x32_bf16 v[8:11], v[170:173], v[214:217], v[8:11]
	v_mfma_f32_16x16x32_bf16 v[0:3], v[178:181], v[214:217], v[0:3]
	s_barrier
	s_setprio 1
	s_add_i32 s49, s49, 2
	s_add_u32 s22, s22, 0x100
	s_addc_u32 s23, s23, 0
	s_add_u32 s47, s47, 0x100
	s_addc_u32 s48, s48, 0
	s_cmp_gt_u32 s49, 29
	s_cbranch_scc1 .Lkpeel_985_exit
.LBB0_985:
	ds_read_b128 v[150:153], v147
	ds_read_b128 v[154:157], v147 offset:1024
	ds_read_b128 v[158:161], v147 offset:2048
	ds_read_b128 v[162:165], v147 offset:3072
	ds_read_b128 v[166:169], v148
	ds_read_b128 v[170:173], v148 offset:1024
	ds_read_b128 v[174:177], v148 offset:2048
	ds_read_b128 v[178:181], v148 offset:3072
	s_add_u32 s24, s22, 0xfff80080
	s_addc_u32 s25, s23, -1
	s_cmp_eq_u32 s49, 28
	s_cselect_b32 s27, s15, s25
	s_cselect_b32 s26, s45, s24
	s_cselect_b32 s25, s13, s48
	s_cselect_b32 s24, s46, s47
	v_lshl_add_u64 v[190:191], s[22:23], 0, v[136:137]
	s_add_i32 m0, s21, 0xc000
	ds_read_b128 v[182:185], v149
	ds_read_b128 v[186:189], v149 offset:1024
	ds_read_b128 v[194:197], v149 offset:2048
	ds_read_b128 v[198:201], v149 offset:3072
	ds_read_b128 v[202:205], v149 offset:4096
	ds_read_b128 v[206:209], v149 offset:5120
	ds_read_b128 v[210:213], v149 offset:6144
	ds_read_b128 v[214:217], v149 offset:7168
	global_load_lds_dwordx4 v[190:191], off
	v_lshl_add_u64 v[190:191], s[22:23], 0, v[138:139]
	s_add_i32 m0, s21, 0xe000
	s_nop 0
	global_load_lds_dwordx4 v[190:191], off
	s_waitcnt vmcnt(8)
	s_waitcnt lgkmcnt(0)
	s_setprio 0
	s_barrier
; #define PG8_STAGE(bufoff, gbase, voff) do { _Pragma("unroll") for (int _i = 0; _i < 2; ++_i) \
;         __builtin_amdgcn_global_load_lds((const unsigned*)((const char*)(gbase) + (voff)[_i]), (LAS unsigned*)(lds + (bufoff) + ldsw + _i * 8192), 16, 0, 0); } while (0)
; #define PG8_LDA(dst, b, h) do { _Pragma("unroll") for (int m = 0; m < 4; ++m) _Pragma("unroll") for (int k = 0; k < 2; ++k) dst[m][k] = *(const LAS bf16x8*)(lds + PG8_SA(b, h) + aoff + m * 2048 + k * 1024); } while (0)
; #define PG8_LDB(dst, b, h) do { _Pragma("unroll") for (int n = 0; n < 2; ++n) _Pragma("unroll") for (int k = 0; k < 2; ++k) dst[n][k] = *(const LAS bf16x8*)(lds + PG8_SB(b, h) + boff + n * 2048 + k * 1024); } while (0)
; #define PG8_MMA(ai, bj, At, Bt) do { __builtin_amdgcn_s_setprio(1); _Pragma("unroll") for (int m = 0; m < 4; ++m) _Pragma("unroll") for (int n = 0; n < 2; ++n) _Pragma("unroll") for (int k = 0; k < 2; ++k) \
;         acc[ai][bj][m][n] = __builtin_amdgcn_mfma_f32_16x16x32_bf16(Bt[n][k], At[m][k], acc[ai][bj][m][n], 0, 0, 0); __builtin_amdgcn_s_setprio(0); } while (0)
; #define PG8_WAIT_V(n) asm volatile("s_waitcnt vmcnt(" #n ")" ::: "memory")
; #define PG8_WAIT_L(n) asm volatile("s_waitcnt lgkmcnt(" #n ")" ::: "memory")
; #define PG8_BAR __builtin_amdgcn_s_barrier()
; #define PG8_SCHED __builtin_amdgcn_sched_barrier(0)
; template <class Epi, class Sched = StaticOrder, class EpiSub = NoSub, bool FAST = false>
; __device__ __forceinline__ void gemm_phase(LAS unsigned char* lds, const Gemm g, const Sched& S, const Epi& E, const EpiSub& ES = EpiSub()) {
;     ...
;             PG8_LDB(B0, 0, 0); PG8_LDB(B1, 0, 1); PG8_SCHED; PG8_LDA(At, 0, 0); PG8_STAGE(PG8_SA(1, 1), a1 + hstepA, voffA);
;             PG8_WAIT_V(8); PG8_WAIT_L(0); PG8_BAR; PG8_MMA(0, 0, At, B0); PG8_MMA(0, 1, At, B1); PG8_BAR; PG8_SCHED;
;             PG8_LDA(At, 0, 1); PG8_STAGE(PG8_SB(0, 0), b2, voffB); PG8_STAGE(PG8_SB(0, 1), b2 + hstepB, voffB); PG8_STAGE(PG8_SA(0, 0), a2, voffA);
;             PG8_WAIT_V(8); PG8_WAIT_L(0); PG8_BAR; PG8_MMA(1, 0, At, B0); PG8_MMA(1, 1, At, B1); PG8_BAR; PG8_SCHED;
	v_mfma_f32_16x16x32_bf16 v[124:127], v[150:153], v[182:185], v[124:127]
	v_mfma_f32_16x16x32_bf16 v[116:119], v[158:161], v[182:185], v[116:119]
	v_mfma_f32_16x16x32_bf16 v[108:111], v[150:153], v[194:197], v[108:111]
	v_mfma_f32_16x16x32_bf16 v[100:103], v[158:161], v[194:197], v[100:103]
	v_mfma_f32_16x16x32_bf16 v[92:95], v[150:153], v[202:205], v[92:95]
	v_mfma_f32_16x16x32_bf16 v[84:87], v[158:161], v[202:205], v[84:87]
	v_mfma_f32_16x16x32_bf16 v[76:79], v[150:153], v[210:213], v[76:79]
	v_mfma_f32_16x16x32_bf16 v[68:71], v[158:161], v[210:213], v[68:71]
	v_mfma_f32_16x16x32_bf16 v[124:127], v[154:157], v[186:189], v[124:127]
	v_mfma_f32_16x16x32_bf16 v[116:119], v[162:165], v[186:189], v[116:119]
	v_mfma_f32_16x16x32_bf16 v[108:111], v[154:157], v[198:201], v[108:111]
	v_mfma_f32_16x16x32_bf16 v[100:103], v[162:165], v[198:201], v[100:103]
	v_mfma_f32_16x16x32_bf16 v[92:95], v[154:157], v[206:209], v[92:95]
	v_mfma_f32_16x16x32_bf16 v[84:87], v[162:165], v[206:209], v[84:87]
	v_mfma_f32_16x16x32_bf16 v[76:79], v[154:157], v[214:217], v[76:79]
	v_mfma_f32_16x16x32_bf16 v[68:71], v[162:165], v[214:217], v[68:71]
	v_mfma_f32_16x16x32_bf16 v[120:123], v[166:169], v[182:185], v[120:123]
	v_mfma_f32_16x16x32_bf16 v[112:115], v[174:177], v[182:185], v[112:115]
	v_mfma_f32_16x16x32_bf16 v[104:107], v[166:169], v[194:197], v[104:107]
	v_mfma_f32_16x16x32_bf16 v[96:99], v[174:177], v[194:197], v[96:99]
	v_mfma_f32_16x16x32_bf16 v[88:91], v[166:169], v[202:205], v[88:91]
	v_mfma_f32_16x16x32_bf16 v[80:83], v[174:177], v[202:205], v[80:83]
	v_mfma_f32_16x16x32_bf16 v[72:75], v[166:169], v[210:213], v[72:75]
	v_mfma_f32_16x16x32_bf16 v[64:67], v[174:177], v[210:213], v[64:67]
	v_mfma_f32_16x16x32_bf16 v[120:123], v[170:173], v[186:189], v[120:123]
	v_mfma_f32_16x16x32_bf16 v[112:115], v[178:181], v[186:189], v[112:115]
	v_mfma_f32_16x16x32_bf16 v[104:107], v[170:173], v[198:201], v[104:107]
	v_mfma_f32_16x16x32_bf16 v[96:99], v[178:181], v[198:201], v[96:99]
	v_mfma_f32_16x16x32_bf16 v[88:91], v[170:173], v[206:209], v[88:91]
	v_mfma_f32_16x16x32_bf16 v[80:83], v[178:181], v[206:209], v[80:83]
	v_mfma_f32_16x16x32_bf16 v[72:75], v[170:173], v[214:217], v[72:75]
	v_mfma_f32_16x16x32_bf16 v[64:67], v[178:181], v[214:217], v[64:67]
	s_barrier
	s_setprio 1
	s_add_i32 s50, s42, s28
	v_lshl_add_u64 v[190:191], s[24:25], 0, v[130:131]
	s_mov_b32 m0, s50
	ds_read_b128 v[182:185], v149 offset:16384
	ds_read_b128 v[186:189], v149 offset:17408
	ds_read_b128 v[194:197], v149 offset:18432
	ds_read_b128 v[198:201], v149 offset:19456
	ds_read_b128 v[202:205], v149 offset:20480
	ds_read_b128 v[206:209], v149 offset:21504
	ds_read_b128 v[210:213], v149 offset:22528
	ds_read_b128 v[214:217], v149 offset:23552
	global_load_lds_dwordx4 v[190:191], off
	s_add_i32 m0, s50, 0x2000
	s_add_u32 s50, s24, 0x80000
	v_lshl_add_u64 v[218:219], s[24:25], 0, v[134:135]
	s_addc_u32 s51, s25, 0
	s_add_i32 s52, s43, s28
	global_load_lds_dwordx4 v[218:219], off
	v_lshl_add_u64 v[220:221], s[50:51], 0, v[130:131]
	s_mov_b32 m0, s52
	v_lshl_add_u64 v[222:223], s[26:27], 0, v[132:133]
	global_load_lds_dwordx4 v[220:221], off
	v_lshl_add_u64 v[220:221], s[50:51], 0, v[134:135]
	s_add_i32 m0, s52, 0x2000
	s_nop 0
	global_load_lds_dwordx4 v[220:221], off
	v_lshl_add_u64 v[220:221], s[26:27], 0, v[128:129]
	s_mov_b32 m0, s21
	s_nop 0
	global_load_lds_dwordx4 v[220:221], off
	s_mov_b32 m0, s31
	s_nop 0
	global_load_lds_dwordx4 v[222:223], off
	s_waitcnt vmcnt(8)
	s_waitcnt lgkmcnt(0)
	s_setprio 0
	s_barrier
	v_mfma_f32_16x16x32_bf16 v[60:63], v[150:153], v[182:185], v[60:63]
	v_mfma_f32_16x16x32_bf16 v[52:55], v[158:161], v[182:185], v[52:55]
	v_mfma_f32_16x16x32_bf16 v[44:47], v[150:153], v[194:197], v[44:47]
	v_mfma_f32_16x16x32_bf16 v[36:39], v[158:161], v[194:197], v[36:39]
	v_mfma_f32_16x16x32_bf16 v[28:31], v[150:153], v[202:205], v[28:31]
	v_mfma_f32_16x16x32_bf16 v[20:23], v[158:161], v[202:205], v[20:23]
	v_mfma_f32_16x16x32_bf16 v[12:15], v[150:153], v[210:213], v[12:15]
	v_mfma_f32_16x16x32_bf16 v[4:7], v[158:161], v[210:213], v[4:7]
	v_mfma_f32_16x16x32_bf16 v[60:63], v[154:157], v[186:189], v[60:63]
	v_mfma_f32_16x16x32_bf16 v[52:55], v[162:165], v[186:189], v[52:55]
	v_mfma_f32_16x16x32_bf16 v[44:47], v[154:157], v[198:201], v[44:47]
	v_mfma_f32_16x16x32_bf16 v[36:39], v[162:165], v[198:201], v[36:39]
	v_mfma_f32_16x16x32_bf16 v[28:31], v[154:157], v[206:209], v[28:31]
	v_mfma_f32_16x16x32_bf16 v[20:23], v[162:165], v[206:209], v[20:23]
	v_mfma_f32_16x16x32_bf16 v[12:15], v[154:157], v[214:217], v[12:15]
	v_mfma_f32_16x16x32_bf16 v[4:7], v[162:165], v[214:217], v[4:7]
	v_mfma_f32_16x16x32_bf16 v[56:59], v[166:169], v[182:185], v[56:59]
	v_mfma_f32_16x16x32_bf16 v[48:51], v[174:177], v[182:185], v[48:51]
	v_mfma_f32_16x16x32_bf16 v[40:43], v[166:169], v[194:197], v[40:43]
	v_mfma_f32_16x16x32_bf16 v[32:35], v[174:177], v[194:197], v[32:35]
	v_mfma_f32_16x16x32_bf16 v[24:27], v[166:169], v[202:205], v[24:27]
	v_mfma_f32_16x16x32_bf16 v[16:19], v[174:177], v[202:205], v[16:19]
	v_mfma_f32_16x16x32_bf16 v[8:11], v[166:169], v[210:213], v[8:11]
	v_mfma_f32_16x16x32_bf16 v[0:3], v[174:177], v[210:213], v[0:3]
	v_mfma_f32_16x16x32_bf16 v[56:59], v[170:173], v[186:189], v[56:59]
	v_mfma_f32_16x16x32_bf16 v[48:51], v[178:181], v[186:189], v[48:51]
	v_mfma_f32_16x16x32_bf16 v[40:43], v[170:173], v[198:201], v[40:43]
	v_mfma_f32_16x16x32_bf16 v[32:35], v[178:181], v[198:201], v[32:35]
	v_mfma_f32_16x16x32_bf16 v[24:27], v[170:173], v[206:209], v[24:27]
	v_mfma_f32_16x16x32_bf16 v[16:19], v[178:181], v[206:209], v[16:19]
	v_mfma_f32_16x16x32_bf16 v[8:11], v[170:173], v[214:217], v[8:11]
	v_mfma_f32_16x16x32_bf16 v[0:3], v[178:181], v[214:217], v[0:3]
	s_barrier
; #define PG8_STAGE(bufoff, gbase, voff) do { _Pragma("unroll") for (int _i = 0; _i < 2; ++_i) \
;         __builtin_amdgcn_global_load_lds((const unsigned*)((const char*)(gbase) + (voff)[_i]), (LAS unsigned*)(lds + (bufoff) + ldsw + _i * 8192), 16, 0, 0); } while (0)
; #define PG8_LDA(dst, b, h) do { _Pragma("unroll") for (int m = 0; m < 4; ++m) _Pragma("unroll") for (int k = 0; k < 2; ++k) dst[m][k] = *(const LAS bf16x8*)(lds + PG8_SA(b, h) + aoff + m * 2048 + k * 1024); } while (0)
; #define PG8_LDB(dst, b, h) do { _Pragma("unroll") for (int n = 0; n < 2; ++n) _Pragma("unroll") for (int k = 0; k < 2; ++k) dst[n][k] = *(const LAS bf16x8*)(lds + PG8_SB(b, h) + boff + n * 2048 + k * 1024); } while (0)
; #define PG8_MMA(ai, bj, At, Bt) do { __builtin_amdgcn_s_setprio(1); _Pragma("unroll") for (int m = 0; m < 4; ++m) _Pragma("unroll") for (int n = 0; n < 2; ++n) _Pragma("unroll") for (int k = 0; k < 2; ++k) \
;         acc[ai][bj][m][n] = __builtin_amdgcn_mfma_f32_16x16x32_bf16(Bt[n][k], At[m][k], acc[ai][bj][m][n], 0, 0, 0); __builtin_amdgcn_s_setprio(0); } while (0)
; #define PG8_WAIT_V(n) asm volatile("s_waitcnt vmcnt(" #n ")" ::: "memory")
; #define PG8_WAIT_L(n) asm volatile("s_waitcnt lgkmcnt(" #n ")" ::: "memory")
; #define PG8_BAR __builtin_amdgcn_s_barrier()
; #define PG8_SCHED __builtin_amdgcn_sched_barrier(0)
; template <class Epi, class Sched = StaticOrder, class EpiSub = NoSub, bool FAST = false>
; __device__ __forceinline__ void gemm_phase(LAS unsigned char* lds, const Gemm g, const Sched& S, const Epi& E, const EpiSub& ES = EpiSub()) {
;     ...
;             PG8_LDB(B0, 1, 0); PG8_LDB(B1, 1, 1); PG8_SCHED; PG8_LDA(At, 1, 0); PG8_STAGE(PG8_SA(0, 1), a2 + hstepA, voffA);
;             PG8_WAIT_V(8); PG8_WAIT_L(0); PG8_BAR; PG8_MMA(0, 0, At, B0); PG8_MMA(0, 1, At, B1); PG8_BAR; PG8_SCHED;
	s_setprio 1
	s_add_i32 s50, 0, 0x18000
	s_add_i32 s51, 0, 0x1c000
	v_add_u32_e32 v162, s50, v145
	v_add_u32_e32 v178, s51, v145
	ds_read_b128 v[150:153], v162
	ds_read_b128 v[154:157], v162 offset:1024
	ds_read_b128 v[158:161], v162 offset:2048
	ds_read_b128 v[162:165], v162 offset:3072
	ds_read_b128 v[166:169], v178
	ds_read_b128 v[170:173], v178 offset:1024
	ds_read_b128 v[174:177], v178 offset:2048
	ds_read_b128 v[178:181], v178 offset:3072
	s_add_u32 s26, s26, 0x80000
	s_addc_u32 s27, s27, 0
	s_mov_b32 m0, s36
	v_lshl_add_u64 v[224:225], s[26:27], 0, v[128:129]
	ds_read_b128 v[182:185], v149 offset:32768
	ds_read_b128 v[186:189], v149 offset:33792
	ds_read_b128 v[194:197], v149 offset:34816
	ds_read_b128 v[198:201], v149 offset:35840
	ds_read_b128 v[202:205], v149 offset:36864
	ds_read_b128 v[206:209], v149 offset:37888
	ds_read_b128 v[210:213], v149 offset:38912
	ds_read_b128 v[214:217], v149 offset:39936
	global_load_lds_dwordx4 v[224:225], off
	v_lshl_add_u64 v[224:225], s[26:27], 0, v[132:133]
	s_mov_b32 m0, s37
	s_nop 0
	global_load_lds_dwordx4 v[224:225], off
	s_waitcnt vmcnt(8)
	s_waitcnt lgkmcnt(0)
	s_setprio 0
	s_barrier
	v_mfma_f32_16x16x32_bf16 v[124:127], v[150:153], v[182:185], v[124:127]
	v_mfma_f32_16x16x32_bf16 v[116:119], v[158:161], v[182:185], v[116:119]
	v_mfma_f32_16x16x32_bf16 v[108:111], v[150:153], v[194:197], v[108:111]
	v_mfma_f32_16x16x32_bf16 v[100:103], v[158:161], v[194:197], v[100:103]
	v_mfma_f32_16x16x32_bf16 v[92:95], v[150:153], v[202:205], v[92:95]
	v_mfma_f32_16x16x32_bf16 v[84:87], v[158:161], v[202:205], v[84:87]
	v_mfma_f32_16x16x32_bf16 v[76:79], v[150:153], v[210:213], v[76:79]
	v_mfma_f32_16x16x32_bf16 v[68:71], v[158:161], v[210:213], v[68:71]
	v_mfma_f32_16x16x32_bf16 v[124:127], v[154:157], v[186:189], v[124:127]
	v_mfma_f32_16x16x32_bf16 v[116:119], v[162:165], v[186:189], v[116:119]
	v_mfma_f32_16x16x32_bf16 v[108:111], v[154:157], v[198:201], v[108:111]
	v_mfma_f32_16x16x32_bf16 v[100:103], v[162:165], v[198:201], v[100:103]
	v_mfma_f32_16x16x32_bf16 v[92:95], v[154:157], v[206:209], v[92:95]
	v_mfma_f32_16x16x32_bf16 v[84:87], v[162:165], v[206:209], v[84:87]
	v_mfma_f32_16x16x32_bf16 v[76:79], v[154:157], v[214:217], v[76:79]
	v_mfma_f32_16x16x32_bf16 v[68:71], v[162:165], v[214:217], v[68:71]
	v_mfma_f32_16x16x32_bf16 v[120:123], v[166:169], v[182:185], v[120:123]
	v_mfma_f32_16x16x32_bf16 v[112:115], v[174:177], v[182:185], v[112:115]
	v_mfma_f32_16x16x32_bf16 v[104:107], v[166:169], v[194:197], v[104:107]
	v_mfma_f32_16x16x32_bf16 v[96:99], v[174:177], v[194:197], v[96:99]
	v_mfma_f32_16x16x32_bf16 v[88:91], v[166:169], v[202:205], v[88:91]
	v_mfma_f32_16x16x32_bf16 v[80:83], v[174:177], v[202:205], v[80:83]
	v_mfma_f32_16x16x32_bf16 v[72:75], v[166:169], v[210:213], v[72:75]
	v_mfma_f32_16x16x32_bf16 v[64:67], v[174:177], v[210:213], v[64:67]
	v_mfma_f32_16x16x32_bf16 v[120:123], v[170:173], v[186:189], v[120:123]
	v_mfma_f32_16x16x32_bf16 v[112:115], v[178:181], v[186:189], v[112:115]
	v_mfma_f32_16x16x32_bf16 v[104:107], v[170:173], v[198:201], v[104:107]
	v_mfma_f32_16x16x32_bf16 v[96:99], v[178:181], v[198:201], v[96:99]
	v_mfma_f32_16x16x32_bf16 v[88:91], v[170:173], v[206:209], v[88:91]
	v_mfma_f32_16x16x32_bf16 v[80:83], v[178:181], v[206:209], v[80:83]
	v_mfma_f32_16x16x32_bf16 v[72:75], v[170:173], v[214:217], v[72:75]
	v_mfma_f32_16x16x32_bf16 v[64:67], v[178:181], v[214:217], v[64:67]
	s_barrier
; #define PG8_STAGE(bufoff, gbase, voff) do { _Pragma("unroll") for (int _i = 0; _i < 2; ++_i) \
;         __builtin_amdgcn_global_load_lds((const unsigned*)((const char*)(gbase) + (voff)[_i]), (LAS unsigned*)(lds + (bufoff) + ldsw + _i * 8192), 16, 0, 0); } while (0)
; #define PG8_LDA(dst, b, h) do { _Pragma("unroll") for (int m = 0; m < 4; ++m) _Pragma("unroll") for (int k = 0; k < 2; ++k) dst[m][k] = *(const LAS bf16x8*)(lds + PG8_SA(b, h) + aoff + m * 2048 + k * 1024); } while (0)
; #define PG8_MMA(ai, bj, At, Bt) do { __builtin_amdgcn_s_setprio(1); _Pragma("unroll") for (int m = 0; m < 4; ++m) _Pragma("unroll") for (int n = 0; n < 2; ++n) _Pragma("unroll") for (int k = 0; k < 2; ++k) \
;         acc[ai][bj][m][n] = __builtin_amdgcn_mfma_f32_16x16x32_bf16(Bt[n][k], At[m][k], acc[ai][bj][m][n], 0, 0, 0); __builtin_amdgcn_s_setprio(0); } while (0)
; #define PG8_WAIT_V(n) asm volatile("s_waitcnt vmcnt(" #n ")" ::: "memory")
; #define PG8_WAIT_L(n) asm volatile("s_waitcnt lgkmcnt(" #n ")" ::: "memory")
; #define PG8_BAR __builtin_amdgcn_s_barrier()
; #define PG8_SCHED __builtin_amdgcn_sched_barrier(0)
; template <class Epi, class Sched = StaticOrder, class EpiSub = NoSub, bool FAST = false>
; __device__ __forceinline__ void gemm_phase(LAS unsigned char* lds, const Gemm g, const Sched& S, const Epi& E, const EpiSub& ES = EpiSub()) {
;     ...
;             PG8_LDA(At, 1, 1); PG8_STAGE(PG8_SB(1, 0), b3, voffB); PG8_STAGE(PG8_SB(1, 1), b3 + hstepB, voffB); PG8_STAGE(PG8_SA(1, 0), a3, voffA);
;             PG8_WAIT_V(8); PG8_WAIT_L(0); PG8_BAR; PG8_MMA(1, 0, At, B0); PG8_MMA(1, 1, At, B1); PG8_BAR; PG8_SCHED;
	s_setprio 1
	s_add_i32 s26, s50, s28
	v_lshl_add_u64 v[190:191], v[190:191], 0, s[8:9]
	s_mov_b32 m0, s26
	ds_read_b128 v[182:185], v149 offset:49152
	ds_read_b128 v[186:189], v149 offset:50176
	ds_read_b128 v[194:197], v149 offset:51200
	ds_read_b128 v[198:201], v149 offset:52224
	ds_read_b128 v[202:205], v149 offset:53248
	ds_read_b128 v[206:209], v149 offset:54272
	ds_read_b128 v[210:213], v149 offset:55296
	ds_read_b128 v[214:217], v149 offset:56320
	global_load_lds_dwordx4 v[190:191], off
	s_add_i32 m0, s26, 0x2000
	s_add_u32 s24, s24, 0x80080
	v_lshl_add_u64 v[190:191], v[218:219], 0, s[8:9]
	s_addc_u32 s25, s25, 0
	s_add_i32 s26, s51, s28
	global_load_lds_dwordx4 v[190:191], off
	v_lshl_add_u64 v[190:191], s[24:25], 0, v[130:131]
	s_mov_b32 m0, s26
	s_nop 0
	global_load_lds_dwordx4 v[190:191], off
	v_lshl_add_u64 v[190:191], s[24:25], 0, v[134:135]
	s_add_i32 m0, s26, 0x2000
	s_nop 0
	global_load_lds_dwordx4 v[190:191], off
	v_lshl_add_u64 v[190:191], v[220:221], 0, s[8:9]
	s_mov_b32 m0, s40
	s_nop 0
	global_load_lds_dwordx4 v[190:191], off
	v_lshl_add_u64 v[190:191], v[222:223], 0, s[8:9]
	s_mov_b32 m0, s41
	s_nop 0
	global_load_lds_dwordx4 v[190:191], off
	s_waitcnt vmcnt(8)
	s_waitcnt lgkmcnt(0)
	s_setprio 0
	s_barrier
	v_mfma_f32_16x16x32_bf16 v[60:63], v[150:153], v[182:185], v[60:63]
	v_mfma_f32_16x16x32_bf16 v[52:55], v[158:161], v[182:185], v[52:55]
	v_mfma_f32_16x16x32_bf16 v[44:47], v[150:153], v[194:197], v[44:47]
	v_mfma_f32_16x16x32_bf16 v[36:39], v[158:161], v[194:197], v[36:39]
	v_mfma_f32_16x16x32_bf16 v[28:31], v[150:153], v[202:205], v[28:31]
	v_mfma_f32_16x16x32_bf16 v[20:23], v[158:161], v[202:205], v[20:23]
	v_mfma_f32_16x16x32_bf16 v[12:15], v[150:153], v[210:213], v[12:15]
	v_mfma_f32_16x16x32_bf16 v[4:7], v[158:161], v[210:213], v[4:7]
	v_mfma_f32_16x16x32_bf16 v[60:63], v[154:157], v[186:189], v[60:63]
	v_mfma_f32_16x16x32_bf16 v[52:55], v[162:165], v[186:189], v[52:55]
	v_mfma_f32_16x16x32_bf16 v[44:47], v[154:157], v[198:201], v[44:47]
	v_mfma_f32_16x16x32_bf16 v[36:39], v[162:165], v[198:201], v[36:39]
	v_mfma_f32_16x16x32_bf16 v[28:31], v[154:157], v[206:209], v[28:31]
	v_mfma_f32_16x16x32_bf16 v[20:23], v[162:165], v[206:209], v[20:23]
	v_mfma_f32_16x16x32_bf16 v[12:15], v[154:157], v[214:217], v[12:15]
	v_mfma_f32_16x16x32_bf16 v[4:7], v[162:165], v[214:217], v[4:7]
	v_mfma_f32_16x16x32_bf16 v[56:59], v[166:169], v[182:185], v[56:59]
	v_mfma_f32_16x16x32_bf16 v[48:51], v[174:177], v[182:185], v[48:51]
	v_mfma_f32_16x16x32_bf16 v[40:43], v[166:169], v[194:197], v[40:43]
	v_mfma_f32_16x16x32_bf16 v[32:35], v[174:177], v[194:197], v[32:35]
	v_mfma_f32_16x16x32_bf16 v[24:27], v[166:169], v[202:205], v[24:27]
	v_mfma_f32_16x16x32_bf16 v[16:19], v[174:177], v[202:205], v[16:19]
	v_mfma_f32_16x16x32_bf16 v[8:11], v[166:169], v[210:213], v[8:11]
	v_mfma_f32_16x16x32_bf16 v[0:3], v[174:177], v[210:213], v[0:3]
	v_mfma_f32_16x16x32_bf16 v[56:59], v[170:173], v[186:189], v[56:59]
	v_mfma_f32_16x16x32_bf16 v[48:51], v[178:181], v[186:189], v[48:51]
	v_mfma_f32_16x16x32_bf16 v[40:43], v[170:173], v[198:201], v[40:43]
	v_mfma_f32_16x16x32_bf16 v[32:35], v[178:181], v[198:201], v[32:35]
	v_mfma_f32_16x16x32_bf16 v[24:27], v[170:173], v[206:209], v[24:27]
	v_mfma_f32_16x16x32_bf16 v[16:19], v[178:181], v[206:209], v[16:19]
	v_mfma_f32_16x16x32_bf16 v[8:11], v[170:173], v[214:217], v[8:11]
	v_mfma_f32_16x16x32_bf16 v[0:3], v[178:181], v[214:217], v[0:3]
	s_barrier
	s_setprio 1
	s_add_i32 s49, s49, 2
	s_add_u32 s22, s22, 0x100
	s_addc_u32 s23, s23, 0
	s_add_u32 s47, s47, 0x100
	s_addc_u32 s48, s48, 0
	s_cmp_gt_u32 s49, 29
	s_cbranch_scc0 .LBB0_985

; #define PG8_STAGE(bufoff, gbase, voff) do { _Pragma("unroll") for (int _i = 0; _i < 2; ++_i) \
;         __builtin_amdgcn_global_load_lds((const unsigned*)((const char*)(gbase) + (voff)[_i]), (LAS unsigned*)(lds + (bufoff) + ldsw + _i * 8192), 16, 0, 0); } while (0)
; #define PG8_LDA(dst, b, h) do { _Pragma("unroll") for (int m = 0; m < 4; ++m) _Pragma("unroll") for (int k = 0; k < 2; ++k) dst[m][k] = *(const LAS bf16x8*)(lds + PG8_SA(b, h) + aoff + m * 2048 + k * 1024); } while (0)
; #define PG8_LDB(dst, b, h) do { _Pragma("unroll") for (int n = 0; n < 2; ++n) _Pragma("unroll") for (int k = 0; k < 2; ++k) dst[n][k] = *(const LAS bf16x8*)(lds + PG8_SB(b, h) + boff + n * 2048 + k * 1024); } while (0)
; #define PG8_WAIT_V(n) asm volatile("s_waitcnt vmcnt(" #n ")" ::: "memory")
; #define PG8_BAR __builtin_amdgcn_s_barrier()
; template <class Epi, class Sched = StaticOrder, class EpiSub = NoSub, bool FAST = false>
; __device__ __forceinline__ void gemm_phase(LAS unsigned char* lds, const Gemm g, const Sched& S, const Epi& E, const EpiSub& ES = EpiSub()) {
;     ...
;         const bool has_next = S.next(ui + 1, nxt);
;         const size_t nko = (has_next && nxt.kb >= 0) ? nxt.kb * ksubB : 0;
;         const char* nA = has_next ? (const char*)g.A + (size_t)nxt.pm * tstepA + (size_t)nxt.pn * g.acs + nko : cA; const char* nB = has_next ? (const char*)g.Bt + (size_t)nxt.pn * tstepB + nko : cB;
;         const int nt = cur.kb < 0 ? ntMain : ntSub;
;         for (int t = 0; t < nt; t += 2) {
;             const bool last = (t == nt - 2);
;             const char* a1 = cA + (size_t)(t + 1) * kstep;
;             const char* a2 = last ? nA : cA + (size_t)(t + 2) * kstep; const char* b2 = last ? nB : cB + (size_t)(t + 2) * kstep;
;             const char* a3 = a2 + kstep; const char* b3 = b2 + kstep;
;             if constexpr (FAST && PG8_SP2) {
;             PG8_LDB(B0, 0, 0); PG8_LDB(B1, 0, 1); PG8_SCHED; PG8_LDA(At, 0, 0); PG8_STAGE(PG8_SA(1, 1), a1 + hstepA, voffA);
;             PG8_WAIT_V(8); PG8_WAIT_L(0); PG8_BAR; PG8_MMA(0, 0, At, B0); PG8_MMA(0, 1, At, B1); PG8_BAR; PG8_SCHED;
;             PG8_LDA(At, 0, 1); PG8_STAGE(PG8_SB(0, 0), b2, voffB); PG8_STAGE(PG8_SB(0, 1), b2 + hstepB, voffB); PG8_STAGE(PG8_SA(0, 0), a2, voffA);
;             PG8_WAIT_V(8); PG8_WAIT_L(0); PG8_BAR; PG8_MMA(1, 0, At, B0); PG8_MMA(1, 1, At, B1); PG8_BAR; PG8_SCHED;
.LBB0_1078:
	s_cmp_gt_i32 s8, -1
	s_cselect_b64 s[4:5], -1, 0
	s_cmp_lt_i32 s8, 0
	s_cselect_b32 s70, 0x58, 22
	s_add_i32 s71, s70, -2
	s_add_u32 s42, s42, 0x160080
	s_addc_u32 s43, s43, 0
	s_add_u32 s83, s44, 0x100
	s_mov_b32 s46, 0
	s_addc_u32 s84, s45, 0
	ds_read_b128 v[96:99], v201
	ds_read_b128 v[100:103], v201 offset:1024
	ds_read_b128 v[108:111], v201 offset:2048
	ds_read_b128 v[116:119], v201 offset:3072
	ds_read_b128 v[144:147], v202
	ds_read_b128 v[148:151], v202 offset:1024
	ds_read_b128 v[152:155], v202 offset:2048
	ds_read_b128 v[156:159], v202 offset:3072
	s_add_i32 s85, s46, 2
	s_add_u32 s44, s42, 0xffea0080
	s_addc_u32 s45, s43, -1
	s_cmp_eq_u32 s71, s46
	s_cselect_b32 s46, s38, s44
	s_cselect_b32 s47, s39, s45
	s_cselect_b32 s45, s41, s84
	s_cselect_b32 s44, s40, s83
	v_lshl_add_u64 v[190:191], s[42:43], 0, v[176:177]
	s_add_i32 m0, s48, 0xc000
	ds_read_b128 v[160:163], v203
	ds_read_b128 v[164:167], v203 offset:1024
	ds_read_b128 v[182:185], v203 offset:2048
	ds_read_b128 v[186:189], v203 offset:3072
	ds_read_b128 v[194:197], v203 offset:4096
	ds_read_b128 v[204:207], v203 offset:5120
	ds_read_b128 v[208:211], v203 offset:6144
	ds_read_b128 v[212:215], v203 offset:7168
	global_load_lds_dwordx4 v[190:191], off
	v_lshl_add_u64 v[190:191], s[42:43], 0, v[178:179]
	s_add_i32 m0, s48, 0xe000
	s_nop 0
	global_load_lds_dwordx4 v[190:191], off
	s_waitcnt vmcnt(8)
	s_waitcnt lgkmcnt(0)
	s_setprio 0
	s_barrier
	v_mfma_f32_16x16x32_bf16 v[140:143], v[96:99], v[160:163], 0
	v_mfma_f32_16x16x32_bf16 v[136:139], v[108:111], v[160:163], 0
	v_mfma_f32_16x16x32_bf16 v[124:127], v[96:99], v[182:185], 0
	v_mfma_f32_16x16x32_bf16 v[120:123], v[108:111], v[182:185], 0
	v_mfma_f32_16x16x32_bf16 v[92:95], v[96:99], v[194:197], 0
	v_mfma_f32_16x16x32_bf16 v[88:91], v[108:111], v[194:197], 0
	v_mfma_f32_16x16x32_bf16 v[76:79], v[96:99], v[208:211], 0
	v_mfma_f32_16x16x32_bf16 v[72:75], v[108:111], v[208:211], 0
	v_mfma_f32_16x16x32_bf16 v[140:143], v[100:103], v[164:167], v[140:143]
	v_mfma_f32_16x16x32_bf16 v[136:139], v[116:119], v[164:167], v[136:139]
	v_mfma_f32_16x16x32_bf16 v[124:127], v[100:103], v[186:189], v[124:127]
	v_mfma_f32_16x16x32_bf16 v[120:123], v[116:119], v[186:189], v[120:123]
	v_mfma_f32_16x16x32_bf16 v[92:95], v[100:103], v[204:207], v[92:95]
	v_mfma_f32_16x16x32_bf16 v[88:91], v[116:119], v[204:207], v[88:91]
	v_mfma_f32_16x16x32_bf16 v[76:79], v[100:103], v[212:215], v[76:79]
	v_mfma_f32_16x16x32_bf16 v[72:75], v[116:119], v[212:215], v[72:75]
	v_mfma_f32_16x16x32_bf16 v[132:135], v[144:147], v[160:163], 0
	v_mfma_f32_16x16x32_bf16 v[128:131], v[152:155], v[160:163], 0
	v_mfma_f32_16x16x32_bf16 v[112:115], v[144:147], v[182:185], 0
	v_mfma_f32_16x16x32_bf16 v[104:107], v[152:155], v[182:185], 0
	v_mfma_f32_16x16x32_bf16 v[84:87], v[144:147], v[194:197], 0
	v_mfma_f32_16x16x32_bf16 v[80:83], v[152:155], v[194:197], 0
	v_mfma_f32_16x16x32_bf16 v[68:71], v[144:147], v[208:211], 0
	v_mfma_f32_16x16x32_bf16 v[64:67], v[152:155], v[208:211], 0
	v_mfma_f32_16x16x32_bf16 v[132:135], v[148:151], v[164:167], v[132:135]
	v_mfma_f32_16x16x32_bf16 v[128:131], v[156:159], v[164:167], v[128:131]
	v_mfma_f32_16x16x32_bf16 v[112:115], v[148:151], v[186:189], v[112:115]
	v_mfma_f32_16x16x32_bf16 v[104:107], v[156:159], v[186:189], v[104:107]
	v_mfma_f32_16x16x32_bf16 v[84:87], v[148:151], v[204:207], v[84:87]
	v_mfma_f32_16x16x32_bf16 v[80:83], v[156:159], v[204:207], v[80:83]
	v_mfma_f32_16x16x32_bf16 v[68:71], v[148:151], v[212:215], v[68:71]
	v_mfma_f32_16x16x32_bf16 v[64:67], v[156:159], v[212:215], v[64:67]
	s_barrier
	s_setprio 1
	s_add_i32 s86, s58, s27
	v_lshl_add_u64 v[190:191], s[44:45], 0, v[170:171]
	s_mov_b32 m0, s86
	ds_read_b128 v[160:163], v203 offset:16384
	ds_read_b128 v[164:167], v203 offset:17408
	ds_read_b128 v[182:185], v203 offset:18432
	ds_read_b128 v[186:189], v203 offset:19456
	ds_read_b128 v[194:197], v203 offset:20480
	ds_read_b128 v[204:207], v203 offset:21504
	ds_read_b128 v[208:211], v203 offset:22528
	ds_read_b128 v[212:215], v203 offset:23552
	global_load_lds_dwordx4 v[190:191], off
	s_add_i32 m0, s86, 0x2000
	s_add_u32 s86, s44, 0x160000
	v_lshl_add_u64 v[216:217], s[44:45], 0, v[174:175]
	s_addc_u32 s87, s45, 0
	s_add_i32 s88, s59, s27
	global_load_lds_dwordx4 v[216:217], off
	v_lshl_add_u64 v[218:219], s[86:87], 0, v[170:171]
	s_mov_b32 m0, s88
	v_lshl_add_u64 v[220:221], s[46:47], 0, v[172:173]
	global_load_lds_dwordx4 v[218:219], off
	v_lshl_add_u64 v[218:219], s[86:87], 0, v[174:175]
	s_add_i32 m0, s88, 0x2000
	s_nop 0
	global_load_lds_dwordx4 v[218:219], off
	v_lshl_add_u64 v[218:219], s[46:47], 0, v[168:169]
	s_mov_b32 m0, s48
	s_nop 0
	global_load_lds_dwordx4 v[218:219], off
	s_mov_b32 m0, s49
	s_nop 0
	global_load_lds_dwordx4 v[220:221], off
	s_waitcnt vmcnt(8)
	s_waitcnt lgkmcnt(0)
	s_setprio 0
	s_barrier
; #define PG8_STAGE(bufoff, gbase, voff) do { _Pragma("unroll") for (int _i = 0; _i < 2; ++_i) \
;         __builtin_amdgcn_global_load_lds((const unsigned*)((const char*)(gbase) + (voff)[_i]), (LAS unsigned*)(lds + (bufoff) + ldsw + _i * 8192), 16, 0, 0); } while (0)
; #define PG8_LDA(dst, b, h) do { _Pragma("unroll") for (int m = 0; m < 4; ++m) _Pragma("unroll") for (int k = 0; k < 2; ++k) dst[m][k] = *(const LAS bf16x8*)(lds + PG8_SA(b, h) + aoff + m * 2048 + k * 1024); } while (0)
; #define PG8_LDB(dst, b, h) do { _Pragma("unroll") for (int n = 0; n < 2; ++n) _Pragma("unroll") for (int k = 0; k < 2; ++k) dst[n][k] = *(const LAS bf16x8*)(lds + PG8_SB(b, h) + boff + n * 2048 + k * 1024); } while (0)
; #define PG8_MMA(ai, bj, At, Bt) do { __builtin_amdgcn_s_setprio(1); _Pragma("unroll") for (int m = 0; m < 4; ++m) _Pragma("unroll") for (int n = 0; n < 2; ++n) _Pragma("unroll") for (int k = 0; k < 2; ++k) \
;         acc[ai][bj][m][n] = __builtin_amdgcn_mfma_f32_16x16x32_bf16(Bt[n][k], At[m][k], acc[ai][bj][m][n], 0, 0, 0); __builtin_amdgcn_s_setprio(0); } while (0)
; #define PG8_WAIT_V(n) asm volatile("s_waitcnt vmcnt(" #n ")" ::: "memory")
; #define PG8_WAIT_L(n) asm volatile("s_waitcnt lgkmcnt(" #n ")" ::: "memory")
; #define PG8_BAR __builtin_amdgcn_s_barrier()
; #define PG8_SCHED __builtin_amdgcn_sched_barrier(0)
; template <class Epi, class Sched = StaticOrder, class EpiSub = NoSub, bool FAST = false>
; __device__ __forceinline__ void gemm_phase(LAS unsigned char* lds, const Gemm g, const Sched& S, const Epi& E, const EpiSub& ES = EpiSub()) {
;     ...
;             PG8_LDA(At, 0, 1); PG8_STAGE(PG8_SB(0, 0), b2, voffB); PG8_STAGE(PG8_SB(0, 1), b2 + hstepB, voffB); PG8_STAGE(PG8_SA(0, 0), a2, voffA);
;             PG8_WAIT_V(8); PG8_WAIT_L(0); PG8_BAR; PG8_MMA(1, 0, At, B0); PG8_MMA(1, 1, At, B1); PG8_BAR; PG8_SCHED;
;             PG8_LDB(B0, 1, 0); PG8_LDB(B1, 1, 1); PG8_SCHED; PG8_LDA(At, 1, 0); PG8_STAGE(PG8_SA(0, 1), a2 + hstepA, voffA);
;             PG8_WAIT_V(8); PG8_WAIT_L(0); PG8_BAR; PG8_MMA(0, 0, At, B0); PG8_MMA(0, 1, At, B1); PG8_BAR; PG8_SCHED;
	v_mfma_f32_16x16x32_bf16 v[60:63], v[96:99], v[160:163], 0
	v_mfma_f32_16x16x32_bf16 v[56:59], v[108:111], v[160:163], 0
	v_mfma_f32_16x16x32_bf16 v[44:47], v[96:99], v[182:185], 0
	v_mfma_f32_16x16x32_bf16 v[40:43], v[108:111], v[182:185], 0
	v_mfma_f32_16x16x32_bf16 v[28:31], v[96:99], v[194:197], 0
	v_mfma_f32_16x16x32_bf16 v[24:27], v[108:111], v[194:197], 0
	v_mfma_f32_16x16x32_bf16 v[12:15], v[96:99], v[208:211], 0
	v_mfma_f32_16x16x32_bf16 v[8:11], v[108:111], v[208:211], 0
	v_mfma_f32_16x16x32_bf16 v[60:63], v[100:103], v[164:167], v[60:63]
	v_mfma_f32_16x16x32_bf16 v[56:59], v[116:119], v[164:167], v[56:59]
	v_mfma_f32_16x16x32_bf16 v[44:47], v[100:103], v[186:189], v[44:47]
	v_mfma_f32_16x16x32_bf16 v[40:43], v[116:119], v[186:189], v[40:43]
	v_mfma_f32_16x16x32_bf16 v[28:31], v[100:103], v[204:207], v[28:31]
	v_mfma_f32_16x16x32_bf16 v[24:27], v[116:119], v[204:207], v[24:27]
	v_mfma_f32_16x16x32_bf16 v[12:15], v[100:103], v[212:215], v[12:15]
	v_mfma_f32_16x16x32_bf16 v[8:11], v[116:119], v[212:215], v[8:11]
	v_mfma_f32_16x16x32_bf16 v[52:55], v[144:147], v[160:163], 0
	v_mfma_f32_16x16x32_bf16 v[48:51], v[152:155], v[160:163], 0
	v_mfma_f32_16x16x32_bf16 v[36:39], v[144:147], v[182:185], 0
	v_mfma_f32_16x16x32_bf16 v[32:35], v[152:155], v[182:185], 0
	v_mfma_f32_16x16x32_bf16 v[20:23], v[144:147], v[194:197], 0
	v_mfma_f32_16x16x32_bf16 v[16:19], v[152:155], v[194:197], 0
	v_mfma_f32_16x16x32_bf16 v[4:7], v[144:147], v[208:211], 0
	v_mfma_f32_16x16x32_bf16 v[0:3], v[152:155], v[208:211], 0
	v_mfma_f32_16x16x32_bf16 v[52:55], v[148:151], v[164:167], v[52:55]
	v_mfma_f32_16x16x32_bf16 v[48:51], v[156:159], v[164:167], v[48:51]
	v_mfma_f32_16x16x32_bf16 v[36:39], v[148:151], v[186:189], v[36:39]
	v_mfma_f32_16x16x32_bf16 v[32:35], v[156:159], v[186:189], v[32:35]
	v_mfma_f32_16x16x32_bf16 v[20:23], v[148:151], v[204:207], v[20:23]
	v_mfma_f32_16x16x32_bf16 v[16:19], v[156:159], v[204:207], v[16:19]
	v_mfma_f32_16x16x32_bf16 v[4:7], v[148:151], v[212:215], v[4:7]
	v_mfma_f32_16x16x32_bf16 v[0:3], v[156:159], v[212:215], v[0:3]
	s_barrier
	s_setprio 1
	s_add_i32 s86, 0, 0x18000
	s_add_i32 s87, 0, 0x1c000
	v_add_u32_e32 v116, s86, v198
	v_add_u32_e32 v156, s87, v198
	ds_read_b128 v[96:99], v116
	ds_read_b128 v[100:103], v116 offset:1024
	ds_read_b128 v[108:111], v116 offset:2048
	ds_read_b128 v[116:119], v116 offset:3072
	ds_read_b128 v[144:147], v156
	ds_read_b128 v[148:151], v156 offset:1024
	ds_read_b128 v[152:155], v156 offset:2048
	ds_read_b128 v[156:159], v156 offset:3072
	s_add_u32 s46, s46, 0x160000
	s_addc_u32 s47, s47, 0
	s_mov_b32 m0, s50
	v_lshl_add_u64 v[222:223], s[46:47], 0, v[168:169]
	ds_read_b128 v[160:163], v203 offset:32768
	ds_read_b128 v[164:167], v203 offset:33792
	ds_read_b128 v[182:185], v203 offset:34816
	ds_read_b128 v[186:189], v203 offset:35840
	ds_read_b128 v[194:197], v203 offset:36864
	ds_read_b128 v[204:207], v203 offset:37888
	ds_read_b128 v[208:211], v203 offset:38912
	ds_read_b128 v[212:215], v203 offset:39936
	global_load_lds_dwordx4 v[222:223], off
	v_lshl_add_u64 v[222:223], s[46:47], 0, v[172:173]
	s_mov_b32 m0, s51
	s_nop 0
	global_load_lds_dwordx4 v[222:223], off
	s_waitcnt vmcnt(8)
	s_waitcnt lgkmcnt(0)
	s_setprio 0
	s_barrier
	v_mfma_f32_16x16x32_bf16 v[140:143], v[96:99], v[160:163], v[140:143]
	v_mfma_f32_16x16x32_bf16 v[136:139], v[108:111], v[160:163], v[136:139]
	v_mfma_f32_16x16x32_bf16 v[124:127], v[96:99], v[182:185], v[124:127]
	v_mfma_f32_16x16x32_bf16 v[120:123], v[108:111], v[182:185], v[120:123]
	v_mfma_f32_16x16x32_bf16 v[92:95], v[96:99], v[194:197], v[92:95]
	v_mfma_f32_16x16x32_bf16 v[88:91], v[108:111], v[194:197], v[88:91]
	v_mfma_f32_16x16x32_bf16 v[76:79], v[96:99], v[208:211], v[76:79]
	v_mfma_f32_16x16x32_bf16 v[72:75], v[108:111], v[208:211], v[72:75]
	v_mfma_f32_16x16x32_bf16 v[140:143], v[100:103], v[164:167], v[140:143]
	v_mfma_f32_16x16x32_bf16 v[136:139], v[116:119], v[164:167], v[136:139]
	v_mfma_f32_16x16x32_bf16 v[124:127], v[100:103], v[186:189], v[124:127]
	v_mfma_f32_16x16x32_bf16 v[120:123], v[116:119], v[186:189], v[120:123]
	v_mfma_f32_16x16x32_bf16 v[92:95], v[100:103], v[204:207], v[92:95]
	v_mfma_f32_16x16x32_bf16 v[88:91], v[116:119], v[204:207], v[88:91]
	v_mfma_f32_16x16x32_bf16 v[76:79], v[100:103], v[212:215], v[76:79]
	v_mfma_f32_16x16x32_bf16 v[72:75], v[116:119], v[212:215], v[72:75]
	v_mfma_f32_16x16x32_bf16 v[132:135], v[144:147], v[160:163], v[132:135]
	v_mfma_f32_16x16x32_bf16 v[128:131], v[152:155], v[160:163], v[128:131]
	v_mfma_f32_16x16x32_bf16 v[112:115], v[144:147], v[182:185], v[112:115]
	v_mfma_f32_16x16x32_bf16 v[104:107], v[152:155], v[182:185], v[104:107]
	v_mfma_f32_16x16x32_bf16 v[84:87], v[144:147], v[194:197], v[84:87]
	v_mfma_f32_16x16x32_bf16 v[80:83], v[152:155], v[194:197], v[80:83]
	v_mfma_f32_16x16x32_bf16 v[68:71], v[144:147], v[208:211], v[68:71]
	v_mfma_f32_16x16x32_bf16 v[64:67], v[152:155], v[208:211], v[64:67]
	v_mfma_f32_16x16x32_bf16 v[132:135], v[148:151], v[164:167], v[132:135]
	v_mfma_f32_16x16x32_bf16 v[128:131], v[156:159], v[164:167], v[128:131]
	v_mfma_f32_16x16x32_bf16 v[112:115], v[148:151], v[186:189], v[112:115]
	v_mfma_f32_16x16x32_bf16 v[104:107], v[156:159], v[186:189], v[104:107]
	v_mfma_f32_16x16x32_bf16 v[84:87], v[148:151], v[204:207], v[84:87]
	v_mfma_f32_16x16x32_bf16 v[80:83], v[156:159], v[204:207], v[80:83]
	v_mfma_f32_16x16x32_bf16 v[68:71], v[148:151], v[212:215], v[68:71]
	v_mfma_f32_16x16x32_bf16 v[64:67], v[156:159], v[212:215], v[64:67]
	s_barrier
; #define PG8_STAGE(bufoff, gbase, voff) do { _Pragma("unroll") for (int _i = 0; _i < 2; ++_i) \
;         __builtin_amdgcn_global_load_lds((const unsigned*)((const char*)(gbase) + (voff)[_i]), (LAS unsigned*)(lds + (bufoff) + ldsw + _i * 8192), 16, 0, 0); } while (0)
; #define PG8_LDA(dst, b, h) do { _Pragma("unroll") for (int m = 0; m < 4; ++m) _Pragma("unroll") for (int k = 0; k < 2; ++k) dst[m][k] = *(const LAS bf16x8*)(lds + PG8_SA(b, h) + aoff + m * 2048 + k * 1024); } while (0)
; #define PG8_LDB(dst, b, h) do { _Pragma("unroll") for (int n = 0; n < 2; ++n) _Pragma("unroll") for (int k = 0; k < 2; ++k) dst[n][k] = *(const LAS bf16x8*)(lds + PG8_SB(b, h) + boff + n * 2048 + k * 1024); } while (0)
; template <class Epi, class Sched = StaticOrder, class EpiSub = NoSub, bool FAST = false>
; __device__ __forceinline__ void gemm_phase(LAS unsigned char* lds, const Gemm g, const Sched& S, const Epi& E, const EpiSub& ES = EpiSub()) {
;     ...
;         for (int t = 0; t < nt; t += 2) {
;             const bool last = (t == nt - 2);
;             const char* a1 = cA + (size_t)(t + 1) * kstep;
;             const char* a2 = last ? nA : cA + (size_t)(t + 2) * kstep; const char* b2 = last ? nB : cB + (size_t)(t + 2) * kstep;
;             const char* a3 = a2 + kstep; const char* b3 = b2 + kstep;
;             if constexpr (FAST && PG8_SP2) {
;             PG8_LDB(B0, 0, 0); PG8_LDB(B1, 0, 1); PG8_SCHED; PG8_LDA(At, 0, 0); PG8_STAGE(PG8_SA(1, 1), a1 + hstepA, voffA);
;             PG8_WAIT_V(8); PG8_WAIT_L(0); PG8_BAR; PG8_MMA(0, 0, At, B0); PG8_MMA(0, 1, At, B1); PG8_BAR; PG8_SCHED;
;             PG8_LDA(At, 0, 1); PG8_STAGE(PG8_SB(0, 0), b2, voffB); PG8_STAGE(PG8_SB(0, 1), b2 + hstepB, voffB); PG8_STAGE(PG8_SA(0, 0), a2, voffA);
;             PG8_WAIT_V(8); PG8_WAIT_L(0); PG8_BAR; PG8_MMA(1, 0, At, B0); PG8_MMA(1, 1, At, B1); PG8_BAR; PG8_SCHED;
;             PG8_LDB(B0, 1, 0); PG8_LDB(B1, 1, 1); PG8_SCHED; PG8_LDA(At, 1, 0); PG8_STAGE(PG8_SA(0, 1), a2 + hstepA, voffA);
;             PG8_WAIT_V(8); PG8_WAIT_L(0); PG8_BAR; PG8_MMA(0, 0, At, B0); PG8_MMA(0, 1, At, B1); PG8_BAR; PG8_SCHED;
;             PG8_LDA(At, 1, 1); PG8_STAGE(PG8_SB(1, 0), b3, voffB); PG8_STAGE(PG8_SB(1, 1), b3 + hstepB, voffB); PG8_STAGE(PG8_SA(1, 0), a3, voffA);
;             PG8_WAIT_V(8); PG8_WAIT_L(0); PG8_BAR; PG8_MMA(1, 0, At, B0); PG8_MMA(1, 1, At, B1); PG8_BAR; PG8_SCHED;
	s_setprio 1
	s_add_i32 s46, s86, s27
	v_lshl_add_u64 v[190:191], v[190:191], 0, s[16:17]
	s_mov_b32 m0, s46
	ds_read_b128 v[160:163], v203 offset:49152
	ds_read_b128 v[164:167], v203 offset:50176
	ds_read_b128 v[182:185], v203 offset:51200
	ds_read_b128 v[186:189], v203 offset:52224
	ds_read_b128 v[194:197], v203 offset:53248
	ds_read_b128 v[204:207], v203 offset:54272
	ds_read_b128 v[208:211], v203 offset:55296
	ds_read_b128 v[212:215], v203 offset:56320
	global_load_lds_dwordx4 v[190:191], off
	s_add_i32 m0, s46, 0x2000
	s_add_u32 s44, s44, 0x160080
	v_lshl_add_u64 v[190:191], v[216:217], 0, s[16:17]
	s_addc_u32 s45, s45, 0
	s_add_i32 s46, s87, s27
	global_load_lds_dwordx4 v[190:191], off
	v_lshl_add_u64 v[190:191], s[44:45], 0, v[170:171]
	s_mov_b32 m0, s46
	s_nop 0
	global_load_lds_dwordx4 v[190:191], off
	v_lshl_add_u64 v[190:191], s[44:45], 0, v[174:175]
	s_add_i32 m0, s46, 0x2000
	s_nop 0
	global_load_lds_dwordx4 v[190:191], off
	v_lshl_add_u64 v[190:191], v[218:219], 0, s[16:17]
	s_mov_b32 m0, s53
	s_nop 0
	global_load_lds_dwordx4 v[190:191], off
	v_lshl_add_u64 v[190:191], v[220:221], 0, s[16:17]
	s_mov_b32 m0, s54
	s_nop 0
	global_load_lds_dwordx4 v[190:191], off
	s_waitcnt vmcnt(8)
	s_waitcnt lgkmcnt(0)
	s_setprio 0
	s_barrier
	v_mfma_f32_16x16x32_bf16 v[60:63], v[96:99], v[160:163], v[60:63]
	v_mfma_f32_16x16x32_bf16 v[56:59], v[108:111], v[160:163], v[56:59]
	v_mfma_f32_16x16x32_bf16 v[44:47], v[96:99], v[182:185], v[44:47]
	v_mfma_f32_16x16x32_bf16 v[40:43], v[108:111], v[182:185], v[40:43]
	v_mfma_f32_16x16x32_bf16 v[28:31], v[96:99], v[194:197], v[28:31]
	v_mfma_f32_16x16x32_bf16 v[24:27], v[108:111], v[194:197], v[24:27]
	v_mfma_f32_16x16x32_bf16 v[12:15], v[96:99], v[208:211], v[12:15]
	v_mfma_f32_16x16x32_bf16 v[8:11], v[108:111], v[208:211], v[8:11]
	v_mfma_f32_16x16x32_bf16 v[60:63], v[100:103], v[164:167], v[60:63]
	v_mfma_f32_16x16x32_bf16 v[56:59], v[116:119], v[164:167], v[56:59]
	v_mfma_f32_16x16x32_bf16 v[44:47], v[100:103], v[186:189], v[44:47]
	v_mfma_f32_16x16x32_bf16 v[40:43], v[116:119], v[186:189], v[40:43]
	v_mfma_f32_16x16x32_bf16 v[28:31], v[100:103], v[204:207], v[28:31]
	v_mfma_f32_16x16x32_bf16 v[24:27], v[116:119], v[204:207], v[24:27]
	v_mfma_f32_16x16x32_bf16 v[12:15], v[100:103], v[212:215], v[12:15]
	v_mfma_f32_16x16x32_bf16 v[8:11], v[116:119], v[212:215], v[8:11]
	v_mfma_f32_16x16x32_bf16 v[52:55], v[144:147], v[160:163], v[52:55]
	v_mfma_f32_16x16x32_bf16 v[48:51], v[152:155], v[160:163], v[48:51]
	v_mfma_f32_16x16x32_bf16 v[36:39], v[144:147], v[182:185], v[36:39]
	v_mfma_f32_16x16x32_bf16 v[32:35], v[152:155], v[182:185], v[32:35]
	v_mfma_f32_16x16x32_bf16 v[20:23], v[144:147], v[194:197], v[20:23]
	v_mfma_f32_16x16x32_bf16 v[16:19], v[152:155], v[194:197], v[16:19]
	v_mfma_f32_16x16x32_bf16 v[4:7], v[144:147], v[208:211], v[4:7]
	v_mfma_f32_16x16x32_bf16 v[0:3], v[152:155], v[208:211], v[0:3]
	v_mfma_f32_16x16x32_bf16 v[52:55], v[148:151], v[164:167], v[52:55]
	v_mfma_f32_16x16x32_bf16 v[48:51], v[156:159], v[164:167], v[48:51]
	v_mfma_f32_16x16x32_bf16 v[36:39], v[148:151], v[186:189], v[36:39]
	v_mfma_f32_16x16x32_bf16 v[32:35], v[156:159], v[186:189], v[32:35]
	v_mfma_f32_16x16x32_bf16 v[20:23], v[148:151], v[204:207], v[20:23]
	v_mfma_f32_16x16x32_bf16 v[16:19], v[156:159], v[204:207], v[16:19]
	v_mfma_f32_16x16x32_bf16 v[4:7], v[148:151], v[212:215], v[4:7]
	v_mfma_f32_16x16x32_bf16 v[0:3], v[156:159], v[212:215], v[0:3]
	s_barrier
	s_setprio 1
	s_add_u32 s42, s42, 0x100
	s_addc_u32 s43, s43, 0
	s_add_u32 s83, s83, 0x100
	s_addc_u32 s84, s84, 0
	s_cmp_ge_u32 s85, s70
	s_mov_b32 s46, s85
	s_cbranch_scc1 .Lkpeel_1079_exit
.LBB0_1079:
	ds_read_b128 v[96:99], v201
	ds_read_b128 v[100:103], v201 offset:1024
	ds_read_b128 v[108:111], v201 offset:2048
	ds_read_b128 v[116:119], v201 offset:3072
	ds_read_b128 v[144:147], v202
	ds_read_b128 v[148:151], v202 offset:1024
	ds_read_b128 v[152:155], v202 offset:2048
	ds_read_b128 v[156:159], v202 offset:3072
	s_add_i32 s85, s46, 2
	s_add_u32 s44, s42, 0xffea0080
	s_addc_u32 s45, s43, -1
	s_cmp_eq_u32 s71, s46
	s_cselect_b32 s46, s38, s44
	s_cselect_b32 s47, s39, s45
	s_cselect_b32 s45, s41, s84
	s_cselect_b32 s44, s40, s83
	v_lshl_add_u64 v[190:191], s[42:43], 0, v[176:177]
	s_add_i32 m0, s48, 0xc000
	ds_read_b128 v[160:163], v203
	ds_read_b128 v[164:167], v203 offset:1024
	ds_read_b128 v[182:185], v203 offset:2048
	ds_read_b128 v[186:189], v203 offset:3072
	ds_read_b128 v[194:197], v203 offset:4096
	ds_read_b128 v[204:207], v203 offset:5120
	ds_read_b128 v[208:211], v203 offset:6144
	ds_read_b128 v[212:215], v203 offset:7168
	global_load_lds_dwordx4 v[190:191], off
	v_lshl_add_u64 v[190:191], s[42:43], 0, v[178:179]
	s_add_i32 m0, s48, 0xe000
	s_nop 0
	global_load_lds_dwordx4 v[190:191], off
	s_waitcnt vmcnt(8)
	s_waitcnt lgkmcnt(0)
	s_setprio 0
	s_barrier
; #define PG8_STAGE(bufoff, gbase, voff) do { _Pragma("unroll") for (int _i = 0; _i < 2; ++_i) \
;         __builtin_amdgcn_global_load_lds((const unsigned*)((const char*)(gbase) + (voff)[_i]), (LAS unsigned*)(lds + (bufoff) + ldsw + _i * 8192), 16, 0, 0); } while (0)
; #define PG8_LDA(dst, b, h) do { _Pragma("unroll") for (int m = 0; m < 4; ++m) _Pragma("unroll") for (int k = 0; k < 2; ++k) dst[m][k] = *(const LAS bf16x8*)(lds + PG8_SA(b, h) + aoff + m * 2048 + k * 1024); } while (0)
; #define PG8_LDB(dst, b, h) do { _Pragma("unroll") for (int n = 0; n < 2; ++n) _Pragma("unroll") for (int k = 0; k < 2; ++k) dst[n][k] = *(const LAS bf16x8*)(lds + PG8_SB(b, h) + boff + n * 2048 + k * 1024); } while (0)
; #define PG8_MMA(ai, bj, At, Bt) do { __builtin_amdgcn_s_setprio(1); _Pragma("unroll") for (int m = 0; m < 4; ++m) _Pragma("unroll") for (int n = 0; n < 2; ++n) _Pragma("unroll") for (int k = 0; k < 2; ++k) \
;         acc[ai][bj][m][n] = __builtin_amdgcn_mfma_f32_16x16x32_bf16(Bt[n][k], At[m][k], acc[ai][bj][m][n], 0, 0, 0); __builtin_amdgcn_s_setprio(0); } while (0)
; #define PG8_WAIT_V(n) asm volatile("s_waitcnt vmcnt(" #n ")" ::: "memory")
; #define PG8_WAIT_L(n) asm volatile("s_waitcnt lgkmcnt(" #n ")" ::: "memory")
; #define PG8_BAR __builtin_amdgcn_s_barrier()
; #define PG8_SCHED __builtin_amdgcn_sched_barrier(0)
; template <class Epi, class Sched = StaticOrder, class EpiSub = NoSub, bool FAST = false>
; __device__ __forceinline__ void gemm_phase(LAS unsigned char* lds, const Gemm g, const Sched& S, const Epi& E, const EpiSub& ES = EpiSub()) {
;     ...
;             PG8_LDB(B0, 0, 0); PG8_LDB(B1, 0, 1); PG8_SCHED; PG8_LDA(At, 0, 0); PG8_STAGE(PG8_SA(1, 1), a1 + hstepA, voffA);
;             PG8_WAIT_V(8); PG8_WAIT_L(0); PG8_BAR; PG8_MMA(0, 0, At, B0); PG8_MMA(0, 1, At, B1); PG8_BAR; PG8_SCHED;
;             PG8_LDA(At, 0, 1); PG8_STAGE(PG8_SB(0, 0), b2, voffB); PG8_STAGE(PG8_SB(0, 1), b2 + hstepB, voffB); PG8_STAGE(PG8_SA(0, 0), a2, voffA);
;             PG8_WAIT_V(8); PG8_WAIT_L(0); PG8_BAR; PG8_MMA(1, 0, At, B0); PG8_MMA(1, 1, At, B1); PG8_BAR; PG8_SCHED;
	v_mfma_f32_16x16x32_bf16 v[140:143], v[96:99], v[160:163], v[140:143]
	v_mfma_f32_16x16x32_bf16 v[136:139], v[108:111], v[160:163], v[136:139]
	v_mfma_f32_16x16x32_bf16 v[124:127], v[96:99], v[182:185], v[124:127]
	v_mfma_f32_16x16x32_bf16 v[120:123], v[108:111], v[182:185], v[120:123]
	v_mfma_f32_16x16x32_bf16 v[92:95], v[96:99], v[194:197], v[92:95]
	v_mfma_f32_16x16x32_bf16 v[88:91], v[108:111], v[194:197], v[88:91]
	v_mfma_f32_16x16x32_bf16 v[76:79], v[96:99], v[208:211], v[76:79]
	v_mfma_f32_16x16x32_bf16 v[72:75], v[108:111], v[208:211], v[72:75]
	v_mfma_f32_16x16x32_bf16 v[140:143], v[100:103], v[164:167], v[140:143]
	v_mfma_f32_16x16x32_bf16 v[136:139], v[116:119], v[164:167], v[136:139]
	v_mfma_f32_16x16x32_bf16 v[124:127], v[100:103], v[186:189], v[124:127]
	v_mfma_f32_16x16x32_bf16 v[120:123], v[116:119], v[186:189], v[120:123]
	v_mfma_f32_16x16x32_bf16 v[92:95], v[100:103], v[204:207], v[92:95]
	v_mfma_f32_16x16x32_bf16 v[88:91], v[116:119], v[204:207], v[88:91]
	v_mfma_f32_16x16x32_bf16 v[76:79], v[100:103], v[212:215], v[76:79]
	v_mfma_f32_16x16x32_bf16 v[72:75], v[116:119], v[212:215], v[72:75]
	v_mfma_f32_16x16x32_bf16 v[132:135], v[144:147], v[160:163], v[132:135]
	v_mfma_f32_16x16x32_bf16 v[128:131], v[152:155], v[160:163], v[128:131]
	v_mfma_f32_16x16x32_bf16 v[112:115], v[144:147], v[182:185], v[112:115]
	v_mfma_f32_16x16x32_bf16 v[104:107], v[152:155], v[182:185], v[104:107]
	v_mfma_f32_16x16x32_bf16 v[84:87], v[144:147], v[194:197], v[84:87]
	v_mfma_f32_16x16x32_bf16 v[80:83], v[152:155], v[194:197], v[80:83]
	v_mfma_f32_16x16x32_bf16 v[68:71], v[144:147], v[208:211], v[68:71]
	v_mfma_f32_16x16x32_bf16 v[64:67], v[152:155], v[208:211], v[64:67]
	v_mfma_f32_16x16x32_bf16 v[132:135], v[148:151], v[164:167], v[132:135]
	v_mfma_f32_16x16x32_bf16 v[128:131], v[156:159], v[164:167], v[128:131]
	v_mfma_f32_16x16x32_bf16 v[112:115], v[148:151], v[186:189], v[112:115]
	v_mfma_f32_16x16x32_bf16 v[104:107], v[156:159], v[186:189], v[104:107]
	v_mfma_f32_16x16x32_bf16 v[84:87], v[148:151], v[204:207], v[84:87]
	v_mfma_f32_16x16x32_bf16 v[80:83], v[156:159], v[204:207], v[80:83]
	v_mfma_f32_16x16x32_bf16 v[68:71], v[148:151], v[212:215], v[68:71]
	v_mfma_f32_16x16x32_bf16 v[64:67], v[156:159], v[212:215], v[64:67]
	s_barrier
	s_setprio 1
	s_add_i32 s86, s58, s27
	v_lshl_add_u64 v[190:191], s[44:45], 0, v[170:171]
	s_mov_b32 m0, s86
	ds_read_b128 v[160:163], v203 offset:16384
	ds_read_b128 v[164:167], v203 offset:17408
	ds_read_b128 v[182:185], v203 offset:18432
	ds_read_b128 v[186:189], v203 offset:19456
	ds_read_b128 v[194:197], v203 offset:20480
	ds_read_b128 v[204:207], v203 offset:21504
	ds_read_b128 v[208:211], v203 offset:22528
	ds_read_b128 v[212:215], v203 offset:23552
	global_load_lds_dwordx4 v[190:191], off
	s_add_i32 m0, s86, 0x2000
	s_add_u32 s86, s44, 0x160000
	v_lshl_add_u64 v[216:217], s[44:45], 0, v[174:175]
	s_addc_u32 s87, s45, 0
	s_add_i32 s88, s59, s27
	global_load_lds_dwordx4 v[216:217], off
	v_lshl_add_u64 v[218:219], s[86:87], 0, v[170:171]
	s_mov_b32 m0, s88
	v_lshl_add_u64 v[220:221], s[46:47], 0, v[172:173]
	global_load_lds_dwordx4 v[218:219], off
	v_lshl_add_u64 v[218:219], s[86:87], 0, v[174:175]
	s_add_i32 m0, s88, 0x2000
	s_nop 0
	global_load_lds_dwordx4 v[218:219], off
	v_lshl_add_u64 v[218:219], s[46:47], 0, v[168:169]
	s_mov_b32 m0, s48
	s_nop 0
	global_load_lds_dwordx4 v[218:219], off
	s_mov_b32 m0, s49
	s_nop 0
	global_load_lds_dwordx4 v[220:221], off
	s_waitcnt vmcnt(8)
	s_waitcnt lgkmcnt(0)
	s_setprio 0
	s_barrier
	v_mfma_f32_16x16x32_bf16 v[60:63], v[96:99], v[160:163], v[60:63]
	v_mfma_f32_16x16x32_bf16 v[56:59], v[108:111], v[160:163], v[56:59]
	v_mfma_f32_16x16x32_bf16 v[44:47], v[96:99], v[182:185], v[44:47]
	v_mfma_f32_16x16x32_bf16 v[40:43], v[108:111], v[182:185], v[40:43]
	v_mfma_f32_16x16x32_bf16 v[28:31], v[96:99], v[194:197], v[28:31]
	v_mfma_f32_16x16x32_bf16 v[24:27], v[108:111], v[194:197], v[24:27]
	v_mfma_f32_16x16x32_bf16 v[12:15], v[96:99], v[208:211], v[12:15]
	v_mfma_f32_16x16x32_bf16 v[8:11], v[108:111], v[208:211], v[8:11]
	v_mfma_f32_16x16x32_bf16 v[60:63], v[100:103], v[164:167], v[60:63]
	v_mfma_f32_16x16x32_bf16 v[56:59], v[116:119], v[164:167], v[56:59]
	v_mfma_f32_16x16x32_bf16 v[44:47], v[100:103], v[186:189], v[44:47]
	v_mfma_f32_16x16x32_bf16 v[40:43], v[116:119], v[186:189], v[40:43]
	v_mfma_f32_16x16x32_bf16 v[28:31], v[100:103], v[204:207], v[28:31]
	v_mfma_f32_16x16x32_bf16 v[24:27], v[116:119], v[204:207], v[24:27]
	v_mfma_f32_16x16x32_bf16 v[12:15], v[100:103], v[212:215], v[12:15]
	v_mfma_f32_16x16x32_bf16 v[8:11], v[116:119], v[212:215], v[8:11]
	v_mfma_f32_16x16x32_bf16 v[52:55], v[144:147], v[160:163], v[52:55]
	v_mfma_f32_16x16x32_bf16 v[48:51], v[152:155], v[160:163], v[48:51]
	v_mfma_f32_16x16x32_bf16 v[36:39], v[144:147], v[182:185], v[36:39]
	v_mfma_f32_16x16x32_bf16 v[32:35], v[152:155], v[182:185], v[32:35]
	v_mfma_f32_16x16x32_bf16 v[20:23], v[144:147], v[194:197], v[20:23]
	v_mfma_f32_16x16x32_bf16 v[16:19], v[152:155], v[194:197], v[16:19]
	v_mfma_f32_16x16x32_bf16 v[4:7], v[144:147], v[208:211], v[4:7]
	v_mfma_f32_16x16x32_bf16 v[0:3], v[152:155], v[208:211], v[0:3]
	v_mfma_f32_16x16x32_bf16 v[52:55], v[148:151], v[164:167], v[52:55]
	v_mfma_f32_16x16x32_bf16 v[48:51], v[156:159], v[164:167], v[48:51]
	v_mfma_f32_16x16x32_bf16 v[36:39], v[148:151], v[186:189], v[36:39]
	v_mfma_f32_16x16x32_bf16 v[32:35], v[156:159], v[186:189], v[32:35]
	v_mfma_f32_16x16x32_bf16 v[20:23], v[148:151], v[204:207], v[20:23]
	v_mfma_f32_16x16x32_bf16 v[16:19], v[156:159], v[204:207], v[16:19]
	v_mfma_f32_16x16x32_bf16 v[4:7], v[148:151], v[212:215], v[4:7]
	v_mfma_f32_16x16x32_bf16 v[0:3], v[156:159], v[212:215], v[0:3]
	s_barrier
; #define PG8_STAGE(bufoff, gbase, voff) do { _Pragma("unroll") for (int _i = 0; _i < 2; ++_i) \
;         __builtin_amdgcn_global_load_lds((const unsigned*)((const char*)(gbase) + (voff)[_i]), (LAS unsigned*)(lds + (bufoff) + ldsw + _i * 8192), 16, 0, 0); } while (0)
; #define PG8_LDA(dst, b, h) do { _Pragma("unroll") for (int m = 0; m < 4; ++m) _Pragma("unroll") for (int k = 0; k < 2; ++k) dst[m][k] = *(const LAS bf16x8*)(lds + PG8_SA(b, h) + aoff + m * 2048 + k * 1024); } while (0)
; #define PG8_LDB(dst, b, h) do { _Pragma("unroll") for (int n = 0; n < 2; ++n) _Pragma("unroll") for (int k = 0; k < 2; ++k) dst[n][k] = *(const LAS bf16x8*)(lds + PG8_SB(b, h) + boff + n * 2048 + k * 1024); } while (0)
; #define PG8_MMA(ai, bj, At, Bt) do { __builtin_amdgcn_s_setprio(1); _Pragma("unroll") for (int m = 0; m < 4; ++m) _Pragma("unroll") for (int n = 0; n < 2; ++n) _Pragma("unroll") for (int k = 0; k < 2; ++k) \
;         acc[ai][bj][m][n] = __builtin_amdgcn_mfma_f32_16x16x32_bf16(Bt[n][k], At[m][k], acc[ai][bj][m][n], 0, 0, 0); __builtin_amdgcn_s_setprio(0); } while (0)
; #define PG8_WAIT_V(n) asm volatile("s_waitcnt vmcnt(" #n ")" ::: "memory")
; #define PG8_WAIT_L(n) asm volatile("s_waitcnt lgkmcnt(" #n ")" ::: "memory")
; #define PG8_BAR __builtin_amdgcn_s_barrier()
; #define PG8_SCHED __builtin_amdgcn_sched_barrier(0)
; template <class Epi, class Sched = StaticOrder, class EpiSub = NoSub, bool FAST = false>
; __device__ __forceinline__ void gemm_phase(LAS unsigned char* lds, const Gemm g, const Sched& S, const Epi& E, const EpiSub& ES = EpiSub()) {
;     ...
;             PG8_LDB(B0, 1, 0); PG8_LDB(B1, 1, 1); PG8_SCHED; PG8_LDA(At, 1, 0); PG8_STAGE(PG8_SA(0, 1), a2 + hstepA, voffA);
;             PG8_WAIT_V(8); PG8_WAIT_L(0); PG8_BAR; PG8_MMA(0, 0, At, B0); PG8_MMA(0, 1, At, B1); PG8_BAR; PG8_SCHED;
	s_setprio 1
	s_add_i32 s86, 0, 0x18000
	s_add_i32 s87, 0, 0x1c000
	v_add_u32_e32 v116, s86, v198
	v_add_u32_e32 v156, s87, v198
	ds_read_b128 v[96:99], v116
	ds_read_b128 v[100:103], v116 offset:1024
	ds_read_b128 v[108:111], v116 offset:2048
	ds_read_b128 v[116:119], v116 offset:3072
	ds_read_b128 v[144:147], v156
	ds_read_b128 v[148:151], v156 offset:1024
	ds_read_b128 v[152:155], v156 offset:2048
	ds_read_b128 v[156:159], v156 offset:3072
	s_add_u32 s46, s46, 0x160000
	s_addc_u32 s47, s47, 0
	s_mov_b32 m0, s50
	v_lshl_add_u64 v[222:223], s[46:47], 0, v[168:169]
	ds_read_b128 v[160:163], v203 offset:32768
	ds_read_b128 v[164:167], v203 offset:33792
	ds_read_b128 v[182:185], v203 offset:34816
	ds_read_b128 v[186:189], v203 offset:35840
	ds_read_b128 v[194:197], v203 offset:36864
	ds_read_b128 v[204:207], v203 offset:37888
	ds_read_b128 v[208:211], v203 offset:38912
	ds_read_b128 v[212:215], v203 offset:39936
	global_load_lds_dwordx4 v[222:223], off
	v_lshl_add_u64 v[222:223], s[46:47], 0, v[172:173]
	s_mov_b32 m0, s51
	s_nop 0
	global_load_lds_dwordx4 v[222:223], off
	s_waitcnt vmcnt(8)
	s_waitcnt lgkmcnt(0)
	s_setprio 0
	s_barrier
	v_mfma_f32_16x16x32_bf16 v[140:143], v[96:99], v[160:163], v[140:143]
	v_mfma_f32_16x16x32_bf16 v[136:139], v[108:111], v[160:163], v[136:139]
	v_mfma_f32_16x16x32_bf16 v[124:127], v[96:99], v[182:185], v[124:127]
	v_mfma_f32_16x16x32_bf16 v[120:123], v[108:111], v[182:185], v[120:123]
	v_mfma_f32_16x16x32_bf16 v[92:95], v[96:99], v[194:197], v[92:95]
	v_mfma_f32_16x16x32_bf16 v[88:91], v[108:111], v[194:197], v[88:91]
	v_mfma_f32_16x16x32_bf16 v[76:79], v[96:99], v[208:211], v[76:79]
	v_mfma_f32_16x16x32_bf16 v[72:75], v[108:111], v[208:211], v[72:75]
	v_mfma_f32_16x16x32_bf16 v[140:143], v[100:103], v[164:167], v[140:143]
	v_mfma_f32_16x16x32_bf16 v[136:139], v[116:119], v[164:167], v[136:139]
	v_mfma_f32_16x16x32_bf16 v[124:127], v[100:103], v[186:189], v[124:127]
	v_mfma_f32_16x16x32_bf16 v[120:123], v[116:119], v[186:189], v[120:123]
	v_mfma_f32_16x16x32_bf16 v[92:95], v[100:103], v[204:207], v[92:95]
	v_mfma_f32_16x16x32_bf16 v[88:91], v[116:119], v[204:207], v[88:91]
	v_mfma_f32_16x16x32_bf16 v[76:79], v[100:103], v[212:215], v[76:79]
	v_mfma_f32_16x16x32_bf16 v[72:75], v[116:119], v[212:215], v[72:75]
	v_mfma_f32_16x16x32_bf16 v[132:135], v[144:147], v[160:163], v[132:135]
	v_mfma_f32_16x16x32_bf16 v[128:131], v[152:155], v[160:163], v[128:131]
	v_mfma_f32_16x16x32_bf16 v[112:115], v[144:147], v[182:185], v[112:115]
	v_mfma_f32_16x16x32_bf16 v[104:107], v[152:155], v[182:185], v[104:107]
	v_mfma_f32_16x16x32_bf16 v[84:87], v[144:147], v[194:197], v[84:87]
	v_mfma_f32_16x16x32_bf16 v[80:83], v[152:155], v[194:197], v[80:83]
	v_mfma_f32_16x16x32_bf16 v[68:71], v[144:147], v[208:211], v[68:71]
	v_mfma_f32_16x16x32_bf16 v[64:67], v[152:155], v[208:211], v[64:67]
	v_mfma_f32_16x16x32_bf16 v[132:135], v[148:151], v[164:167], v[132:135]
	v_mfma_f32_16x16x32_bf16 v[128:131], v[156:159], v[164:167], v[128:131]
	v_mfma_f32_16x16x32_bf16 v[112:115], v[148:151], v[186:189], v[112:115]
	v_mfma_f32_16x16x32_bf16 v[104:107], v[156:159], v[186:189], v[104:107]
	v_mfma_f32_16x16x32_bf16 v[84:87], v[148:151], v[204:207], v[84:87]
	v_mfma_f32_16x16x32_bf16 v[80:83], v[156:159], v[204:207], v[80:83]
	v_mfma_f32_16x16x32_bf16 v[68:71], v[148:151], v[212:215], v[68:71]
	v_mfma_f32_16x16x32_bf16 v[64:67], v[156:159], v[212:215], v[64:67]
	s_barrier
; #define PG8_STAGE(bufoff, gbase, voff) do { _Pragma("unroll") for (int _i = 0; _i < 2; ++_i) \
;         __builtin_amdgcn_global_load_lds((const unsigned*)((const char*)(gbase) + (voff)[_i]), (LAS unsigned*)(lds + (bufoff) + ldsw + _i * 8192), 16, 0, 0); } while (0)
; #define PG8_LDA(dst, b, h) do { _Pragma("unroll") for (int m = 0; m < 4; ++m) _Pragma("unroll") for (int k = 0; k < 2; ++k) dst[m][k] = *(const LAS bf16x8*)(lds + PG8_SA(b, h) + aoff + m * 2048 + k * 1024); } while (0)
; #define PG8_MMA(ai, bj, At, Bt) do { __builtin_amdgcn_s_setprio(1); _Pragma("unroll") for (int m = 0; m < 4; ++m) _Pragma("unroll") for (int n = 0; n < 2; ++n) _Pragma("unroll") for (int k = 0; k < 2; ++k) \
;         acc[ai][bj][m][n] = __builtin_amdgcn_mfma_f32_16x16x32_bf16(Bt[n][k], At[m][k], acc[ai][bj][m][n], 0, 0, 0); __builtin_amdgcn_s_setprio(0); } while (0)
; #define PG8_WAIT_V(n) asm volatile("s_waitcnt vmcnt(" #n ")" ::: "memory")
; #define PG8_WAIT_L(n) asm volatile("s_waitcnt lgkmcnt(" #n ")" ::: "memory")
; #define PG8_BAR __builtin_amdgcn_s_barrier()
; #define PG8_SCHED __builtin_amdgcn_sched_barrier(0)
; template <class Epi, class Sched = StaticOrder, class EpiSub = NoSub, bool FAST = false>
; __device__ __forceinline__ void gemm_phase(LAS unsigned char* lds, const Gemm g, const Sched& S, const Epi& E, const EpiSub& ES = EpiSub()) {
;     ...
;             PG8_LDA(At, 1, 1); PG8_STAGE(PG8_SB(1, 0), b3, voffB); PG8_STAGE(PG8_SB(1, 1), b3 + hstepB, voffB); PG8_STAGE(PG8_SA(1, 0), a3, voffA);
;             PG8_WAIT_V(8); PG8_WAIT_L(0); PG8_BAR; PG8_MMA(1, 0, At, B0); PG8_MMA(1, 1, At, B1); PG8_BAR; PG8_SCHED;
;     ...
;         if constexpr (FAST && PG8_ALIGN) { if (wr == 0) PG8_BAR; }
	s_setprio 1
	s_add_i32 s46, s86, s27
	v_lshl_add_u64 v[190:191], v[190:191], 0, s[16:17]
	s_mov_b32 m0, s46
	ds_read_b128 v[160:163], v203 offset:49152
	ds_read_b128 v[164:167], v203 offset:50176
	ds_read_b128 v[182:185], v203 offset:51200
	ds_read_b128 v[186:189], v203 offset:52224
	ds_read_b128 v[194:197], v203 offset:53248
	ds_read_b128 v[204:207], v203 offset:54272
	ds_read_b128 v[208:211], v203 offset:55296
	ds_read_b128 v[212:215], v203 offset:56320
	global_load_lds_dwordx4 v[190:191], off
	s_add_i32 m0, s46, 0x2000
	s_add_u32 s44, s44, 0x160080
	v_lshl_add_u64 v[190:191], v[216:217], 0, s[16:17]
	s_addc_u32 s45, s45, 0
	s_add_i32 s46, s87, s27
	global_load_lds_dwordx4 v[190:191], off
	v_lshl_add_u64 v[190:191], s[44:45], 0, v[170:171]
	s_mov_b32 m0, s46
	s_nop 0
	global_load_lds_dwordx4 v[190:191], off
	v_lshl_add_u64 v[190:191], s[44:45], 0, v[174:175]
	s_add_i32 m0, s46, 0x2000
	s_nop 0
	global_load_lds_dwordx4 v[190:191], off
	v_lshl_add_u64 v[190:191], v[218:219], 0, s[16:17]
	s_mov_b32 m0, s53
	s_nop 0
	global_load_lds_dwordx4 v[190:191], off
	v_lshl_add_u64 v[190:191], v[220:221], 0, s[16:17]
	s_mov_b32 m0, s54
	s_nop 0
	global_load_lds_dwordx4 v[190:191], off
	s_waitcnt vmcnt(8)
	s_waitcnt lgkmcnt(0)
	s_setprio 0
	s_barrier
	v_mfma_f32_16x16x32_bf16 v[60:63], v[96:99], v[160:163], v[60:63]
	v_mfma_f32_16x16x32_bf16 v[56:59], v[108:111], v[160:163], v[56:59]
	v_mfma_f32_16x16x32_bf16 v[44:47], v[96:99], v[182:185], v[44:47]
	v_mfma_f32_16x16x32_bf16 v[40:43], v[108:111], v[182:185], v[40:43]
	v_mfma_f32_16x16x32_bf16 v[28:31], v[96:99], v[194:197], v[28:31]
	v_mfma_f32_16x16x32_bf16 v[24:27], v[108:111], v[194:197], v[24:27]
	v_mfma_f32_16x16x32_bf16 v[12:15], v[96:99], v[208:211], v[12:15]
	v_mfma_f32_16x16x32_bf16 v[8:11], v[108:111], v[208:211], v[8:11]
	v_mfma_f32_16x16x32_bf16 v[60:63], v[100:103], v[164:167], v[60:63]
	v_mfma_f32_16x16x32_bf16 v[56:59], v[116:119], v[164:167], v[56:59]
	v_mfma_f32_16x16x32_bf16 v[44:47], v[100:103], v[186:189], v[44:47]
	v_mfma_f32_16x16x32_bf16 v[40:43], v[116:119], v[186:189], v[40:43]
	v_mfma_f32_16x16x32_bf16 v[28:31], v[100:103], v[204:207], v[28:31]
	v_mfma_f32_16x16x32_bf16 v[24:27], v[116:119], v[204:207], v[24:27]
	v_mfma_f32_16x16x32_bf16 v[12:15], v[100:103], v[212:215], v[12:15]
	v_mfma_f32_16x16x32_bf16 v[8:11], v[116:119], v[212:215], v[8:11]
	v_mfma_f32_16x16x32_bf16 v[52:55], v[144:147], v[160:163], v[52:55]
	v_mfma_f32_16x16x32_bf16 v[48:51], v[152:155], v[160:163], v[48:51]
	v_mfma_f32_16x16x32_bf16 v[36:39], v[144:147], v[182:185], v[36:39]
	v_mfma_f32_16x16x32_bf16 v[32:35], v[152:155], v[182:185], v[32:35]
	v_mfma_f32_16x16x32_bf16 v[20:23], v[144:147], v[194:197], v[20:23]
	v_mfma_f32_16x16x32_bf16 v[16:19], v[152:155], v[194:197], v[16:19]
	v_mfma_f32_16x16x32_bf16 v[4:7], v[144:147], v[208:211], v[4:7]
	v_mfma_f32_16x16x32_bf16 v[0:3], v[152:155], v[208:211], v[0:3]
	v_mfma_f32_16x16x32_bf16 v[52:55], v[148:151], v[164:167], v[52:55]
	v_mfma_f32_16x16x32_bf16 v[48:51], v[156:159], v[164:167], v[48:51]
	v_mfma_f32_16x16x32_bf16 v[36:39], v[148:151], v[186:189], v[36:39]
	v_mfma_f32_16x16x32_bf16 v[32:35], v[156:159], v[186:189], v[32:35]
	v_mfma_f32_16x16x32_bf16 v[20:23], v[148:151], v[204:207], v[20:23]
	v_mfma_f32_16x16x32_bf16 v[16:19], v[156:159], v[204:207], v[16:19]
	v_mfma_f32_16x16x32_bf16 v[4:7], v[148:151], v[212:215], v[4:7]
	v_mfma_f32_16x16x32_bf16 v[0:3], v[156:159], v[212:215], v[0:3]
	s_barrier
	s_setprio 1
	s_add_u32 s42, s42, 0x100
	s_addc_u32 s43, s43, 0
	s_add_u32 s83, s83, 0x100
	s_addc_u32 s84, s84, 0
	s_cmp_ge_u32 s85, s70
	s_mov_b32 s46, s85
	s_cbranch_scc0 .LBB0_1079
.Lkpeel_1079_exit:
	s_setprio 0
	s_and_b64 vcc, exec, s[18:19]
	s_cbranch_vccz .LBB0_1082
	s_barrier
